# software-pipelined weight-prep transposes in P1: next tile address calc and 8 global loads issued right after the LDS-write barrier so they overlap the transposed read, cvt and stores; mid-file branch
# baseline (speedup 1.0000x reference)
; #define LAS __attribute__((address_space(3)))
; DI int get_bid() { int b = blockIdx.x; asm volatile("" : "+s"(b)); return b; }
; DI int get_grid() { int g = gridDim.x; asm volatile("" : "+s"(g)); return g; }
; DI unsigned xb_xcc_id() { return (unsigned)__builtin_amdgcn_s_getreg((3 << 11) | 20) & 0xFu; }
; __global__ void __launch_bounds__(NTHR) mega(Params p) {
;     ...
;   for (int ph = ph_lo; ph < ph_hi; ++ph) {
;     if (ph % PH_PER_LAYER == 6 || (ph % PH_PER_LAYER == 0 && ph > 0)) continue;
;     if (ph_hi > 4096) cg::this_grid().sync();
;     if (ph > ph_lo) {
;       CP pb_ = (CP)__builtin_amdgcn_kernarg_segment_ptr(); asm volatile("" : "+s"(pb_));
;       XcdBarrier xbar; xbar.bar = (unsigned*)(pb_->ws + WS_BAR); xbar.x = xb_xcc_id(); xbar.st = (volatile LAS unsigned*)(smem + LDS_BYTES - 16);
;       xcd_barrier(xbar);
;     }
;     const int BID = get_bid(), G = get_grid();
;     CP pp = (CP)__builtin_amdgcn_kernarg_segment_ptr(); asm volatile("" : "+s"(pp));
;     char* ws = pp->ws;
;     u16* proj = (u16*)(ws + WS_PROJ);
;     u16* xn = (u16*)(ws + WS_XN);
;     u16* pb = (u16*)(ws + WS_PB);
;     u16* mg = (u16*)(ws + WS_MG);
;     float* lse = (float*)(ws + WS_LSE);
;     u16* hbuf = proj;
;     const u16* WIN = (const u16*)(ws + WS_WIN); const u16* WG = (const u16*)(ws + WS_WG); const u16* WB = (const u16*)(ws + WS_WB);
;     const u16* WO = (const u16*)(ws + WS_WO); const u16* WUP = (const u16*)(ws + WS_WUP); const u16* WDN = (const u16*)(ws + WS_WDN);
;     const u16* WGLU = (const u16*)(ws + WS_WGLU);
;     float* xres = pp->out;
;     const int l = ph / PH_PER_LAYER, k = ph % PH_PER_LAYER;
;     const float* xin = (l == 0) ? pp->in[0] : xres;
;     switch (k) {
.Ltramp_430:
	s_branch .LBB0_430

; DI int get_tid(int wv) { int l; asm volatile("v_mbcnt_lo_u32_b32 %0, -1, 0\n\tv_mbcnt_hi_u32_b32 %0, -1, %0" : "=v"(l)); return wv * 64 + l; }
; DI void transpose_tile(WVP float* sm, const float* __restrict__ src, int lds_, u16* __restrict__ dst, int ldd, int k0, int n0) {
;   const int tid = get_tid(WV);
;   constexpr int P = 257;
;   f32x4 v[8];
;   const int rb = tid >> 6, c4 = (tid & 63) * 4;
; #pragma unroll
;   for (int i = 0; i < 8; ++i) v[i] = *(const f32x4*)(src + (long)(k0 + rb + 8 * i) * lds_ + n0 + c4);
;   const int GRD0 = get_grid(); const int GRD = GRD0 / gdiv; const int BID = (get_bid() + bid_shift) % GRD0;
;   if (BID >= GRD) return;
;   char* ws = pp->ws;
;   float* sm = (float*)smem;
;   const float* w_in = pp->in[2] + (size_t)l * DM * INW;
;   const float* w_gate = pp->in[16] + (size_t)l * 4 * DM * DM;
;   const float* w_branch = pp->in[15] + (size_t)l * 1792 * DM;
;   const float* w_out = pp->in[17] + (size_t)l * DM * DM;
;   const float* w_up = pp->in[19] + (size_t)l * DM * 2 * FFN;
;   const float* w_down = pp->in[20] + (size_t)l * FFN * DM;
;   const float* w_glu = pp->in[14] + (size_t)l * 512 * 1024;
;   u16* WB = (u16*)(ws + WS_WB);
;   constexpr int NJ = 12;
;   const float* src[NJ] = {w_in, w_gate, w_gate + DM * DM, w_gate + 2 * DM * DM, w_gate + 3 * DM * DM,
;                           w_branch + 512 * DM, w_branch + 768 * DM, w_branch + 1280 * DM, w_out, w_up, w_down, w_glu};
;   const int lds_[NJ] = {INW, DM, DM, DM, DM, DM, DM, DM, DM, 2 * FFN, DM, 1024};
;   const int Kd[NJ] = {DM, DM, DM, DM, DM, 256, 512, 512, DM, DM, FFN, 512};
;   const int Nd[NJ] = {INW, DM, DM, DM, DM, DM, DM, DM, DM, 2 * FFN, DM, 1024};
;   u16* dst[NJ] = {(u16*)(ws + WS_WIN), (u16*)(ws + WS_WG), (u16*)(ws + WS_WG) + DM * DM, (u16*)(ws + WS_WG) + 2 * DM * DM, (u16*)(ws + WS_WG) + 3 * DM * DM,
;                   WB + DM * 512, WB + DM * 768, WB + DM * 1280, (u16*)(ws + WS_WO), (u16*)(ws + WS_WUP), (u16*)(ws + WS_WDN), (u16*)(ws + WS_WGLU)};
;   int base = 0;
; #pragma unroll
;   for (int j = 0; j < NJ; ++j) {
;     if (!((mask >> j) & 1)) continue;
;     int nk = Kd[j] / 64, nn = Nd[j] / 256, cnt = nk * nn;
;     int first = (BID - base % GRD + GRD) % GRD;
;     for (int i = first; i < cnt; i += GRD) transpose_tile(WV, sm, src[j], lds_[j], dst[j], Kd[j], (i / nn) * 64, (i % nn) * 256);
.LBB0_373:
	v_readlane_b32 s1, v255, 21
	s_lshr_b32 s0, s1, 31
	s_add_i32 s0, s1, s0
	s_mov_b32 s1, s53
	s_abs_i32 s4, s1
	v_cvt_f32_u32_e32 v0, s4
	s_lshr_b32 s5, s1, 31
	s_add_i32 s1, s1, s5
	s_ashr_i32 s20, s1, 1
	v_rcp_iflag_f32_e32 v0, v0
	s_mov_b32 s1, s57
	s_sub_i32 s5, 0, s4
	s_ashr_i32 s0, s0, 1
	v_mul_f32_e32 v0, 0x4f7ffffe, v0
	v_cvt_u32_f32_e32 v0, v0
	s_add_i32 s1, s1, s0
	s_ashr_i32 s0, s1, 31
	v_readfirstlane_b32 s8, v0
	s_mul_i32 s5, s5, s8
	s_mul_hi_u32 s5, s8, s5
	s_abs_i32 s1, s1
	s_add_i32 s8, s8, s5
	s_mul_hi_u32 s5, s1, s8
	s_mul_i32 s5, s5, s4
	s_sub_i32 s1, s1, s5
	s_sub_i32 s5, s1, s4
	s_cmp_ge_u32 s1, s4
	s_cselect_b32 s1, s5, s1
	s_sub_i32 s5, s1, s4
	s_cmp_ge_u32 s1, s4
	s_cselect_b32 s1, s5, s1
	s_xor_b32 s1, s1, s0
	s_sub_i32 s21, s1, s0
	s_cmp_ge_i32 s21, s20
	s_cbranch_scc1 .LBB0_412
	v_readlane_b32 s4, v255, 22
	v_readlane_b32 s5, v255, 23
	s_load_dwordx8 s[8:15], s[4:5], 0x70
	s_ashr_i32 s47, s46, 31
	s_lshl_b64 s[0:1], s[46:47], 24
	s_load_dwordx4 s[16:19], s[4:5], 0x98
	s_movk_i32 s28, 0x404
	s_waitcnt lgkmcnt(0)
	s_add_u32 s23, s12, s0
	s_addc_u32 s24, s13, s1
	s_abs_i32 s12, s20
	v_cvt_f32_u32_e32 v0, s12
	s_sub_i32 s4, 0, s12
	s_add_i32 s13, s21, s20
	s_abs_i32 s1, s13
	v_rcp_iflag_f32_e32 v0, v0
	s_ashr_i32 s0, s13, 31
	v_readlane_b32 s29, v255, 33
	v_readlane_b32 s30, v255, 34
	v_mul_f32_e32 v0, 0x4f7ffffe, v0
	v_cvt_u32_f32_e32 v0, v0
	s_nop 0
	v_readfirstlane_b32 s22, v0
	s_mul_i32 s4, s4, s22
	s_mul_hi_u32 s4, s22, s4
	s_add_i32 s22, s22, s4
	s_mul_hi_u32 s4, s1, s22
	s_mul_i32 s4, s4, s12
	s_sub_i32 s1, s1, s4
	s_sub_i32 s4, s1, s12
	s_cmp_ge_u32 s1, s12
	s_cselect_b32 s1, s4, s1
	s_sub_i32 s4, s1, s12
	s_cmp_ge_u32 s1, s12
	s_cselect_b32 s1, s4, s1
	s_xor_b32 s1, s1, s0
	s_sub_i32 s0, s1, s0
	s_cmp_gt_i32 s0, 63
	s_cbranch_scc1 .LBB0_377
	s_lshl_b32 s1, s0, 8
	s_lshl_b32 s25, s20, 8
	s_ashr_i32 s4, s0, 31
	s_lshr_b32 s4, s4, 30
	s_add_i32 s4, s0, s4
	s_ashr_i32 s5, s4, 2
	s_lshl_b32 s4, s5, 6
	s_lshl_b32 s5, s5, 10
	v_mbcnt_lo_u32_b32 v0, -1, 0
	v_mbcnt_hi_u32_b32 v0, -1, v0
	s_sub_i32 s26, s1, s5
	v_add_u32_e32 v2, s3, v0
	v_lshlrev_b32_e32 v3, 4, v0
	v_lshlrev_b32_e32 v4, 3, v0
	v_ashrrev_i32_e32 v5, 6, v2
	v_and_b32_e32 v0, 0x3f0, v3
	v_and_b32_e32 v42, 56, v4
	v_ashrrev_i32_e32 v3, 3, v2
	v_add_u32_e32 v4, 0x200, v2
	v_add_u32_e32 v6, 0x400, v2
	v_add_u32_e32 v2, 0x600, v2
	s_ashr_i32 s27, s26, 31
	v_mul_lo_u32 v7, v5, s28
	v_mad_u32_u24 v8, v42, s28, 0
	v_ashrrev_i32_e32 v4, 3, v4
	v_ashrrev_i32_e32 v9, 3, v2
	v_add_u32_e32 v2, s4, v5
	v_subrev_u32_e32 v5, s5, v3
	s_lshl_b64 s[26:27], s[26:27], 2
	v_ashrrev_i32_e32 v6, 3, v6
	v_add3_u32 v44, 0, v0, v7
	v_lshl_add_u32 v46, v4, 2, v8
	v_subrev_u32_e32 v7, s5, v4
	v_add_u32_e32 v4, s1, v5
	s_add_u32 s26, s23, s26
	v_lshl_add_u32 v45, v3, 2, v8
	v_lshl_add_u32 v47, v6, 2, v8
	v_lshl_add_u32 v48, v9, 2, v8
	v_subrev_u32_e32 v8, s5, v6
	v_ashrrev_i32_e32 v3, 31, v2
	v_add_u32_e32 v6, s1, v7
	v_ashrrev_i32_e32 v5, 31, v4
	s_addc_u32 s27, s24, s27
	v_subrev_u32_e32 v9, s5, v9
	v_add_u32_e32 v8, s1, v8
	v_lshlrev_b64 v[2:3], 12, v[2:3]
	v_ashrrev_i32_e32 v7, 31, v6
	v_lshlrev_b64 v[34:35], 11, v[4:5]
	v_lshl_add_u64 v[4:5], s[26:27], 0, v[0:1]
	v_add_u32_e32 v10, s1, v9
	v_ashrrev_i32_e32 v9, 31, v8
	v_lshlrev_b64 v[36:37], 11, v[6:7]
	v_lshl_add_u64 v[6:7], v[4:5], 0, v[2:3]
	v_lshlrev_b64 v[38:39], 11, v[8:9]
	v_add_co_u32_e32 v8, vcc, s38, v6
	v_ashrrev_i32_e32 v11, 31, v10
	s_nop 0
	v_addc_co_u32_e32 v9, vcc, 0, v7, vcc
	v_lshlrev_b64 v[40:41], 11, v[10:11]
	v_add_co_u32_e32 v10, vcc, s36, v6
	global_load_dwordx4 v[2:5], v[6:7], off
	s_nop 0
	v_addc_co_u32_e32 v11, vcc, 0, v7, vcc
	v_add_co_u32_e32 v14, vcc, s37, v6
	s_ashr_i32 s5, s4, 31
	s_nop 0
	v_addc_co_u32_e32 v15, vcc, 0, v7, vcc
	v_add_co_u32_e32 v18, vcc, s39, v6
	s_lshl_b64 s[4:5], s[4:5], 1
	s_nop 0
	v_addc_co_u32_e32 v19, vcc, 0, v7, vcc
	v_add_co_u32_e32 v22, vcc, s40, v6
	s_add_u32 s4, s29, s4
	s_nop 0
	v_addc_co_u32_e32 v23, vcc, 0, v7, vcc
	v_add_co_u32_e32 v26, vcc, s41, v6
	v_lshlrev_b32_e32 v0, 1, v42
	s_nop 0
	v_addc_co_u32_e32 v27, vcc, 0, v7, vcc
	v_add_co_u32_e32 v30, vcc, s42, v6
	s_addc_u32 s5, s30, s5
	s_nop 0
	v_addc_co_u32_e32 v31, vcc, 0, v7, vcc
	global_load_dwordx4 v[6:9], v[8:9], off
	s_nop 0
	global_load_dwordx4 v[10:13], v[10:11], off
	s_nop 0
	global_load_dwordx4 v[14:17], v[14:15], off
	s_nop 0
	global_load_dwordx4 v[18:21], v[18:19], off
	s_nop 0
	global_load_dwordx4 v[22:25], v[22:23], off
	s_nop 0
	global_load_dwordx4 v[26:29], v[26:27], off
	s_nop 0
	global_load_dwordx4 v[30:33], v[30:31], off
	v_add_u32_e32 v49, 0x2020, v44
	v_add_u32_e32 v50, 0x2028, v44
	v_add_u32_e32 v51, 0x4040, v44
	v_add_u32_e32 v52, 0x4048, v44
	v_add_u32_e32 v53, 0x6060, v44
	v_add_u32_e32 v54, 0x6068, v44
	v_add_u32_e32 v55, 0x8080, v44
	v_add_u32_e32 v56, 0x8088, v44
	v_add_u32_e32 v57, 0xa0a0, v44
	v_add_u32_e32 v58, 0xa0a8, v44
	v_add_u32_e32 v59, 0xc0c0, v44
	v_add_u32_e32 v60, 0xc0c8, v44
	v_add_u32_e32 v61, 0xe0e0, v44
	v_add_u32_e32 v62, 0xe0e8, v44
	s_waitcnt vmcnt(0)
; DI unsigned pack2(float a, float b) { f2_t v = {a, b}; bf2_t r = __builtin_convertvector(v, bf2_t); return __builtin_bit_cast(unsigned, r); }
; DI void transpose_tile(WVP float* sm, const float* __restrict__ src, int lds_, u16* __restrict__ dst, int ldd, int k0, int n0) {
;     ...
;   for (int i = 0; i < 8; ++i) v[i] = *(const f32x4*)(src + (long)(k0 + rb + 8 * i) * lds_ + n0 + c4);
;   __syncthreads();
; #pragma unroll
;   for (int i = 0; i < 8; ++i) for (int j = 0; j < 4; ++j) sm[(rb + 8 * i) * P + c4 + j] = v[i][j];
;   __syncthreads();
; #pragma unroll
;   for (int i = 0; i < 4; ++i) {
;     const int c = tid + NTHR * i, n = c >> 3, k8 = (c & 7) * 8;
;     u32x4 o;
;     o[0] = pack2(sm[(k8 + 0) * P + n], sm[(k8 + 1) * P + n]); o[1] = pack2(sm[(k8 + 2) * P + n], sm[(k8 + 3) * P + n]);
;     o[2] = pack2(sm[(k8 + 4) * P + n], sm[(k8 + 5) * P + n]); o[3] = pack2(sm[(k8 + 6) * P + n], sm[(k8 + 7) * P + n]);
;     *(u32x4*)(dst + (long)(n0 + n) * ldd + k0 + k8) = o;
;   }
;     ...
;     for (int i = first; i < cnt; i += GRD) transpose_tile(WV, sm, src[j], lds_[j], dst[j], Kd[j], (i / nn) * 64, (i % nn) * 256);
.LBB0_376:
	s_barrier
	v_lshl_add_u64 v[100:101], s[4:5], 0, v[0:1]
	v_lshl_add_u64 v[102:103], v[100:101], 0, v[34:35]
	v_lshl_add_u64 v[104:105], v[100:101], 0, v[36:37]
	v_lshl_add_u64 v[106:107], v[100:101], 0, v[38:39]
	v_lshl_add_u64 v[108:109], v[100:101], 0, v[40:41]
	s_waitcnt vmcnt(11)
	ds_write2_b32 v44, v2, v3 offset1:1
	ds_write2_b32 v44, v4, v5 offset0:2 offset1:3
	s_waitcnt vmcnt(10)
	ds_write2_b32 v49, v6, v7 offset1:1
	ds_write2_b32 v50, v8, v9 offset1:1
	s_waitcnt vmcnt(9)
	ds_write2_b32 v51, v10, v11 offset1:1
	ds_write2_b32 v52, v12, v13 offset1:1
	s_waitcnt vmcnt(8)
	ds_write2_b32 v53, v14, v15 offset1:1
	ds_write2_b32 v54, v16, v17 offset1:1
	s_waitcnt vmcnt(7)
	ds_write2_b32 v55, v18, v19 offset1:1
	ds_write2_b32 v56, v20, v21 offset1:1
	s_waitcnt vmcnt(6)
	ds_write2_b32 v57, v22, v23 offset1:1
	ds_write2_b32 v58, v24, v25 offset1:1
	s_waitcnt vmcnt(5)
	ds_write2_b32 v59, v26, v27 offset1:1
	ds_write2_b32 v60, v28, v29 offset1:1
	s_waitcnt vmcnt(4)
	ds_write2_b32 v61, v30, v31 offset1:1
	ds_write2_b32 v62, v32, v33 offset1:1
	s_waitcnt lgkmcnt(0)
	s_barrier
	s_add_i32 s0, s0, s20
	s_add_i32 s1, s1, s25
	s_cmp_lt_i32 s0, 64
	s_cbranch_scc0 .Lwp_skip_376
	s_ashr_i32 s4, s0, 31
	s_lshr_b32 s4, s4, 30
	s_add_i32 s4, s0, s4
	s_ashr_i32 s5, s4, 2
	s_lshl_b32 s4, s5, 6
	s_lshl_b32 s5, s5, 10
	v_mbcnt_lo_u32_b32 v0, -1, 0
	v_mbcnt_hi_u32_b32 v0, -1, v0
	s_sub_i32 s26, s1, s5
	v_add_u32_e32 v2, s3, v0
	v_lshlrev_b32_e32 v3, 4, v0
	v_lshlrev_b32_e32 v4, 3, v0
	v_ashrrev_i32_e32 v5, 6, v2
	v_and_b32_e32 v0, 0x3f0, v3
	v_and_b32_e32 v42, 56, v4
	v_ashrrev_i32_e32 v3, 3, v2
	v_add_u32_e32 v4, 0x200, v2
	v_add_u32_e32 v6, 0x400, v2
	v_add_u32_e32 v2, 0x600, v2
	s_ashr_i32 s27, s26, 31
	v_mul_lo_u32 v7, v5, s28
	v_mad_u32_u24 v8, v42, s28, 0
	v_ashrrev_i32_e32 v4, 3, v4
	v_ashrrev_i32_e32 v9, 3, v2
	v_add_u32_e32 v2, s4, v5
	v_subrev_u32_e32 v5, s5, v3
	s_lshl_b64 s[26:27], s[26:27], 2
	v_ashrrev_i32_e32 v6, 3, v6
	v_add3_u32 v44, 0, v0, v7
	v_lshl_add_u32 v46, v4, 2, v8
	v_subrev_u32_e32 v7, s5, v4
	v_add_u32_e32 v4, s1, v5
	s_add_u32 s26, s23, s26
	v_lshl_add_u32 v45, v3, 2, v8
	v_lshl_add_u32 v47, v6, 2, v8
	v_lshl_add_u32 v48, v9, 2, v8
	v_subrev_u32_e32 v8, s5, v6
	v_ashrrev_i32_e32 v3, 31, v2
	v_add_u32_e32 v6, s1, v7
	v_ashrrev_i32_e32 v5, 31, v4
	s_addc_u32 s27, s24, s27
	v_subrev_u32_e32 v9, s5, v9
	v_add_u32_e32 v8, s1, v8
	v_lshlrev_b64 v[2:3], 12, v[2:3]
	v_ashrrev_i32_e32 v7, 31, v6
	v_lshlrev_b64 v[34:35], 11, v[4:5]
	v_lshl_add_u64 v[4:5], s[26:27], 0, v[0:1]
	v_add_u32_e32 v10, s1, v9
	v_ashrrev_i32_e32 v9, 31, v8
	v_lshlrev_b64 v[36:37], 11, v[6:7]
	v_lshl_add_u64 v[6:7], v[4:5], 0, v[2:3]
	v_lshlrev_b64 v[38:39], 11, v[8:9]
	v_add_co_u32_e32 v8, vcc, s38, v6
	v_ashrrev_i32_e32 v11, 31, v10
	s_nop 0
	v_addc_co_u32_e32 v9, vcc, 0, v7, vcc
	v_lshlrev_b64 v[40:41], 11, v[10:11]
	v_add_co_u32_e32 v10, vcc, s36, v6
	global_load_dwordx4 v[2:5], v[6:7], off
	s_nop 0
	v_addc_co_u32_e32 v11, vcc, 0, v7, vcc
	v_add_co_u32_e32 v14, vcc, s37, v6
	s_ashr_i32 s5, s4, 31
	s_nop 0
	v_addc_co_u32_e32 v15, vcc, 0, v7, vcc
	v_add_co_u32_e32 v18, vcc, s39, v6
	s_lshl_b64 s[4:5], s[4:5], 1
	s_nop 0
	v_addc_co_u32_e32 v19, vcc, 0, v7, vcc
	v_add_co_u32_e32 v22, vcc, s40, v6
	s_add_u32 s4, s29, s4
	s_nop 0
	v_addc_co_u32_e32 v23, vcc, 0, v7, vcc
	v_add_co_u32_e32 v26, vcc, s41, v6
	v_lshlrev_b32_e32 v0, 1, v42
	s_nop 0
	v_addc_co_u32_e32 v27, vcc, 0, v7, vcc
	v_add_co_u32_e32 v30, vcc, s42, v6
	s_addc_u32 s5, s30, s5
	s_nop 0
	v_addc_co_u32_e32 v31, vcc, 0, v7, vcc
	global_load_dwordx4 v[6:9], v[8:9], off
	s_nop 0
	global_load_dwordx4 v[10:13], v[10:11], off
	s_nop 0
	global_load_dwordx4 v[14:17], v[14:15], off
	s_nop 0
	global_load_dwordx4 v[18:21], v[18:19], off
	s_nop 0
	global_load_dwordx4 v[22:25], v[22:23], off
	s_nop 0
	global_load_dwordx4 v[26:29], v[26:27], off
	s_nop 0
	global_load_dwordx4 v[30:33], v[30:31], off
	v_add_u32_e32 v49, 0x2020, v44
	v_add_u32_e32 v50, 0x2028, v44
	v_add_u32_e32 v51, 0x4040, v44
	v_add_u32_e32 v52, 0x4048, v44
	v_add_u32_e32 v53, 0x6060, v44
	v_add_u32_e32 v54, 0x6068, v44
	v_add_u32_e32 v55, 0x8080, v44
	v_add_u32_e32 v56, 0x8088, v44
	v_add_u32_e32 v57, 0xa0a0, v44
	v_add_u32_e32 v58, 0xa0a8, v44
	v_add_u32_e32 v59, 0xc0c0, v44
	v_add_u32_e32 v60, 0xc0c8, v44
	v_add_u32_e32 v61, 0xe0e0, v44
	v_add_u32_e32 v62, 0xe0e8, v44
.Lwp_skip_376:
	ds_read_b32 v64, v45
	ds_read_b32 v66, v45 offset:1028
	ds_read_b32 v67, v45 offset:2056
	ds_read_b32 v68, v45 offset:3084
	ds_read_b32 v69, v45 offset:4112
	ds_read_b32 v70, v45 offset:5140
	ds_read_b32 v71, v45 offset:6168
	ds_read_b32 v72, v45 offset:7196
	ds_read_b32 v73, v46
	ds_read_b32 v74, v46 offset:1028
	ds_read_b32 v75, v46 offset:2056
	ds_read_b32 v76, v46 offset:3084
	ds_read_b32 v77, v46 offset:4112
	ds_read_b32 v78, v46 offset:5140
	ds_read_b32 v79, v46 offset:6168
	ds_read_b32 v80, v46 offset:7196
	ds_read_b32 v81, v47
	ds_read_b32 v82, v47 offset:1028
	ds_read_b32 v83, v47 offset:2056
	ds_read_b32 v84, v47 offset:3084
	ds_read_b32 v85, v47 offset:4112
	ds_read_b32 v86, v47 offset:5140
	ds_read_b32 v87, v47 offset:6168
	ds_read_b32 v88, v47 offset:7196
	ds_read_b32 v89, v48
	ds_read_b32 v90, v48 offset:1028
	ds_read_b32 v91, v48 offset:2056
	ds_read_b32 v92, v48 offset:3084
	ds_read_b32 v93, v48 offset:4112
	ds_read_b32 v94, v48 offset:5140
	ds_read_b32 v95, v48 offset:6168
	ds_read_b32 v96, v48 offset:7196
	s_waitcnt lgkmcnt(14)
	v_cvt_pk_bf16_f32 v66, v64, v66
	v_cvt_pk_bf16_f32 v67, v67, v68
	v_cvt_pk_bf16_f32 v68, v69, v70
	v_cvt_pk_bf16_f32 v69, v71, v72
	v_cvt_pk_bf16_f32 v70, v73, v74
	v_cvt_pk_bf16_f32 v71, v75, v76
	v_cvt_pk_bf16_f32 v72, v77, v78
	v_cvt_pk_bf16_f32 v73, v79, v80
	v_cvt_pk_bf16_f32 v74, v81, v82
	s_waitcnt lgkmcnt(12)
	v_cvt_pk_bf16_f32 v75, v83, v84
	s_waitcnt lgkmcnt(10)
	v_cvt_pk_bf16_f32 v76, v85, v86
	s_waitcnt lgkmcnt(8)
	v_cvt_pk_bf16_f32 v77, v87, v88
	s_waitcnt lgkmcnt(6)
	v_cvt_pk_bf16_f32 v78, v89, v90
	s_waitcnt lgkmcnt(4)
	v_cvt_pk_bf16_f32 v79, v91, v92
	s_waitcnt lgkmcnt(2)
	v_cvt_pk_bf16_f32 v80, v93, v94
	s_waitcnt lgkmcnt(0)
	v_cvt_pk_bf16_f32 v81, v95, v96
	global_store_dwordx4 v[102:103], v[66:69], off
	global_store_dwordx4 v[104:105], v[70:73], off
	global_store_dwordx4 v[106:107], v[74:77], off
	global_store_dwordx4 v[108:109], v[78:81], off
	s_cmp_lt_i32 s0, 64
	s_cbranch_scc1 .LBB0_376
; DI int get_tid(int wv) { int l; asm volatile("v_mbcnt_lo_u32_b32 %0, -1, 0\n\tv_mbcnt_hi_u32_b32 %0, -1, %0" : "=v"(l)); return wv * 64 + l; }
; DI void transpose_tile(WVP float* sm, const float* __restrict__ src, int lds_, u16* __restrict__ dst, int ldd, int k0, int n0) {
;   const int tid = get_tid(WV);
;   constexpr int P = 257;
;   f32x4 v[8];
;   const int rb = tid >> 6, c4 = (tid & 63) * 4;
; #pragma unroll
;   for (int i = 0; i < 8; ++i) v[i] = *(const f32x4*)(src + (long)(k0 + rb + 8 * i) * lds_ + n0 + c4);
;   __syncthreads();
; #pragma unroll
;   for (int i = 0; i < 8; ++i) for (int j = 0; j < 4; ++j) sm[(rb + 8 * i) * P + c4 + j] = v[i][j];
;     ...
;     int first = (BID - base % GRD + GRD) % GRD;
;     for (int i = first; i < cnt; i += GRD) transpose_tile(WV, sm, src[j], lds_[j], dst[j], Kd[j], (i / nn) * 64, (i % nn) * 256);
.LBB0_377:
	s_lshr_b32 s0, s22, 26
	s_mul_i32 s0, s0, s12
	s_sub_i32 s0, 64, s0
	s_sub_i32 s1, s0, s12
	s_cmp_ge_u32 s0, s12
	s_cselect_b32 s0, s1, s0
	s_sub_i32 s1, s0, s12
	s_cmp_ge_u32 s0, s12
	s_cselect_b32 s0, s1, s0
	s_sub_i32 s0, s13, s0
	s_ashr_i32 s1, s0, 31
	s_abs_i32 s0, s0
	s_mul_hi_u32 s4, s0, s22
	s_mul_i32 s4, s4, s12
	s_sub_i32 s0, s0, s4
	s_sub_i32 s4, s0, s12
	s_cmp_ge_u32 s0, s12
	s_cselect_b32 s0, s4, s0
	s_sub_i32 s4, s0, s12
	s_cmp_ge_u32 s0, s12
	s_cselect_b32 s0, s4, s0
	s_xor_b32 s0, s0, s1
	s_sub_i32 s0, s0, s1
	s_cmp_gt_i32 s0, 63
	s_movk_i32 s34, 0x404
	s_cbranch_scc1 .LBB0_380
	s_add_u32 s1, s23, 0x400000
	s_addc_u32 s25, s24, 0
	s_add_u32 s26, s54, 0x1dd00000
	s_addc_u32 s27, s55, 0
	s_lshl_b32 s28, s0, 8
	s_lshl_b32 s29, s20, 8
	s_ashr_i32 s4, s0, 31
	s_lshr_b32 s4, s4, 30
	s_add_i32 s4, s0, s4
	s_ashr_i32 s5, s4, 2
	s_lshl_b32 s4, s5, 6
	s_lshl_b32 s5, s5, 10
	v_mbcnt_lo_u32_b32 v0, -1, 0
	v_mbcnt_hi_u32_b32 v0, -1, v0
	s_sub_i32 s30, s28, s5
	v_add_u32_e32 v2, s3, v0
	v_lshlrev_b32_e32 v3, 4, v0
	v_lshlrev_b32_e32 v4, 3, v0
	v_ashrrev_i32_e32 v5, 6, v2
	v_and_b32_e32 v0, 0x3f0, v3
	v_and_b32_e32 v42, 56, v4
	v_ashrrev_i32_e32 v3, 3, v2
	v_add_u32_e32 v4, 0x200, v2
	v_add_u32_e32 v6, 0x400, v2
	v_add_u32_e32 v2, 0x600, v2
	s_ashr_i32 s31, s30, 31
	v_mul_lo_u32 v7, v5, s34
	v_mad_u32_u24 v8, v42, s34, 0
	v_ashrrev_i32_e32 v4, 3, v4
	v_ashrrev_i32_e32 v9, 3, v2
	v_add_u32_e32 v2, s4, v5
	v_subrev_u32_e32 v5, s5, v3
	s_lshl_b64 s[30:31], s[30:31], 2
	v_ashrrev_i32_e32 v6, 3, v6
	v_add3_u32 v44, 0, v0, v7
	v_lshl_add_u32 v46, v4, 2, v8
	v_subrev_u32_e32 v7, s5, v4
	v_add_u32_e32 v4, s28, v5
	s_add_u32 s30, s1, s30
	v_lshl_add_u32 v45, v3, 2, v8
	v_lshl_add_u32 v47, v6, 2, v8
	v_lshl_add_u32 v48, v9, 2, v8
	v_subrev_u32_e32 v8, s5, v6
	v_ashrrev_i32_e32 v3, 31, v2
	v_add_u32_e32 v6, s28, v7
	v_ashrrev_i32_e32 v5, 31, v4
	s_addc_u32 s31, s25, s31
	v_subrev_u32_e32 v9, s5, v9
	v_add_u32_e32 v8, s28, v8
	v_lshlrev_b64 v[2:3], 12, v[2:3]
	v_ashrrev_i32_e32 v7, 31, v6
	v_lshlrev_b64 v[34:35], 11, v[4:5]
	v_lshl_add_u64 v[4:5], s[30:31], 0, v[0:1]
	v_add_u32_e32 v10, s28, v9
	v_ashrrev_i32_e32 v9, 31, v8
	v_lshlrev_b64 v[36:37], 11, v[6:7]
	v_lshl_add_u64 v[6:7], v[4:5], 0, v[2:3]
	v_lshlrev_b64 v[38:39], 11, v[8:9]
	v_add_co_u32_e32 v8, vcc, s38, v6
	v_ashrrev_i32_e32 v11, 31, v10
	s_nop 0
	v_addc_co_u32_e32 v9, vcc, 0, v7, vcc
	v_lshlrev_b64 v[40:41], 11, v[10:11]
	v_add_co_u32_e32 v10, vcc, s36, v6
	global_load_dwordx4 v[2:5], v[6:7], off
	s_nop 0
	v_addc_co_u32_e32 v11, vcc, 0, v7, vcc
	v_add_co_u32_e32 v14, vcc, s37, v6
	s_ashr_i32 s5, s4, 31
	s_nop 0
	v_addc_co_u32_e32 v15, vcc, 0, v7, vcc
	v_add_co_u32_e32 v18, vcc, s39, v6
	s_lshl_b64 s[4:5], s[4:5], 1
	s_nop 0
	v_addc_co_u32_e32 v19, vcc, 0, v7, vcc
	v_add_co_u32_e32 v22, vcc, s40, v6
	s_add_u32 s4, s26, s4
	s_nop 0
	v_addc_co_u32_e32 v23, vcc, 0, v7, vcc
	v_add_co_u32_e32 v26, vcc, s41, v6
	v_lshlrev_b32_e32 v0, 1, v42
	s_nop 0
	v_addc_co_u32_e32 v27, vcc, 0, v7, vcc
	v_add_co_u32_e32 v30, vcc, s42, v6
	s_addc_u32 s5, s27, s5
	s_nop 0
	v_addc_co_u32_e32 v31, vcc, 0, v7, vcc
	global_load_dwordx4 v[6:9], v[8:9], off
	s_nop 0
	global_load_dwordx4 v[10:13], v[10:11], off
	s_nop 0
	global_load_dwordx4 v[14:17], v[14:15], off
	s_nop 0
	global_load_dwordx4 v[18:21], v[18:19], off
	s_nop 0
	global_load_dwordx4 v[22:25], v[22:23], off
	s_nop 0
	global_load_dwordx4 v[26:29], v[26:27], off
	s_nop 0
	global_load_dwordx4 v[30:33], v[30:31], off
	v_add_u32_e32 v49, 0x2020, v44
	v_add_u32_e32 v50, 0x2028, v44
	v_add_u32_e32 v51, 0x4040, v44
	v_add_u32_e32 v52, 0x4048, v44
	v_add_u32_e32 v53, 0x6060, v44
	v_add_u32_e32 v54, 0x6068, v44
	v_add_u32_e32 v55, 0x8080, v44
	v_add_u32_e32 v56, 0x8088, v44
	v_add_u32_e32 v57, 0xa0a0, v44
	v_add_u32_e32 v58, 0xa0a8, v44
	v_add_u32_e32 v59, 0xc0c0, v44
	v_add_u32_e32 v60, 0xc0c8, v44
	v_add_u32_e32 v61, 0xe0e0, v44
	v_add_u32_e32 v62, 0xe0e8, v44
	s_waitcnt vmcnt(0)
; DI unsigned pack2(float a, float b) { f2_t v = {a, b}; bf2_t r = __builtin_convertvector(v, bf2_t); return __builtin_bit_cast(unsigned, r); }
; DI int get_tid(int wv) { int l; asm volatile("v_mbcnt_lo_u32_b32 %0, -1, 0\n\tv_mbcnt_hi_u32_b32 %0, -1, %0" : "=v"(l)); return wv * 64 + l; }
; DI void transpose_tile(WVP float* sm, const float* __restrict__ src, int lds_, u16* __restrict__ dst, int ldd, int k0, int n0) {
;   const int tid = get_tid(WV);
;   constexpr int P = 257;
;   f32x4 v[8];
;   const int rb = tid >> 6, c4 = (tid & 63) * 4;
; #pragma unroll
;   for (int i = 0; i < 8; ++i) v[i] = *(const f32x4*)(src + (long)(k0 + rb + 8 * i) * lds_ + n0 + c4);
;   __syncthreads();
; #pragma unroll
;   for (int i = 0; i < 8; ++i) for (int j = 0; j < 4; ++j) sm[(rb + 8 * i) * P + c4 + j] = v[i][j];
;   __syncthreads();
; #pragma unroll
;   for (int i = 0; i < 4; ++i) {
;     const int c = tid + NTHR * i, n = c >> 3, k8 = (c & 7) * 8;
;     u32x4 o;
;     o[0] = pack2(sm[(k8 + 0) * P + n], sm[(k8 + 1) * P + n]); o[1] = pack2(sm[(k8 + 2) * P + n], sm[(k8 + 3) * P + n]);
;     o[2] = pack2(sm[(k8 + 4) * P + n], sm[(k8 + 5) * P + n]); o[3] = pack2(sm[(k8 + 6) * P + n], sm[(k8 + 7) * P + n]);
;     *(u32x4*)(dst + (long)(n0 + n) * ldd + k0 + k8) = o;
;   }
.LBB0_379:
	s_barrier
	v_lshl_add_u64 v[100:101], s[4:5], 0, v[0:1]
	v_lshl_add_u64 v[102:103], v[100:101], 0, v[34:35]
	v_lshl_add_u64 v[104:105], v[100:101], 0, v[36:37]
	v_lshl_add_u64 v[106:107], v[100:101], 0, v[38:39]
	v_lshl_add_u64 v[108:109], v[100:101], 0, v[40:41]
	s_waitcnt vmcnt(11)
	ds_write2_b32 v44, v2, v3 offset1:1
	ds_write2_b32 v44, v4, v5 offset0:2 offset1:3
	s_waitcnt vmcnt(10)
	ds_write2_b32 v49, v6, v7 offset1:1
	ds_write2_b32 v50, v8, v9 offset1:1
	s_waitcnt vmcnt(9)
	ds_write2_b32 v51, v10, v11 offset1:1
	ds_write2_b32 v52, v12, v13 offset1:1
	s_waitcnt vmcnt(8)
	ds_write2_b32 v53, v14, v15 offset1:1
	ds_write2_b32 v54, v16, v17 offset1:1
	s_waitcnt vmcnt(7)
	ds_write2_b32 v55, v18, v19 offset1:1
	ds_write2_b32 v56, v20, v21 offset1:1
	s_waitcnt vmcnt(6)
	ds_write2_b32 v57, v22, v23 offset1:1
	ds_write2_b32 v58, v24, v25 offset1:1
	s_waitcnt vmcnt(5)
	ds_write2_b32 v59, v26, v27 offset1:1
	ds_write2_b32 v60, v28, v29 offset1:1
	s_waitcnt vmcnt(4)
	ds_write2_b32 v61, v30, v31 offset1:1
	ds_write2_b32 v62, v32, v33 offset1:1
	s_waitcnt lgkmcnt(0)
	s_barrier
	s_add_i32 s0, s0, s20
	s_add_i32 s28, s28, s29
	s_movk_i32 s34, 0x404
	s_cmp_lt_i32 s0, 64
	s_cbranch_scc0 .Lwp_skip_379
	s_ashr_i32 s4, s0, 31
	s_lshr_b32 s4, s4, 30
	s_add_i32 s4, s0, s4
	s_ashr_i32 s5, s4, 2
	s_lshl_b32 s4, s5, 6
	s_lshl_b32 s5, s5, 10
	v_mbcnt_lo_u32_b32 v0, -1, 0
	v_mbcnt_hi_u32_b32 v0, -1, v0
	s_sub_i32 s30, s28, s5
	v_add_u32_e32 v2, s3, v0
	v_lshlrev_b32_e32 v3, 4, v0
	v_lshlrev_b32_e32 v4, 3, v0
	v_ashrrev_i32_e32 v5, 6, v2
	v_and_b32_e32 v0, 0x3f0, v3
	v_and_b32_e32 v42, 56, v4
	v_ashrrev_i32_e32 v3, 3, v2
	v_add_u32_e32 v4, 0x200, v2
	v_add_u32_e32 v6, 0x400, v2
	v_add_u32_e32 v2, 0x600, v2
	s_ashr_i32 s31, s30, 31
	v_mul_lo_u32 v7, v5, s34
	v_mad_u32_u24 v8, v42, s34, 0
	v_ashrrev_i32_e32 v4, 3, v4
	v_ashrrev_i32_e32 v9, 3, v2
	v_add_u32_e32 v2, s4, v5
	v_subrev_u32_e32 v5, s5, v3
	s_lshl_b64 s[30:31], s[30:31], 2
	v_ashrrev_i32_e32 v6, 3, v6
	v_add3_u32 v44, 0, v0, v7
	v_lshl_add_u32 v46, v4, 2, v8
	v_subrev_u32_e32 v7, s5, v4
	v_add_u32_e32 v4, s28, v5
	s_add_u32 s30, s1, s30
	v_lshl_add_u32 v45, v3, 2, v8
	v_lshl_add_u32 v47, v6, 2, v8
	v_lshl_add_u32 v48, v9, 2, v8
	v_subrev_u32_e32 v8, s5, v6
	v_ashrrev_i32_e32 v3, 31, v2
	v_add_u32_e32 v6, s28, v7
	v_ashrrev_i32_e32 v5, 31, v4
	s_addc_u32 s31, s25, s31
	v_subrev_u32_e32 v9, s5, v9
	v_add_u32_e32 v8, s28, v8
	v_lshlrev_b64 v[2:3], 12, v[2:3]
	v_ashrrev_i32_e32 v7, 31, v6
	v_lshlrev_b64 v[34:35], 11, v[4:5]
	v_lshl_add_u64 v[4:5], s[30:31], 0, v[0:1]
	v_add_u32_e32 v10, s28, v9
	v_ashrrev_i32_e32 v9, 31, v8
	v_lshlrev_b64 v[36:37], 11, v[6:7]
	v_lshl_add_u64 v[6:7], v[4:5], 0, v[2:3]
	v_lshlrev_b64 v[38:39], 11, v[8:9]
	v_add_co_u32_e32 v8, vcc, s38, v6
	v_ashrrev_i32_e32 v11, 31, v10
	s_nop 0
	v_addc_co_u32_e32 v9, vcc, 0, v7, vcc
	v_lshlrev_b64 v[40:41], 11, v[10:11]
	v_add_co_u32_e32 v10, vcc, s36, v6
	global_load_dwordx4 v[2:5], v[6:7], off
	s_nop 0
	v_addc_co_u32_e32 v11, vcc, 0, v7, vcc
	v_add_co_u32_e32 v14, vcc, s37, v6
	s_ashr_i32 s5, s4, 31
	s_nop 0
	v_addc_co_u32_e32 v15, vcc, 0, v7, vcc
	v_add_co_u32_e32 v18, vcc, s39, v6
	s_lshl_b64 s[4:5], s[4:5], 1
	s_nop 0
	v_addc_co_u32_e32 v19, vcc, 0, v7, vcc
	v_add_co_u32_e32 v22, vcc, s40, v6
	s_add_u32 s4, s26, s4
	s_nop 0
	v_addc_co_u32_e32 v23, vcc, 0, v7, vcc
	v_add_co_u32_e32 v26, vcc, s41, v6
	v_lshlrev_b32_e32 v0, 1, v42
	s_nop 0
	v_addc_co_u32_e32 v27, vcc, 0, v7, vcc
	v_add_co_u32_e32 v30, vcc, s42, v6
	s_addc_u32 s5, s27, s5
	s_nop 0
	v_addc_co_u32_e32 v31, vcc, 0, v7, vcc
	global_load_dwordx4 v[6:9], v[8:9], off
	s_nop 0
	global_load_dwordx4 v[10:13], v[10:11], off
	s_nop 0
	global_load_dwordx4 v[14:17], v[14:15], off
	s_nop 0
	global_load_dwordx4 v[18:21], v[18:19], off
	s_nop 0
	global_load_dwordx4 v[22:25], v[22:23], off
	s_nop 0
	global_load_dwordx4 v[26:29], v[26:27], off
	s_nop 0
	global_load_dwordx4 v[30:33], v[30:31], off
	v_add_u32_e32 v49, 0x2020, v44
	v_add_u32_e32 v50, 0x2028, v44
	v_add_u32_e32 v51, 0x4040, v44
	v_add_u32_e32 v52, 0x4048, v44
	v_add_u32_e32 v53, 0x6060, v44
	v_add_u32_e32 v54, 0x6068, v44
	v_add_u32_e32 v55, 0x8080, v44
	v_add_u32_e32 v56, 0x8088, v44
	v_add_u32_e32 v57, 0xa0a0, v44
	v_add_u32_e32 v58, 0xa0a8, v44
	v_add_u32_e32 v59, 0xc0c0, v44
	v_add_u32_e32 v60, 0xc0c8, v44
	v_add_u32_e32 v61, 0xe0e0, v44
	v_add_u32_e32 v62, 0xe0e8, v44

; DI int get_tid(int wv) { int l; asm volatile("v_mbcnt_lo_u32_b32 %0, -1, 0\n\tv_mbcnt_hi_u32_b32 %0, -1, %0" : "=v"(l)); return wv * 64 + l; }
; DI void transpose_tile(WVP float* sm, const float* __restrict__ src, int lds_, u16* __restrict__ dst, int ldd, int k0, int n0) {
;   const int tid = get_tid(WV);
;   constexpr int P = 257;
;   f32x4 v[8];
;   const int rb = tid >> 6, c4 = (tid & 63) * 4;
; #pragma unroll
;   for (int i = 0; i < 8; ++i) v[i] = *(const f32x4*)(src + (long)(k0 + rb + 8 * i) * lds_ + n0 + c4);
;   __syncthreads();
; #pragma unroll
;   for (int i = 0; i < 8; ++i) for (int j = 0; j < 4; ++j) sm[(rb + 8 * i) * P + c4 + j] = v[i][j];
;     ...
;     int first = (BID - base % GRD + GRD) % GRD;
;     for (int i = first; i < cnt; i += GRD) transpose_tile(WV, sm, src[j], lds_[j], dst[j], Kd[j], (i / nn) * 64, (i % nn) * 256);
.LBB0_380:
	s_lshr_b32 s0, s22, 25
	s_mul_i32 s0, s0, s12
	s_sub_i32 s0, 0x80, s0
	s_sub_i32 s1, s0, s12
	s_cmp_ge_u32 s0, s12
	s_cselect_b32 s0, s1, s0
	s_sub_i32 s1, s0, s12
	s_cmp_ge_u32 s0, s12
	s_cselect_b32 s0, s1, s0
	s_sub_i32 s0, s13, s0
	s_ashr_i32 s1, s0, 31
	s_abs_i32 s0, s0
	s_mul_hi_u32 s4, s0, s22
	s_mul_i32 s4, s4, s12
	s_sub_i32 s0, s0, s4
	s_sub_i32 s4, s0, s12
	s_cmp_ge_u32 s0, s12
	s_cselect_b32 s0, s4, s0
	s_sub_i32 s4, s0, s12
	s_cmp_ge_u32 s0, s12
	s_cselect_b32 s0, s4, s0
	s_xor_b32 s0, s0, s1
	s_sub_i32 s0, s0, s1
	s_cmp_gt_i32 s0, 63
	s_cbranch_scc1 .LBB0_383
	s_add_u32 s1, s23, 0x800000
	s_addc_u32 s25, s24, 0
	s_add_u32 s26, s54, 0x1df00000
	s_addc_u32 s27, s55, 0
	s_lshl_b32 s28, s0, 8
	s_lshl_b32 s29, s20, 8
	s_ashr_i32 s4, s0, 31
	s_lshr_b32 s4, s4, 30
	s_add_i32 s4, s0, s4
	s_ashr_i32 s5, s4, 2
	s_lshl_b32 s4, s5, 6
	s_lshl_b32 s5, s5, 10
	v_mbcnt_lo_u32_b32 v0, -1, 0
	v_mbcnt_hi_u32_b32 v0, -1, v0
	s_sub_i32 s30, s28, s5
	v_add_u32_e32 v2, s3, v0
	v_lshlrev_b32_e32 v3, 4, v0
	v_lshlrev_b32_e32 v4, 3, v0
	v_ashrrev_i32_e32 v5, 6, v2
	v_and_b32_e32 v0, 0x3f0, v3
	v_and_b32_e32 v42, 56, v4
	v_ashrrev_i32_e32 v3, 3, v2
	v_add_u32_e32 v4, 0x200, v2
	v_add_u32_e32 v6, 0x400, v2
	v_add_u32_e32 v2, 0x600, v2
	s_ashr_i32 s31, s30, 31
	v_mul_lo_u32 v7, v5, s34
	v_mad_u32_u24 v8, v42, s34, 0
	v_ashrrev_i32_e32 v4, 3, v4
	v_ashrrev_i32_e32 v9, 3, v2
	v_add_u32_e32 v2, s4, v5
	v_subrev_u32_e32 v5, s5, v3
	s_lshl_b64 s[30:31], s[30:31], 2
	v_ashrrev_i32_e32 v6, 3, v6
	v_add3_u32 v44, 0, v0, v7
	v_lshl_add_u32 v46, v4, 2, v8
	v_subrev_u32_e32 v7, s5, v4
	v_add_u32_e32 v4, s28, v5
	s_add_u32 s30, s1, s30
	v_lshl_add_u32 v45, v3, 2, v8
	v_lshl_add_u32 v47, v6, 2, v8
	v_lshl_add_u32 v48, v9, 2, v8
	v_subrev_u32_e32 v8, s5, v6
	v_ashrrev_i32_e32 v3, 31, v2
	v_add_u32_e32 v6, s28, v7
	v_ashrrev_i32_e32 v5, 31, v4
	s_addc_u32 s31, s25, s31
	v_subrev_u32_e32 v9, s5, v9
	v_add_u32_e32 v8, s28, v8
	v_lshlrev_b64 v[2:3], 12, v[2:3]
	v_ashrrev_i32_e32 v7, 31, v6
	v_lshlrev_b64 v[34:35], 11, v[4:5]
	v_lshl_add_u64 v[4:5], s[30:31], 0, v[0:1]
	v_add_u32_e32 v10, s28, v9
	v_ashrrev_i32_e32 v9, 31, v8
	v_lshlrev_b64 v[36:37], 11, v[6:7]
	v_lshl_add_u64 v[6:7], v[4:5], 0, v[2:3]
	v_lshlrev_b64 v[38:39], 11, v[8:9]
	v_add_co_u32_e32 v8, vcc, s38, v6
	v_ashrrev_i32_e32 v11, 31, v10
	s_nop 0
	v_addc_co_u32_e32 v9, vcc, 0, v7, vcc
	v_lshlrev_b64 v[40:41], 11, v[10:11]
	v_add_co_u32_e32 v10, vcc, s36, v6
	global_load_dwordx4 v[2:5], v[6:7], off
	s_nop 0
	v_addc_co_u32_e32 v11, vcc, 0, v7, vcc
	v_add_co_u32_e32 v14, vcc, s37, v6
	s_ashr_i32 s5, s4, 31
	s_nop 0
	v_addc_co_u32_e32 v15, vcc, 0, v7, vcc
	v_add_co_u32_e32 v18, vcc, s39, v6
	s_lshl_b64 s[4:5], s[4:5], 1
	s_nop 0
	v_addc_co_u32_e32 v19, vcc, 0, v7, vcc
	v_add_co_u32_e32 v22, vcc, s40, v6
	s_add_u32 s4, s26, s4
	s_nop 0
	v_addc_co_u32_e32 v23, vcc, 0, v7, vcc
	v_add_co_u32_e32 v26, vcc, s41, v6
	v_lshlrev_b32_e32 v0, 1, v42
	s_nop 0
	v_addc_co_u32_e32 v27, vcc, 0, v7, vcc
	v_add_co_u32_e32 v30, vcc, s42, v6
	s_addc_u32 s5, s27, s5
	s_nop 0
	v_addc_co_u32_e32 v31, vcc, 0, v7, vcc
	global_load_dwordx4 v[6:9], v[8:9], off
	s_nop 0
	global_load_dwordx4 v[10:13], v[10:11], off
	s_nop 0
	global_load_dwordx4 v[14:17], v[14:15], off
	s_nop 0
	global_load_dwordx4 v[18:21], v[18:19], off
	s_nop 0
	global_load_dwordx4 v[22:25], v[22:23], off
	s_nop 0
	global_load_dwordx4 v[26:29], v[26:27], off
	s_nop 0
	global_load_dwordx4 v[30:33], v[30:31], off
	v_add_u32_e32 v49, 0x2020, v44
	v_add_u32_e32 v50, 0x2028, v44
	v_add_u32_e32 v51, 0x4040, v44
	v_add_u32_e32 v52, 0x4048, v44
	v_add_u32_e32 v53, 0x6060, v44
	v_add_u32_e32 v54, 0x6068, v44
	v_add_u32_e32 v55, 0x8080, v44
	v_add_u32_e32 v56, 0x8088, v44
	v_add_u32_e32 v57, 0xa0a0, v44
	v_add_u32_e32 v58, 0xa0a8, v44
	v_add_u32_e32 v59, 0xc0c0, v44
	v_add_u32_e32 v60, 0xc0c8, v44
	v_add_u32_e32 v61, 0xe0e0, v44
	v_add_u32_e32 v62, 0xe0e8, v44
	s_waitcnt vmcnt(0)

; DI int get_tid(int wv) { int l; asm volatile("v_mbcnt_lo_u32_b32 %0, -1, 0\n\tv_mbcnt_hi_u32_b32 %0, -1, %0" : "=v"(l)); return wv * 64 + l; }
; DI void transpose_tile(WVP float* sm, const float* __restrict__ src, int lds_, u16* __restrict__ dst, int ldd, int k0, int n0) {
;   const int tid = get_tid(WV);
;   constexpr int P = 257;
;   f32x4 v[8];
;   const int rb = tid >> 6, c4 = (tid & 63) * 4;
; #pragma unroll
;   for (int i = 0; i < 8; ++i) v[i] = *(const f32x4*)(src + (long)(k0 + rb + 8 * i) * lds_ + n0 + c4);
;   __syncthreads();
; #pragma unroll
;   for (int i = 0; i < 8; ++i) for (int j = 0; j < 4; ++j) sm[(rb + 8 * i) * P + c4 + j] = v[i][j];
;     ...
;     int first = (BID - base % GRD + GRD) % GRD;
;     for (int i = first; i < cnt; i += GRD) transpose_tile(WV, sm, src[j], lds_[j], dst[j], Kd[j], (i / nn) * 64, (i % nn) * 256);
.LBB0_383:
	s_mul_hi_u32 s0, s22, 0xc0
	s_mul_i32 s0, s0, s12
	s_sub_i32 s0, 0xc0, s0
	s_sub_i32 s1, s0, s12
	s_cmp_ge_u32 s0, s12
	s_cselect_b32 s0, s1, s0
	s_sub_i32 s1, s0, s12
	s_cmp_ge_u32 s0, s12
	s_cselect_b32 s0, s1, s0
	s_sub_i32 s0, s13, s0
	s_ashr_i32 s1, s0, 31
	s_abs_i32 s0, s0
	s_mul_hi_u32 s4, s0, s22
	s_mul_i32 s4, s4, s12
	s_sub_i32 s0, s0, s4
	s_sub_i32 s4, s0, s12
	s_cmp_ge_u32 s0, s12
	s_cselect_b32 s0, s4, s0
	s_sub_i32 s4, s0, s12
	s_cmp_ge_u32 s0, s12
	s_cselect_b32 s0, s4, s0
	s_xor_b32 s0, s0, s1
	s_sub_i32 s0, s0, s1
	s_cmp_gt_i32 s0, 63
	s_cbranch_scc1 .LBB0_386
	s_add_u32 s1, s23, 0xc00000
	s_addc_u32 s23, s24, 0
	s_add_u32 s24, s54, 0x1e100000
	s_addc_u32 s25, s55, 0
	s_lshl_b32 s26, s0, 8
	s_lshl_b32 s27, s20, 8
	s_ashr_i32 s4, s0, 31
	s_lshr_b32 s4, s4, 30
	s_add_i32 s4, s0, s4
	s_ashr_i32 s5, s4, 2
	s_lshl_b32 s4, s5, 6
	s_lshl_b32 s5, s5, 10
	v_mbcnt_lo_u32_b32 v0, -1, 0
	v_mbcnt_hi_u32_b32 v0, -1, v0
	s_sub_i32 s28, s26, s5
	v_add_u32_e32 v2, s3, v0
	v_lshlrev_b32_e32 v3, 4, v0
	v_lshlrev_b32_e32 v4, 3, v0
	v_ashrrev_i32_e32 v5, 6, v2
	v_and_b32_e32 v0, 0x3f0, v3
	v_and_b32_e32 v42, 56, v4
	v_ashrrev_i32_e32 v3, 3, v2
	v_add_u32_e32 v4, 0x200, v2
	v_add_u32_e32 v6, 0x400, v2
	v_add_u32_e32 v2, 0x600, v2
	s_ashr_i32 s29, s28, 31
	v_mul_lo_u32 v7, v5, s34
	v_mad_u32_u24 v8, v42, s34, 0
	v_ashrrev_i32_e32 v4, 3, v4
	v_ashrrev_i32_e32 v9, 3, v2
	v_add_u32_e32 v2, s4, v5
	v_subrev_u32_e32 v5, s5, v3
	s_lshl_b64 s[28:29], s[28:29], 2
	v_ashrrev_i32_e32 v6, 3, v6
	v_add3_u32 v44, 0, v0, v7
	v_lshl_add_u32 v46, v4, 2, v8
	v_subrev_u32_e32 v7, s5, v4
	v_add_u32_e32 v4, s26, v5
	s_add_u32 s28, s1, s28
	v_lshl_add_u32 v45, v3, 2, v8
	v_lshl_add_u32 v47, v6, 2, v8
	v_lshl_add_u32 v48, v9, 2, v8
	v_subrev_u32_e32 v8, s5, v6
	v_ashrrev_i32_e32 v3, 31, v2
	v_add_u32_e32 v6, s26, v7
	v_ashrrev_i32_e32 v5, 31, v4
	s_addc_u32 s29, s23, s29
	v_subrev_u32_e32 v9, s5, v9
	v_add_u32_e32 v8, s26, v8
	v_lshlrev_b64 v[2:3], 12, v[2:3]
	v_ashrrev_i32_e32 v7, 31, v6
	v_lshlrev_b64 v[34:35], 11, v[4:5]
	v_lshl_add_u64 v[4:5], s[28:29], 0, v[0:1]
	v_add_u32_e32 v10, s26, v9
	v_ashrrev_i32_e32 v9, 31, v8
	v_lshlrev_b64 v[36:37], 11, v[6:7]
	v_lshl_add_u64 v[6:7], v[4:5], 0, v[2:3]
	v_lshlrev_b64 v[38:39], 11, v[8:9]
	v_add_co_u32_e32 v8, vcc, s38, v6
	v_ashrrev_i32_e32 v11, 31, v10
	s_nop 0
	v_addc_co_u32_e32 v9, vcc, 0, v7, vcc
	v_lshlrev_b64 v[40:41], 11, v[10:11]
	v_add_co_u32_e32 v10, vcc, s36, v6
	global_load_dwordx4 v[2:5], v[6:7], off
	s_nop 0
	v_addc_co_u32_e32 v11, vcc, 0, v7, vcc
	v_add_co_u32_e32 v14, vcc, s37, v6
	s_ashr_i32 s5, s4, 31
	s_nop 0
	v_addc_co_u32_e32 v15, vcc, 0, v7, vcc
	v_add_co_u32_e32 v18, vcc, s39, v6
	s_lshl_b64 s[4:5], s[4:5], 1
	s_nop 0
	v_addc_co_u32_e32 v19, vcc, 0, v7, vcc
	v_add_co_u32_e32 v22, vcc, s40, v6
	s_add_u32 s4, s24, s4
	s_nop 0
	v_addc_co_u32_e32 v23, vcc, 0, v7, vcc
	v_add_co_u32_e32 v26, vcc, s41, v6
	v_lshlrev_b32_e32 v0, 1, v42
	s_nop 0
	v_addc_co_u32_e32 v27, vcc, 0, v7, vcc
	v_add_co_u32_e32 v30, vcc, s42, v6
	s_addc_u32 s5, s25, s5
	s_nop 0
	v_addc_co_u32_e32 v31, vcc, 0, v7, vcc
	global_load_dwordx4 v[6:9], v[8:9], off
	s_nop 0
	global_load_dwordx4 v[10:13], v[10:11], off
	s_nop 0
	global_load_dwordx4 v[14:17], v[14:15], off
	s_nop 0
	global_load_dwordx4 v[18:21], v[18:19], off
	s_nop 0
	global_load_dwordx4 v[22:25], v[22:23], off
	s_nop 0
	global_load_dwordx4 v[26:29], v[26:27], off
	s_nop 0
	global_load_dwordx4 v[30:33], v[30:31], off
	v_add_u32_e32 v49, 0x2020, v44
	v_add_u32_e32 v50, 0x2028, v44
	v_add_u32_e32 v51, 0x4040, v44
	v_add_u32_e32 v52, 0x4048, v44
	v_add_u32_e32 v53, 0x6060, v44
	v_add_u32_e32 v54, 0x6068, v44
	v_add_u32_e32 v55, 0x8080, v44
	v_add_u32_e32 v56, 0x8088, v44
	v_add_u32_e32 v57, 0xa0a0, v44
	v_add_u32_e32 v58, 0xa0a8, v44
	v_add_u32_e32 v59, 0xc0c0, v44
	v_add_u32_e32 v60, 0xc0c8, v44
	v_add_u32_e32 v61, 0xe0e0, v44
	v_add_u32_e32 v62, 0xe0e8, v44
	s_waitcnt vmcnt(0)
; DI unsigned pack2(float a, float b) { f2_t v = {a, b}; bf2_t r = __builtin_convertvector(v, bf2_t); return __builtin_bit_cast(unsigned, r); }
; DI int get_tid(int wv) { int l; asm volatile("v_mbcnt_lo_u32_b32 %0, -1, 0\n\tv_mbcnt_hi_u32_b32 %0, -1, %0" : "=v"(l)); return wv * 64 + l; }
; DI void transpose_tile(WVP float* sm, const float* __restrict__ src, int lds_, u16* __restrict__ dst, int ldd, int k0, int n0) {
;   const int tid = get_tid(WV);
;   constexpr int P = 257;
;   f32x4 v[8];
;   const int rb = tid >> 6, c4 = (tid & 63) * 4;
; #pragma unroll
;   for (int i = 0; i < 8; ++i) v[i] = *(const f32x4*)(src + (long)(k0 + rb + 8 * i) * lds_ + n0 + c4);
;   __syncthreads();
; #pragma unroll
;   for (int i = 0; i < 8; ++i) for (int j = 0; j < 4; ++j) sm[(rb + 8 * i) * P + c4 + j] = v[i][j];
;   __syncthreads();
; #pragma unroll
;   for (int i = 0; i < 4; ++i) {
;     const int c = tid + NTHR * i, n = c >> 3, k8 = (c & 7) * 8;
;     u32x4 o;
;     o[0] = pack2(sm[(k8 + 0) * P + n], sm[(k8 + 1) * P + n]); o[1] = pack2(sm[(k8 + 2) * P + n], sm[(k8 + 3) * P + n]);
;     o[2] = pack2(sm[(k8 + 4) * P + n], sm[(k8 + 5) * P + n]); o[3] = pack2(sm[(k8 + 6) * P + n], sm[(k8 + 7) * P + n]);
;     *(u32x4*)(dst + (long)(n0 + n) * ldd + k0 + k8) = o;
;   }
.LBB0_385:
	s_barrier
	v_lshl_add_u64 v[100:101], s[4:5], 0, v[0:1]
	v_lshl_add_u64 v[102:103], v[100:101], 0, v[34:35]
	v_lshl_add_u64 v[104:105], v[100:101], 0, v[36:37]
	v_lshl_add_u64 v[106:107], v[100:101], 0, v[38:39]
	v_lshl_add_u64 v[108:109], v[100:101], 0, v[40:41]
	s_waitcnt vmcnt(11)
	ds_write2_b32 v44, v2, v3 offset1:1
	ds_write2_b32 v44, v4, v5 offset0:2 offset1:3
	s_waitcnt vmcnt(10)
	ds_write2_b32 v49, v6, v7 offset1:1
	ds_write2_b32 v50, v8, v9 offset1:1
	s_waitcnt vmcnt(9)
	ds_write2_b32 v51, v10, v11 offset1:1
	ds_write2_b32 v52, v12, v13 offset1:1
	s_waitcnt vmcnt(8)
	ds_write2_b32 v53, v14, v15 offset1:1
	ds_write2_b32 v54, v16, v17 offset1:1
	s_waitcnt vmcnt(7)
	ds_write2_b32 v55, v18, v19 offset1:1
	ds_write2_b32 v56, v20, v21 offset1:1
	s_waitcnt vmcnt(6)
	ds_write2_b32 v57, v22, v23 offset1:1
	ds_write2_b32 v58, v24, v25 offset1:1
	s_waitcnt vmcnt(5)
	ds_write2_b32 v59, v26, v27 offset1:1
	ds_write2_b32 v60, v28, v29 offset1:1
	s_waitcnt vmcnt(4)
	ds_write2_b32 v61, v30, v31 offset1:1
	ds_write2_b32 v62, v32, v33 offset1:1
	s_waitcnt lgkmcnt(0)
	s_barrier
	s_add_i32 s0, s0, s20
	s_add_i32 s26, s26, s27
	s_movk_i32 s34, 0x404
	s_cmp_lt_i32 s0, 64
	s_cbranch_scc0 .Lwp_skip_385
	s_ashr_i32 s4, s0, 31
	s_lshr_b32 s4, s4, 30
	s_add_i32 s4, s0, s4
	s_ashr_i32 s5, s4, 2
	s_lshl_b32 s4, s5, 6
	s_lshl_b32 s5, s5, 10
	v_mbcnt_lo_u32_b32 v0, -1, 0
	v_mbcnt_hi_u32_b32 v0, -1, v0
	s_sub_i32 s28, s26, s5
	v_add_u32_e32 v2, s3, v0
	v_lshlrev_b32_e32 v3, 4, v0
	v_lshlrev_b32_e32 v4, 3, v0
	v_ashrrev_i32_e32 v5, 6, v2
	v_and_b32_e32 v0, 0x3f0, v3
	v_and_b32_e32 v42, 56, v4
	v_ashrrev_i32_e32 v3, 3, v2
	v_add_u32_e32 v4, 0x200, v2
	v_add_u32_e32 v6, 0x400, v2
	v_add_u32_e32 v2, 0x600, v2
	s_ashr_i32 s29, s28, 31
	v_mul_lo_u32 v7, v5, s34
	v_mad_u32_u24 v8, v42, s34, 0
	v_ashrrev_i32_e32 v4, 3, v4
	v_ashrrev_i32_e32 v9, 3, v2
	v_add_u32_e32 v2, s4, v5
	v_subrev_u32_e32 v5, s5, v3
	s_lshl_b64 s[28:29], s[28:29], 2
	v_ashrrev_i32_e32 v6, 3, v6
	v_add3_u32 v44, 0, v0, v7
	v_lshl_add_u32 v46, v4, 2, v8
	v_subrev_u32_e32 v7, s5, v4
	v_add_u32_e32 v4, s26, v5
	s_add_u32 s28, s1, s28
	v_lshl_add_u32 v45, v3, 2, v8
	v_lshl_add_u32 v47, v6, 2, v8
	v_lshl_add_u32 v48, v9, 2, v8
	v_subrev_u32_e32 v8, s5, v6
	v_ashrrev_i32_e32 v3, 31, v2
	v_add_u32_e32 v6, s26, v7
	v_ashrrev_i32_e32 v5, 31, v4
	s_addc_u32 s29, s23, s29
	v_subrev_u32_e32 v9, s5, v9
	v_add_u32_e32 v8, s26, v8
	v_lshlrev_b64 v[2:3], 12, v[2:3]
	v_ashrrev_i32_e32 v7, 31, v6
	v_lshlrev_b64 v[34:35], 11, v[4:5]
	v_lshl_add_u64 v[4:5], s[28:29], 0, v[0:1]
	v_add_u32_e32 v10, s26, v9
	v_ashrrev_i32_e32 v9, 31, v8
	v_lshlrev_b64 v[36:37], 11, v[6:7]
	v_lshl_add_u64 v[6:7], v[4:5], 0, v[2:3]
	v_lshlrev_b64 v[38:39], 11, v[8:9]
	v_add_co_u32_e32 v8, vcc, s38, v6
	v_ashrrev_i32_e32 v11, 31, v10
	s_nop 0
	v_addc_co_u32_e32 v9, vcc, 0, v7, vcc
	v_lshlrev_b64 v[40:41], 11, v[10:11]
	v_add_co_u32_e32 v10, vcc, s36, v6
	global_load_dwordx4 v[2:5], v[6:7], off
	s_nop 0
	v_addc_co_u32_e32 v11, vcc, 0, v7, vcc
	v_add_co_u32_e32 v14, vcc, s37, v6
	s_ashr_i32 s5, s4, 31
	s_nop 0
	v_addc_co_u32_e32 v15, vcc, 0, v7, vcc
	v_add_co_u32_e32 v18, vcc, s39, v6
	s_lshl_b64 s[4:5], s[4:5], 1
	s_nop 0
	v_addc_co_u32_e32 v19, vcc, 0, v7, vcc
	v_add_co_u32_e32 v22, vcc, s40, v6
	s_add_u32 s4, s24, s4
	s_nop 0
	v_addc_co_u32_e32 v23, vcc, 0, v7, vcc
	v_add_co_u32_e32 v26, vcc, s41, v6
	v_lshlrev_b32_e32 v0, 1, v42
	s_nop 0
	v_addc_co_u32_e32 v27, vcc, 0, v7, vcc
	v_add_co_u32_e32 v30, vcc, s42, v6
	s_addc_u32 s5, s25, s5
	s_nop 0
	v_addc_co_u32_e32 v31, vcc, 0, v7, vcc
	global_load_dwordx4 v[6:9], v[8:9], off
	s_nop 0
	global_load_dwordx4 v[10:13], v[10:11], off
	s_nop 0
	global_load_dwordx4 v[14:17], v[14:15], off
	s_nop 0
	global_load_dwordx4 v[18:21], v[18:19], off
	s_nop 0
	global_load_dwordx4 v[22:25], v[22:23], off
	s_nop 0
	global_load_dwordx4 v[26:29], v[26:27], off
	s_nop 0
	global_load_dwordx4 v[30:33], v[30:31], off
	v_add_u32_e32 v49, 0x2020, v44
	v_add_u32_e32 v50, 0x2028, v44
	v_add_u32_e32 v51, 0x4040, v44
	v_add_u32_e32 v52, 0x4048, v44
	v_add_u32_e32 v53, 0x6060, v44
	v_add_u32_e32 v54, 0x6068, v44
	v_add_u32_e32 v55, 0x8080, v44
	v_add_u32_e32 v56, 0x8088, v44
	v_add_u32_e32 v57, 0xa0a0, v44
	v_add_u32_e32 v58, 0xa0a8, v44
	v_add_u32_e32 v59, 0xc0c0, v44
	v_add_u32_e32 v60, 0xc0c8, v44
	v_add_u32_e32 v61, 0xe0e0, v44
	v_add_u32_e32 v62, 0xe0e8, v44

; DI int get_tid(int wv) { int l; asm volatile("v_mbcnt_lo_u32_b32 %0, -1, 0\n\tv_mbcnt_hi_u32_b32 %0, -1, %0" : "=v"(l)); return wv * 64 + l; }
; DI void transpose_tile(WVP float* sm, const float* __restrict__ src, int lds_, u16* __restrict__ dst, int ldd, int k0, int n0) {
;   const int tid = get_tid(WV);
;   constexpr int P = 257;
;   f32x4 v[8];
;   const int rb = tid >> 6, c4 = (tid & 63) * 4;
; #pragma unroll
;   for (int i = 0; i < 8; ++i) v[i] = *(const f32x4*)(src + (long)(k0 + rb + 8 * i) * lds_ + n0 + c4);
;   __syncthreads();
; #pragma unroll
;   for (int i = 0; i < 8; ++i) for (int j = 0; j < 4; ++j) sm[(rb + 8 * i) * P + c4 + j] = v[i][j];
;   __syncthreads();
;     ...
;     int first = (BID - base % GRD + GRD) % GRD;
;     for (int i = first; i < cnt; i += GRD) transpose_tile(WV, sm, src[j], lds_[j], dst[j], Kd[j], (i / nn) * 64, (i % nn) * 256);
.LBB0_386:
	s_mul_i32 s24, s46, 0x700000
	s_mul_hi_i32 s23, s46, 0x700000
	s_add_u32 s0, s10, s24
	s_addc_u32 s1, s11, s23
	s_lshr_b32 s4, s22, 24
	s_mul_i32 s4, s4, s12
	s_sub_i32 s4, 0x100, s4
	s_sub_i32 s5, s4, s12
	s_cmp_ge_u32 s4, s12
	s_cselect_b32 s4, s5, s4
	s_sub_i32 s5, s4, s12
	s_cmp_ge_u32 s4, s12
	s_cselect_b32 s4, s5, s4
	s_sub_i32 s4, s13, s4
	s_ashr_i32 s5, s4, 31
	s_abs_i32 s4, s4
	s_mul_hi_u32 s25, s4, s22
	s_mul_i32 s25, s25, s12
	s_sub_i32 s4, s4, s25
	s_sub_i32 s25, s4, s12
	s_cmp_ge_u32 s4, s12
	s_cselect_b32 s4, s25, s4
	s_sub_i32 s25, s4, s12
	s_cmp_ge_u32 s4, s12
	s_cselect_b32 s4, s25, s4
	s_xor_b32 s4, s4, s5
	s_sub_i32 s25, s4, s5
	s_cmp_gt_i32 s25, 15
	s_cbranch_scc1 .LBB0_389
	s_add_u32 s26, s0, 0x200000
	s_addc_u32 s27, s1, 0
	s_add_u32 s28, s54, 0x1e400000
	s_addc_u32 s29, s55, 0
	s_lshl_b32 s30, s25, 8
	s_lshl_b32 s31, s20, 8
	s_ashr_i32 s4, s25, 31
	s_lshr_b32 s4, s4, 30
	s_add_i32 s4, s25, s4
	v_mbcnt_lo_u32_b32 v0, -1, 0
	v_mbcnt_hi_u32_b32 v0, -1, v0
	s_ashr_i32 s5, s4, 2
	v_add_u32_e32 v2, s3, v0
	v_lshlrev_b32_e32 v4, 3, v0
	v_ashrrev_i32_e32 v5, 6, v2
	v_and_b32_e32 v42, 56, v4
	s_lshl_b32 s4, s5, 6
	s_lshl_b32 s5, s5, 10
	v_lshlrev_b32_e32 v3, 4, v0
	v_mul_lo_u32 v7, v5, s34
	v_mad_u32_u24 v8, v42, s34, 0
	s_sub_i32 s34, s30, s5
	v_and_b32_e32 v0, 0x3f0, v3
	v_ashrrev_i32_e32 v3, 3, v2
	v_add_u32_e32 v4, 0x200, v2
	v_add_u32_e32 v6, 0x400, v2
	v_add_u32_e32 v2, 0x600, v2
	s_ashr_i32 s35, s34, 31
	v_ashrrev_i32_e32 v4, 3, v4
	v_ashrrev_i32_e32 v9, 3, v2
	v_add_u32_e32 v2, s4, v5
	v_subrev_u32_e32 v5, s5, v3
	s_lshl_b64 s[34:35], s[34:35], 2
	v_ashrrev_i32_e32 v6, 3, v6
	v_add3_u32 v44, 0, v0, v7
	v_lshl_add_u32 v46, v4, 2, v8
	v_subrev_u32_e32 v7, s5, v4
	v_add_u32_e32 v4, s30, v5
	s_add_u32 s34, s26, s34
	v_lshl_add_u32 v45, v3, 2, v8
	v_lshl_add_u32 v47, v6, 2, v8
	v_lshl_add_u32 v48, v9, 2, v8
	v_subrev_u32_e32 v8, s5, v6
	v_ashrrev_i32_e32 v3, 31, v2
	v_add_u32_e32 v6, s30, v7
	v_ashrrev_i32_e32 v5, 31, v4
	s_addc_u32 s35, s27, s35
	v_subrev_u32_e32 v9, s5, v9
	v_add_u32_e32 v8, s30, v8
	v_lshlrev_b64 v[2:3], 12, v[2:3]
	v_ashrrev_i32_e32 v7, 31, v6
	v_lshlrev_b64 v[34:35], 9, v[4:5]
	v_lshl_add_u64 v[4:5], s[34:35], 0, v[0:1]
	v_add_u32_e32 v10, s30, v9
	v_ashrrev_i32_e32 v9, 31, v8
	v_lshlrev_b64 v[36:37], 9, v[6:7]
	v_lshl_add_u64 v[6:7], v[4:5], 0, v[2:3]
	v_lshlrev_b64 v[38:39], 9, v[8:9]
	v_add_co_u32_e32 v8, vcc, s38, v6
	v_ashrrev_i32_e32 v11, 31, v10
	s_nop 0
	v_addc_co_u32_e32 v9, vcc, 0, v7, vcc
	v_lshlrev_b64 v[40:41], 9, v[10:11]
	v_add_co_u32_e32 v10, vcc, s36, v6
	global_load_dwordx4 v[2:5], v[6:7], off
	s_nop 0
	v_addc_co_u32_e32 v11, vcc, 0, v7, vcc
	v_add_co_u32_e32 v14, vcc, s37, v6
	s_ashr_i32 s5, s4, 31
	s_nop 0
	v_addc_co_u32_e32 v15, vcc, 0, v7, vcc
	v_add_co_u32_e32 v18, vcc, s39, v6
	s_lshl_b64 s[4:5], s[4:5], 1
	s_nop 0
	v_addc_co_u32_e32 v19, vcc, 0, v7, vcc
	v_add_co_u32_e32 v22, vcc, s40, v6
	s_add_u32 s4, s28, s4
	s_nop 0
	v_addc_co_u32_e32 v23, vcc, 0, v7, vcc
	v_add_co_u32_e32 v26, vcc, s41, v6
	v_lshlrev_b32_e32 v0, 1, v42
	s_nop 0
	v_addc_co_u32_e32 v27, vcc, 0, v7, vcc
	v_add_co_u32_e32 v30, vcc, s42, v6
	s_addc_u32 s5, s29, s5
	s_nop 0
	v_addc_co_u32_e32 v31, vcc, 0, v7, vcc
	global_load_dwordx4 v[6:9], v[8:9], off
	s_nop 0
	global_load_dwordx4 v[10:13], v[10:11], off
	s_nop 0
	global_load_dwordx4 v[14:17], v[14:15], off
	s_nop 0
	global_load_dwordx4 v[18:21], v[18:19], off
	s_nop 0
	global_load_dwordx4 v[22:25], v[22:23], off
	s_nop 0
	global_load_dwordx4 v[26:29], v[26:27], off
	s_nop 0
	global_load_dwordx4 v[30:33], v[30:31], off
	v_add_u32_e32 v49, 0x2020, v44
	v_add_u32_e32 v50, 0x2028, v44
	v_add_u32_e32 v51, 0x4040, v44
	v_add_u32_e32 v52, 0x4048, v44
	v_add_u32_e32 v53, 0x6060, v44
	v_add_u32_e32 v54, 0x6068, v44
	v_add_u32_e32 v55, 0x8080, v44
	v_add_u32_e32 v56, 0x8088, v44
	v_add_u32_e32 v57, 0xa0a0, v44
	v_add_u32_e32 v58, 0xa0a8, v44
	v_add_u32_e32 v59, 0xc0c0, v44
	v_add_u32_e32 v60, 0xc0c8, v44
	v_add_u32_e32 v61, 0xe0e0, v44
	v_add_u32_e32 v62, 0xe0e8, v44
	s_waitcnt vmcnt(0)
.LBB0_388:
	s_barrier
	v_lshl_add_u64 v[100:101], s[4:5], 0, v[0:1]
	v_lshl_add_u64 v[102:103], v[100:101], 0, v[34:35]
	v_lshl_add_u64 v[104:105], v[100:101], 0, v[36:37]
	v_lshl_add_u64 v[106:107], v[100:101], 0, v[38:39]
	v_lshl_add_u64 v[108:109], v[100:101], 0, v[40:41]
	s_waitcnt vmcnt(11)
	ds_write2_b32 v44, v2, v3 offset1:1
	ds_write2_b32 v44, v4, v5 offset0:2 offset1:3
	s_waitcnt vmcnt(10)
	ds_write2_b32 v49, v6, v7 offset1:1
	ds_write2_b32 v50, v8, v9 offset1:1
	s_waitcnt vmcnt(9)
	ds_write2_b32 v51, v10, v11 offset1:1
	ds_write2_b32 v52, v12, v13 offset1:1
	s_waitcnt vmcnt(8)
	ds_write2_b32 v53, v14, v15 offset1:1
	ds_write2_b32 v54, v16, v17 offset1:1
	s_waitcnt vmcnt(7)
	ds_write2_b32 v55, v18, v19 offset1:1
	ds_write2_b32 v56, v20, v21 offset1:1
	s_waitcnt vmcnt(6)
	ds_write2_b32 v57, v22, v23 offset1:1
	ds_write2_b32 v58, v24, v25 offset1:1
	s_waitcnt vmcnt(5)
	ds_write2_b32 v59, v26, v27 offset1:1
	ds_write2_b32 v60, v28, v29 offset1:1
	s_waitcnt vmcnt(4)
	ds_write2_b32 v61, v30, v31 offset1:1
	ds_write2_b32 v62, v32, v33 offset1:1
	s_waitcnt lgkmcnt(0)
	s_barrier
	s_add_i32 s25, s25, s20
	s_add_i32 s30, s30, s31
	s_movk_i32 s34, 0x404
	s_cmp_lt_i32 s25, 16
	s_cbranch_scc0 .Lwp_skip_388
; DI unsigned pack2(float a, float b) { f2_t v = {a, b}; bf2_t r = __builtin_convertvector(v, bf2_t); return __builtin_bit_cast(unsigned, r); }
; DI int get_tid(int wv) { int l; asm volatile("v_mbcnt_lo_u32_b32 %0, -1, 0\n\tv_mbcnt_hi_u32_b32 %0, -1, %0" : "=v"(l)); return wv * 64 + l; }
; DI void transpose_tile(WVP float* sm, const float* __restrict__ src, int lds_, u16* __restrict__ dst, int ldd, int k0, int n0) {
;   const int tid = get_tid(WV);
;   constexpr int P = 257;
;   f32x4 v[8];
;   const int rb = tid >> 6, c4 = (tid & 63) * 4;
; #pragma unroll
;   for (int i = 0; i < 8; ++i) v[i] = *(const f32x4*)(src + (long)(k0 + rb + 8 * i) * lds_ + n0 + c4);
;   __syncthreads();
; #pragma unroll
;   for (int i = 0; i < 8; ++i) for (int j = 0; j < 4; ++j) sm[(rb + 8 * i) * P + c4 + j] = v[i][j];
;   __syncthreads();
; #pragma unroll
;   for (int i = 0; i < 4; ++i) {
;     const int c = tid + NTHR * i, n = c >> 3, k8 = (c & 7) * 8;
;     u32x4 o;
;     o[0] = pack2(sm[(k8 + 0) * P + n], sm[(k8 + 1) * P + n]); o[1] = pack2(sm[(k8 + 2) * P + n], sm[(k8 + 3) * P + n]);
;     o[2] = pack2(sm[(k8 + 4) * P + n], sm[(k8 + 5) * P + n]); o[3] = pack2(sm[(k8 + 6) * P + n], sm[(k8 + 7) * P + n]);
;     *(u32x4*)(dst + (long)(n0 + n) * ldd + k0 + k8) = o;
;   }
	s_ashr_i32 s4, s25, 31
	s_lshr_b32 s4, s4, 30
	s_add_i32 s4, s25, s4
	v_mbcnt_lo_u32_b32 v0, -1, 0
	v_mbcnt_hi_u32_b32 v0, -1, v0
	s_ashr_i32 s5, s4, 2
	v_add_u32_e32 v2, s3, v0
	v_lshlrev_b32_e32 v4, 3, v0
	v_ashrrev_i32_e32 v5, 6, v2
	v_and_b32_e32 v42, 56, v4
	s_lshl_b32 s4, s5, 6
	s_lshl_b32 s5, s5, 10
	v_lshlrev_b32_e32 v3, 4, v0
	v_mul_lo_u32 v7, v5, s34
	v_mad_u32_u24 v8, v42, s34, 0
	s_sub_i32 s34, s30, s5
	v_and_b32_e32 v0, 0x3f0, v3
	v_ashrrev_i32_e32 v3, 3, v2
	v_add_u32_e32 v4, 0x200, v2
	v_add_u32_e32 v6, 0x400, v2
	v_add_u32_e32 v2, 0x600, v2
	s_ashr_i32 s35, s34, 31
	v_ashrrev_i32_e32 v4, 3, v4
	v_ashrrev_i32_e32 v9, 3, v2
	v_add_u32_e32 v2, s4, v5
	v_subrev_u32_e32 v5, s5, v3
	s_lshl_b64 s[34:35], s[34:35], 2
	v_ashrrev_i32_e32 v6, 3, v6
	v_add3_u32 v44, 0, v0, v7
	v_lshl_add_u32 v46, v4, 2, v8
	v_subrev_u32_e32 v7, s5, v4
	v_add_u32_e32 v4, s30, v5
	s_add_u32 s34, s26, s34
	v_lshl_add_u32 v45, v3, 2, v8
	v_lshl_add_u32 v47, v6, 2, v8
	v_lshl_add_u32 v48, v9, 2, v8
	v_subrev_u32_e32 v8, s5, v6
	v_ashrrev_i32_e32 v3, 31, v2
	v_add_u32_e32 v6, s30, v7
	v_ashrrev_i32_e32 v5, 31, v4
	s_addc_u32 s35, s27, s35
	v_subrev_u32_e32 v9, s5, v9
	v_add_u32_e32 v8, s30, v8
	v_lshlrev_b64 v[2:3], 12, v[2:3]
	v_ashrrev_i32_e32 v7, 31, v6
	v_lshlrev_b64 v[34:35], 9, v[4:5]
	v_lshl_add_u64 v[4:5], s[34:35], 0, v[0:1]
	v_add_u32_e32 v10, s30, v9
	v_ashrrev_i32_e32 v9, 31, v8
	v_lshlrev_b64 v[36:37], 9, v[6:7]
	v_lshl_add_u64 v[6:7], v[4:5], 0, v[2:3]
	v_lshlrev_b64 v[38:39], 9, v[8:9]
	v_add_co_u32_e32 v8, vcc, s38, v6
	v_ashrrev_i32_e32 v11, 31, v10
	s_nop 0
	v_addc_co_u32_e32 v9, vcc, 0, v7, vcc
	v_lshlrev_b64 v[40:41], 9, v[10:11]
	v_add_co_u32_e32 v10, vcc, s36, v6
	global_load_dwordx4 v[2:5], v[6:7], off
	s_nop 0
	v_addc_co_u32_e32 v11, vcc, 0, v7, vcc
	v_add_co_u32_e32 v14, vcc, s37, v6
	s_ashr_i32 s5, s4, 31
	s_nop 0
	v_addc_co_u32_e32 v15, vcc, 0, v7, vcc
	v_add_co_u32_e32 v18, vcc, s39, v6
	s_lshl_b64 s[4:5], s[4:5], 1
	s_nop 0
	v_addc_co_u32_e32 v19, vcc, 0, v7, vcc
	v_add_co_u32_e32 v22, vcc, s40, v6
	s_add_u32 s4, s28, s4
	s_nop 0
	v_addc_co_u32_e32 v23, vcc, 0, v7, vcc
	v_add_co_u32_e32 v26, vcc, s41, v6
	v_lshlrev_b32_e32 v0, 1, v42
	s_nop 0
	v_addc_co_u32_e32 v27, vcc, 0, v7, vcc
	v_add_co_u32_e32 v30, vcc, s42, v6
	s_addc_u32 s5, s29, s5
	s_nop 0
	v_addc_co_u32_e32 v31, vcc, 0, v7, vcc
	global_load_dwordx4 v[6:9], v[8:9], off
	s_nop 0
	global_load_dwordx4 v[10:13], v[10:11], off
	s_nop 0
	global_load_dwordx4 v[14:17], v[14:15], off
	s_nop 0
	global_load_dwordx4 v[18:21], v[18:19], off
	s_nop 0
	global_load_dwordx4 v[22:25], v[22:23], off
	s_nop 0
	global_load_dwordx4 v[26:29], v[26:27], off
	s_nop 0
	global_load_dwordx4 v[30:33], v[30:31], off
	v_add_u32_e32 v49, 0x2020, v44
	v_add_u32_e32 v50, 0x2028, v44
	v_add_u32_e32 v51, 0x4040, v44
	v_add_u32_e32 v52, 0x4048, v44
	v_add_u32_e32 v53, 0x6060, v44
	v_add_u32_e32 v54, 0x6068, v44
	v_add_u32_e32 v55, 0x8080, v44
	v_add_u32_e32 v56, 0x8088, v44
	v_add_u32_e32 v57, 0xa0a0, v44
	v_add_u32_e32 v58, 0xa0a8, v44
	v_add_u32_e32 v59, 0xc0c0, v44
	v_add_u32_e32 v60, 0xc0c8, v44
	v_add_u32_e32 v61, 0xe0e0, v44
	v_add_u32_e32 v62, 0xe0e8, v44
.Lwp_skip_388:
	ds_read_b32 v64, v45
	ds_read_b32 v66, v45 offset:1028
	ds_read_b32 v67, v45 offset:2056
	ds_read_b32 v68, v45 offset:3084
	ds_read_b32 v69, v45 offset:4112
	ds_read_b32 v70, v45 offset:5140
	ds_read_b32 v71, v45 offset:6168
	ds_read_b32 v72, v45 offset:7196
	ds_read_b32 v73, v46
	ds_read_b32 v74, v46 offset:1028
	ds_read_b32 v75, v46 offset:2056
	ds_read_b32 v76, v46 offset:3084
	ds_read_b32 v77, v46 offset:4112
	ds_read_b32 v78, v46 offset:5140
	ds_read_b32 v79, v46 offset:6168
	ds_read_b32 v80, v46 offset:7196
	ds_read_b32 v81, v47
	ds_read_b32 v82, v47 offset:1028
	ds_read_b32 v83, v47 offset:2056
	ds_read_b32 v84, v47 offset:3084
	ds_read_b32 v85, v47 offset:4112
	ds_read_b32 v86, v47 offset:5140
	ds_read_b32 v87, v47 offset:6168
	ds_read_b32 v88, v47 offset:7196
	ds_read_b32 v89, v48
	ds_read_b32 v90, v48 offset:1028
	ds_read_b32 v91, v48 offset:2056
	ds_read_b32 v92, v48 offset:3084
	ds_read_b32 v93, v48 offset:4112
	ds_read_b32 v94, v48 offset:5140
	ds_read_b32 v95, v48 offset:6168
	ds_read_b32 v96, v48 offset:7196
	s_waitcnt lgkmcnt(14)
	v_cvt_pk_bf16_f32 v66, v64, v66
	v_cvt_pk_bf16_f32 v67, v67, v68
	v_cvt_pk_bf16_f32 v68, v69, v70
	v_cvt_pk_bf16_f32 v69, v71, v72
	v_cvt_pk_bf16_f32 v70, v73, v74
	v_cvt_pk_bf16_f32 v71, v75, v76
	v_cvt_pk_bf16_f32 v72, v77, v78
	v_cvt_pk_bf16_f32 v73, v79, v80
	v_cvt_pk_bf16_f32 v74, v81, v82
	s_waitcnt lgkmcnt(12)
	v_cvt_pk_bf16_f32 v75, v83, v84
	s_waitcnt lgkmcnt(10)
	v_cvt_pk_bf16_f32 v76, v85, v86
	s_waitcnt lgkmcnt(8)
	v_cvt_pk_bf16_f32 v77, v87, v88
	s_waitcnt lgkmcnt(6)
	v_cvt_pk_bf16_f32 v78, v89, v90
	s_waitcnt lgkmcnt(4)
	v_cvt_pk_bf16_f32 v79, v91, v92
	s_waitcnt lgkmcnt(2)
	v_cvt_pk_bf16_f32 v80, v93, v94
	s_waitcnt lgkmcnt(0)
	v_cvt_pk_bf16_f32 v81, v95, v96
	global_store_dwordx4 v[102:103], v[66:69], off
	global_store_dwordx4 v[104:105], v[70:73], off
	global_store_dwordx4 v[106:107], v[74:77], off
	global_store_dwordx4 v[108:109], v[78:81], off
	s_cmp_lt_i32 s25, 16
	s_cbranch_scc1 .LBB0_388
; DI int get_tid(int wv) { int l; asm volatile("v_mbcnt_lo_u32_b32 %0, -1, 0\n\tv_mbcnt_hi_u32_b32 %0, -1, %0" : "=v"(l)); return wv * 64 + l; }
; DI void transpose_tile(WVP float* sm, const float* __restrict__ src, int lds_, u16* __restrict__ dst, int ldd, int k0, int n0) {
;   const int tid = get_tid(WV);
;   constexpr int P = 257;
;   f32x4 v[8];
;   const int rb = tid >> 6, c4 = (tid & 63) * 4;
; #pragma unroll
;   for (int i = 0; i < 8; ++i) v[i] = *(const f32x4*)(src + (long)(k0 + rb + 8 * i) * lds_ + n0 + c4);
;   __syncthreads();
; #pragma unroll
;   for (int i = 0; i < 8; ++i) for (int j = 0; j < 4; ++j) sm[(rb + 8 * i) * P + c4 + j] = v[i][j];
;   __syncthreads();
;     ...
;     int first = (BID - base % GRD + GRD) % GRD;
;     for (int i = first; i < cnt; i += GRD) transpose_tile(WV, sm, src[j], lds_[j], dst[j], Kd[j], (i / nn) * 64, (i % nn) * 256);
.LBB0_389:
	s_mul_hi_u32 s4, s22, 0x110
	s_mul_i32 s4, s4, s12
	s_sub_i32 s4, 0x110, s4
	s_sub_i32 s5, s4, s12
	s_cmp_ge_u32 s4, s12
	s_cselect_b32 s4, s5, s4
	s_sub_i32 s5, s4, s12
	s_cmp_ge_u32 s4, s12
	s_cselect_b32 s4, s5, s4
	s_sub_i32 s4, s13, s4
	s_ashr_i32 s5, s4, 31
	s_abs_i32 s4, s4
	s_mul_hi_u32 s25, s4, s22
	s_mul_i32 s25, s25, s12
	s_sub_i32 s4, s4, s25
	s_sub_i32 s25, s4, s12
	s_cmp_ge_u32 s4, s12
	s_cselect_b32 s4, s25, s4
	s_sub_i32 s25, s4, s12
	s_cmp_ge_u32 s4, s12
	s_cselect_b32 s4, s25, s4
	s_xor_b32 s4, s4, s5
	s_sub_i32 s25, s4, s5
	s_cmp_gt_i32 s25, 31
	s_cbranch_scc1 .LBB0_392
	s_add_u32 s26, s0, 0x300000
	s_addc_u32 s27, s1, 0
	s_add_u32 s28, s54, 0x1e480000
	s_addc_u32 s29, s55, 0
	s_lshl_b32 s30, s25, 8
	s_lshl_b32 s31, s20, 8
	s_ashr_i32 s4, s25, 31
	s_lshr_b32 s4, s4, 30
	s_add_i32 s4, s25, s4
	v_mbcnt_lo_u32_b32 v0, -1, 0
	v_mbcnt_hi_u32_b32 v0, -1, v0
	s_ashr_i32 s5, s4, 2
	v_add_u32_e32 v2, s3, v0
	v_lshlrev_b32_e32 v4, 3, v0
	v_ashrrev_i32_e32 v5, 6, v2
	v_and_b32_e32 v42, 56, v4
	s_lshl_b32 s4, s5, 6
	s_lshl_b32 s5, s5, 10
	v_lshlrev_b32_e32 v3, 4, v0
	v_mul_lo_u32 v7, v5, s34
	v_mad_u32_u24 v8, v42, s34, 0
	s_sub_i32 s34, s30, s5
	v_and_b32_e32 v0, 0x3f0, v3
	v_ashrrev_i32_e32 v3, 3, v2
	v_add_u32_e32 v4, 0x200, v2
	v_add_u32_e32 v6, 0x400, v2
	v_add_u32_e32 v2, 0x600, v2
	s_ashr_i32 s35, s34, 31
	v_ashrrev_i32_e32 v4, 3, v4
	v_ashrrev_i32_e32 v9, 3, v2
	v_add_u32_e32 v2, s4, v5
	v_subrev_u32_e32 v5, s5, v3
	s_lshl_b64 s[34:35], s[34:35], 2
	v_ashrrev_i32_e32 v6, 3, v6
	v_add3_u32 v44, 0, v0, v7
	v_lshl_add_u32 v46, v4, 2, v8
	v_subrev_u32_e32 v7, s5, v4
	v_add_u32_e32 v4, s30, v5
	s_add_u32 s34, s26, s34
	v_lshl_add_u32 v45, v3, 2, v8
	v_lshl_add_u32 v47, v6, 2, v8
	v_lshl_add_u32 v48, v9, 2, v8
	v_subrev_u32_e32 v8, s5, v6
	v_ashrrev_i32_e32 v3, 31, v2
	v_add_u32_e32 v6, s30, v7
	v_ashrrev_i32_e32 v5, 31, v4
	s_addc_u32 s35, s27, s35
	v_subrev_u32_e32 v9, s5, v9
	v_add_u32_e32 v8, s30, v8
	v_lshlrev_b64 v[2:3], 12, v[2:3]
	v_ashrrev_i32_e32 v7, 31, v6
	v_lshlrev_b64 v[34:35], 10, v[4:5]
	v_lshl_add_u64 v[4:5], s[34:35], 0, v[0:1]
	v_add_u32_e32 v10, s30, v9
	v_ashrrev_i32_e32 v9, 31, v8
	v_lshlrev_b64 v[36:37], 10, v[6:7]
	v_lshl_add_u64 v[6:7], v[4:5], 0, v[2:3]
	v_lshlrev_b64 v[38:39], 10, v[8:9]
	v_add_co_u32_e32 v8, vcc, s38, v6
	v_ashrrev_i32_e32 v11, 31, v10
	s_nop 0
	v_addc_co_u32_e32 v9, vcc, 0, v7, vcc
	v_lshlrev_b64 v[40:41], 10, v[10:11]
	v_add_co_u32_e32 v10, vcc, s36, v6
	global_load_dwordx4 v[2:5], v[6:7], off
	s_nop 0
	v_addc_co_u32_e32 v11, vcc, 0, v7, vcc
	v_add_co_u32_e32 v14, vcc, s37, v6
	s_ashr_i32 s5, s4, 31
	s_nop 0
	v_addc_co_u32_e32 v15, vcc, 0, v7, vcc
	v_add_co_u32_e32 v18, vcc, s39, v6
	s_lshl_b64 s[4:5], s[4:5], 1
	s_nop 0
	v_addc_co_u32_e32 v19, vcc, 0, v7, vcc
	v_add_co_u32_e32 v22, vcc, s40, v6
	s_add_u32 s4, s28, s4
	s_nop 0
	v_addc_co_u32_e32 v23, vcc, 0, v7, vcc
	v_add_co_u32_e32 v26, vcc, s41, v6
	v_lshlrev_b32_e32 v0, 1, v42
	s_nop 0
	v_addc_co_u32_e32 v27, vcc, 0, v7, vcc
	v_add_co_u32_e32 v30, vcc, s42, v6
	s_addc_u32 s5, s29, s5
	s_nop 0
	v_addc_co_u32_e32 v31, vcc, 0, v7, vcc
	global_load_dwordx4 v[6:9], v[8:9], off
	s_nop 0
	global_load_dwordx4 v[10:13], v[10:11], off
	s_nop 0
	global_load_dwordx4 v[14:17], v[14:15], off
	s_nop 0
	global_load_dwordx4 v[18:21], v[18:19], off
	s_nop 0
	global_load_dwordx4 v[22:25], v[22:23], off
	s_nop 0
	global_load_dwordx4 v[26:29], v[26:27], off
	s_nop 0
	global_load_dwordx4 v[30:33], v[30:31], off
	v_add_u32_e32 v49, 0x2020, v44
	v_add_u32_e32 v50, 0x2028, v44
	v_add_u32_e32 v51, 0x4040, v44
	v_add_u32_e32 v52, 0x4048, v44
	v_add_u32_e32 v53, 0x6060, v44
	v_add_u32_e32 v54, 0x6068, v44
	v_add_u32_e32 v55, 0x8080, v44
	v_add_u32_e32 v56, 0x8088, v44
	v_add_u32_e32 v57, 0xa0a0, v44
	v_add_u32_e32 v58, 0xa0a8, v44
	v_add_u32_e32 v59, 0xc0c0, v44
	v_add_u32_e32 v60, 0xc0c8, v44
	v_add_u32_e32 v61, 0xe0e0, v44
	v_add_u32_e32 v62, 0xe0e8, v44
	s_waitcnt vmcnt(0)
.LBB0_391:
	s_barrier
	v_lshl_add_u64 v[100:101], s[4:5], 0, v[0:1]
	v_lshl_add_u64 v[102:103], v[100:101], 0, v[34:35]
	v_lshl_add_u64 v[104:105], v[100:101], 0, v[36:37]
	v_lshl_add_u64 v[106:107], v[100:101], 0, v[38:39]
	v_lshl_add_u64 v[108:109], v[100:101], 0, v[40:41]
	s_waitcnt vmcnt(11)
	ds_write2_b32 v44, v2, v3 offset1:1
	ds_write2_b32 v44, v4, v5 offset0:2 offset1:3
	s_waitcnt vmcnt(10)
	ds_write2_b32 v49, v6, v7 offset1:1
	ds_write2_b32 v50, v8, v9 offset1:1
	s_waitcnt vmcnt(9)
	ds_write2_b32 v51, v10, v11 offset1:1
	ds_write2_b32 v52, v12, v13 offset1:1
	s_waitcnt vmcnt(8)
	ds_write2_b32 v53, v14, v15 offset1:1
	ds_write2_b32 v54, v16, v17 offset1:1
	s_waitcnt vmcnt(7)
	ds_write2_b32 v55, v18, v19 offset1:1
	ds_write2_b32 v56, v20, v21 offset1:1
	s_waitcnt vmcnt(6)
	ds_write2_b32 v57, v22, v23 offset1:1
	ds_write2_b32 v58, v24, v25 offset1:1
	s_waitcnt vmcnt(5)
	ds_write2_b32 v59, v26, v27 offset1:1
	ds_write2_b32 v60, v28, v29 offset1:1
	s_waitcnt vmcnt(4)
	ds_write2_b32 v61, v30, v31 offset1:1
	ds_write2_b32 v62, v32, v33 offset1:1
	s_waitcnt lgkmcnt(0)
	s_barrier
	s_add_i32 s25, s25, s20
	s_add_i32 s30, s30, s31
	s_movk_i32 s34, 0x404
	s_cmp_lt_i32 s25, 32
	s_cbranch_scc0 .Lwp_skip_391
; DI unsigned pack2(float a, float b) { f2_t v = {a, b}; bf2_t r = __builtin_convertvector(v, bf2_t); return __builtin_bit_cast(unsigned, r); }
; DI int get_tid(int wv) { int l; asm volatile("v_mbcnt_lo_u32_b32 %0, -1, 0\n\tv_mbcnt_hi_u32_b32 %0, -1, %0" : "=v"(l)); return wv * 64 + l; }
; DI void transpose_tile(WVP float* sm, const float* __restrict__ src, int lds_, u16* __restrict__ dst, int ldd, int k0, int n0) {
;   const int tid = get_tid(WV);
;   constexpr int P = 257;
;   f32x4 v[8];
;   const int rb = tid >> 6, c4 = (tid & 63) * 4;
; #pragma unroll
;   for (int i = 0; i < 8; ++i) v[i] = *(const f32x4*)(src + (long)(k0 + rb + 8 * i) * lds_ + n0 + c4);
;   __syncthreads();
; #pragma unroll
;   for (int i = 0; i < 8; ++i) for (int j = 0; j < 4; ++j) sm[(rb + 8 * i) * P + c4 + j] = v[i][j];
;   __syncthreads();
; #pragma unroll
;   for (int i = 0; i < 4; ++i) {
;     const int c = tid + NTHR * i, n = c >> 3, k8 = (c & 7) * 8;
;     u32x4 o;
;     o[0] = pack2(sm[(k8 + 0) * P + n], sm[(k8 + 1) * P + n]); o[1] = pack2(sm[(k8 + 2) * P + n], sm[(k8 + 3) * P + n]);
;     o[2] = pack2(sm[(k8 + 4) * P + n], sm[(k8 + 5) * P + n]); o[3] = pack2(sm[(k8 + 6) * P + n], sm[(k8 + 7) * P + n]);
;     *(u32x4*)(dst + (long)(n0 + n) * ldd + k0 + k8) = o;
;   }
	s_ashr_i32 s4, s25, 31
	s_lshr_b32 s4, s4, 30
	s_add_i32 s4, s25, s4
	v_mbcnt_lo_u32_b32 v0, -1, 0
	v_mbcnt_hi_u32_b32 v0, -1, v0
	s_ashr_i32 s5, s4, 2
	v_add_u32_e32 v2, s3, v0
	v_lshlrev_b32_e32 v4, 3, v0
	v_ashrrev_i32_e32 v5, 6, v2
	v_and_b32_e32 v42, 56, v4
	s_lshl_b32 s4, s5, 6
	s_lshl_b32 s5, s5, 10
	v_lshlrev_b32_e32 v3, 4, v0
	v_mul_lo_u32 v7, v5, s34
	v_mad_u32_u24 v8, v42, s34, 0
	s_sub_i32 s34, s30, s5
	v_and_b32_e32 v0, 0x3f0, v3
	v_ashrrev_i32_e32 v3, 3, v2
	v_add_u32_e32 v4, 0x200, v2
	v_add_u32_e32 v6, 0x400, v2
	v_add_u32_e32 v2, 0x600, v2
	s_ashr_i32 s35, s34, 31
	v_ashrrev_i32_e32 v4, 3, v4
	v_ashrrev_i32_e32 v9, 3, v2
	v_add_u32_e32 v2, s4, v5
	v_subrev_u32_e32 v5, s5, v3
	s_lshl_b64 s[34:35], s[34:35], 2
	v_ashrrev_i32_e32 v6, 3, v6
	v_add3_u32 v44, 0, v0, v7
	v_lshl_add_u32 v46, v4, 2, v8
	v_subrev_u32_e32 v7, s5, v4
	v_add_u32_e32 v4, s30, v5
	s_add_u32 s34, s26, s34
	v_lshl_add_u32 v45, v3, 2, v8
	v_lshl_add_u32 v47, v6, 2, v8
	v_lshl_add_u32 v48, v9, 2, v8
	v_subrev_u32_e32 v8, s5, v6
	v_ashrrev_i32_e32 v3, 31, v2
	v_add_u32_e32 v6, s30, v7
	v_ashrrev_i32_e32 v5, 31, v4
	s_addc_u32 s35, s27, s35
	v_subrev_u32_e32 v9, s5, v9
	v_add_u32_e32 v8, s30, v8
	v_lshlrev_b64 v[2:3], 12, v[2:3]
	v_ashrrev_i32_e32 v7, 31, v6
	v_lshlrev_b64 v[34:35], 10, v[4:5]
	v_lshl_add_u64 v[4:5], s[34:35], 0, v[0:1]
	v_add_u32_e32 v10, s30, v9
	v_ashrrev_i32_e32 v9, 31, v8
	v_lshlrev_b64 v[36:37], 10, v[6:7]
	v_lshl_add_u64 v[6:7], v[4:5], 0, v[2:3]
	v_lshlrev_b64 v[38:39], 10, v[8:9]
	v_add_co_u32_e32 v8, vcc, s38, v6
	v_ashrrev_i32_e32 v11, 31, v10
	s_nop 0
	v_addc_co_u32_e32 v9, vcc, 0, v7, vcc
	v_lshlrev_b64 v[40:41], 10, v[10:11]
	v_add_co_u32_e32 v10, vcc, s36, v6
	global_load_dwordx4 v[2:5], v[6:7], off
	s_nop 0
	v_addc_co_u32_e32 v11, vcc, 0, v7, vcc
	v_add_co_u32_e32 v14, vcc, s37, v6
	s_ashr_i32 s5, s4, 31
	s_nop 0
	v_addc_co_u32_e32 v15, vcc, 0, v7, vcc
	v_add_co_u32_e32 v18, vcc, s39, v6
	s_lshl_b64 s[4:5], s[4:5], 1
	s_nop 0
	v_addc_co_u32_e32 v19, vcc, 0, v7, vcc
	v_add_co_u32_e32 v22, vcc, s40, v6
	s_add_u32 s4, s28, s4
	s_nop 0
	v_addc_co_u32_e32 v23, vcc, 0, v7, vcc
	v_add_co_u32_e32 v26, vcc, s41, v6
	v_lshlrev_b32_e32 v0, 1, v42
	s_nop 0
	v_addc_co_u32_e32 v27, vcc, 0, v7, vcc
	v_add_co_u32_e32 v30, vcc, s42, v6
	s_addc_u32 s5, s29, s5
	s_nop 0
	v_addc_co_u32_e32 v31, vcc, 0, v7, vcc
	global_load_dwordx4 v[6:9], v[8:9], off
	s_nop 0
	global_load_dwordx4 v[10:13], v[10:11], off
	s_nop 0
	global_load_dwordx4 v[14:17], v[14:15], off
	s_nop 0
	global_load_dwordx4 v[18:21], v[18:19], off
	s_nop 0
	global_load_dwordx4 v[22:25], v[22:23], off
	s_nop 0
	global_load_dwordx4 v[26:29], v[26:27], off
	s_nop 0
	global_load_dwordx4 v[30:33], v[30:31], off
	v_add_u32_e32 v49, 0x2020, v44
	v_add_u32_e32 v50, 0x2028, v44
	v_add_u32_e32 v51, 0x4040, v44
	v_add_u32_e32 v52, 0x4048, v44
	v_add_u32_e32 v53, 0x6060, v44
	v_add_u32_e32 v54, 0x6068, v44
	v_add_u32_e32 v55, 0x8080, v44
	v_add_u32_e32 v56, 0x8088, v44
	v_add_u32_e32 v57, 0xa0a0, v44
	v_add_u32_e32 v58, 0xa0a8, v44
	v_add_u32_e32 v59, 0xc0c0, v44
	v_add_u32_e32 v60, 0xc0c8, v44
	v_add_u32_e32 v61, 0xe0e0, v44
	v_add_u32_e32 v62, 0xe0e8, v44
.Lwp_skip_391:
	ds_read_b32 v64, v45
	ds_read_b32 v66, v45 offset:1028
	ds_read_b32 v67, v45 offset:2056
	ds_read_b32 v68, v45 offset:3084
	ds_read_b32 v69, v45 offset:4112
	ds_read_b32 v70, v45 offset:5140
	ds_read_b32 v71, v45 offset:6168
	ds_read_b32 v72, v45 offset:7196
	ds_read_b32 v73, v46
	ds_read_b32 v74, v46 offset:1028
	ds_read_b32 v75, v46 offset:2056
	ds_read_b32 v76, v46 offset:3084
	ds_read_b32 v77, v46 offset:4112
	ds_read_b32 v78, v46 offset:5140
	ds_read_b32 v79, v46 offset:6168
	ds_read_b32 v80, v46 offset:7196
	ds_read_b32 v81, v47
	ds_read_b32 v82, v47 offset:1028
	ds_read_b32 v83, v47 offset:2056
	ds_read_b32 v84, v47 offset:3084
	ds_read_b32 v85, v47 offset:4112
	ds_read_b32 v86, v47 offset:5140
	ds_read_b32 v87, v47 offset:6168
	ds_read_b32 v88, v47 offset:7196
	ds_read_b32 v89, v48
	ds_read_b32 v90, v48 offset:1028
	ds_read_b32 v91, v48 offset:2056
	ds_read_b32 v92, v48 offset:3084
	ds_read_b32 v93, v48 offset:4112
	ds_read_b32 v94, v48 offset:5140
	ds_read_b32 v95, v48 offset:6168
	ds_read_b32 v96, v48 offset:7196
	s_waitcnt lgkmcnt(14)
	v_cvt_pk_bf16_f32 v66, v64, v66
	v_cvt_pk_bf16_f32 v67, v67, v68
	v_cvt_pk_bf16_f32 v68, v69, v70
	v_cvt_pk_bf16_f32 v69, v71, v72
	v_cvt_pk_bf16_f32 v70, v73, v74
	v_cvt_pk_bf16_f32 v71, v75, v76
	v_cvt_pk_bf16_f32 v72, v77, v78
	v_cvt_pk_bf16_f32 v73, v79, v80
	v_cvt_pk_bf16_f32 v74, v81, v82
	s_waitcnt lgkmcnt(12)
	v_cvt_pk_bf16_f32 v75, v83, v84
	s_waitcnt lgkmcnt(10)
	v_cvt_pk_bf16_f32 v76, v85, v86
	s_waitcnt lgkmcnt(8)
	v_cvt_pk_bf16_f32 v77, v87, v88
	s_waitcnt lgkmcnt(6)
	v_cvt_pk_bf16_f32 v78, v89, v90
	s_waitcnt lgkmcnt(4)
	v_cvt_pk_bf16_f32 v79, v91, v92
	s_waitcnt lgkmcnt(2)
	v_cvt_pk_bf16_f32 v80, v93, v94
	s_waitcnt lgkmcnt(0)
	v_cvt_pk_bf16_f32 v81, v95, v96
	global_store_dwordx4 v[102:103], v[66:69], off
	global_store_dwordx4 v[104:105], v[70:73], off
	global_store_dwordx4 v[106:107], v[74:77], off
	global_store_dwordx4 v[108:109], v[78:81], off
	s_cmp_lt_i32 s25, 32
	s_cbranch_scc1 .LBB0_391
; DI int get_tid(int wv) { int l; asm volatile("v_mbcnt_lo_u32_b32 %0, -1, 0\n\tv_mbcnt_hi_u32_b32 %0, -1, %0" : "=v"(l)); return wv * 64 + l; }
; DI void transpose_tile(WVP float* sm, const float* __restrict__ src, int lds_, u16* __restrict__ dst, int ldd, int k0, int n0) {
;   const int tid = get_tid(WV);
;   constexpr int P = 257;
;   f32x4 v[8];
;   const int rb = tid >> 6, c4 = (tid & 63) * 4;
; #pragma unroll
;   for (int i = 0; i < 8; ++i) v[i] = *(const f32x4*)(src + (long)(k0 + rb + 8 * i) * lds_ + n0 + c4);
;   __syncthreads();
; #pragma unroll
;   for (int i = 0; i < 8; ++i) for (int j = 0; j < 4; ++j) sm[(rb + 8 * i) * P + c4 + j] = v[i][j];
;     ...
;     int first = (BID - base % GRD + GRD) % GRD;
;     for (int i = first; i < cnt; i += GRD) transpose_tile(WV, sm, src[j], lds_[j], dst[j], Kd[j], (i / nn) * 64, (i % nn) * 256);
.LBB0_392:
	s_mul_hi_u32 s4, s22, 0x130
	s_mul_i32 s4, s4, s12
	s_sub_i32 s4, 0x130, s4
	s_sub_i32 s5, s4, s12
	s_cmp_ge_u32 s4, s12
	s_cselect_b32 s4, s5, s4
	s_sub_i32 s5, s4, s12
	s_cmp_ge_u32 s4, s12
	s_cselect_b32 s4, s5, s4
	s_sub_i32 s4, s13, s4
	s_ashr_i32 s5, s4, 31
	s_abs_i32 s4, s4
	s_mul_hi_u32 s25, s4, s22
	s_mul_i32 s25, s25, s12
	s_sub_i32 s4, s4, s25
	s_sub_i32 s25, s4, s12
	s_cmp_ge_u32 s4, s12
	s_cselect_b32 s4, s25, s4
	s_sub_i32 s25, s4, s12
	s_cmp_ge_u32 s4, s12
	s_cselect_b32 s4, s25, s4
	s_xor_b32 s4, s4, s5
	s_sub_i32 s25, s4, s5
	s_cmp_gt_i32 s25, 31
	s_cbranch_scc1 .LBB0_395
	s_add_u32 s0, s0, 0x500000
	s_addc_u32 s1, s1, 0
	s_add_u32 s26, s54, 0x1e580000
	s_addc_u32 s27, s55, 0
	s_lshl_b32 s28, s25, 8
	s_lshl_b32 s29, s20, 8
	s_ashr_i32 s4, s25, 31
	s_lshr_b32 s4, s4, 30
	s_add_i32 s4, s25, s4
	s_ashr_i32 s5, s4, 2
	s_lshl_b32 s4, s5, 6
	s_lshl_b32 s5, s5, 10
	v_mbcnt_lo_u32_b32 v0, -1, 0
	v_mbcnt_hi_u32_b32 v0, -1, v0
	s_sub_i32 s30, s28, s5
	v_add_u32_e32 v2, s3, v0
	v_lshlrev_b32_e32 v3, 4, v0
	v_lshlrev_b32_e32 v4, 3, v0
	v_ashrrev_i32_e32 v5, 6, v2
	v_and_b32_e32 v0, 0x3f0, v3
	v_and_b32_e32 v42, 56, v4
	v_ashrrev_i32_e32 v3, 3, v2
	v_add_u32_e32 v4, 0x200, v2
	v_add_u32_e32 v6, 0x400, v2
	v_add_u32_e32 v2, 0x600, v2
	s_ashr_i32 s31, s30, 31
	v_mul_lo_u32 v7, v5, s34
	v_mad_u32_u24 v8, v42, s34, 0
	v_ashrrev_i32_e32 v4, 3, v4
	v_ashrrev_i32_e32 v9, 3, v2
	v_add_u32_e32 v2, s4, v5
	v_subrev_u32_e32 v5, s5, v3
	s_lshl_b64 s[30:31], s[30:31], 2
	v_ashrrev_i32_e32 v6, 3, v6
	v_add3_u32 v44, 0, v0, v7
	v_lshl_add_u32 v46, v4, 2, v8
	v_subrev_u32_e32 v7, s5, v4
	v_add_u32_e32 v4, s28, v5
	s_add_u32 s30, s0, s30
	v_lshl_add_u32 v45, v3, 2, v8
	v_lshl_add_u32 v47, v6, 2, v8
	v_lshl_add_u32 v48, v9, 2, v8
	v_subrev_u32_e32 v8, s5, v6
	v_ashrrev_i32_e32 v3, 31, v2
	v_add_u32_e32 v6, s28, v7
	v_ashrrev_i32_e32 v5, 31, v4
	s_addc_u32 s31, s1, s31
	v_subrev_u32_e32 v9, s5, v9
	v_add_u32_e32 v8, s28, v8
	v_lshlrev_b64 v[2:3], 12, v[2:3]
	v_ashrrev_i32_e32 v7, 31, v6
	v_lshlrev_b64 v[34:35], 10, v[4:5]
	v_lshl_add_u64 v[4:5], s[30:31], 0, v[0:1]
	v_add_u32_e32 v10, s28, v9
	v_ashrrev_i32_e32 v9, 31, v8
	v_lshlrev_b64 v[36:37], 10, v[6:7]
	v_lshl_add_u64 v[6:7], v[4:5], 0, v[2:3]
	v_lshlrev_b64 v[38:39], 10, v[8:9]
	v_add_co_u32_e32 v8, vcc, s38, v6
	v_ashrrev_i32_e32 v11, 31, v10
	s_nop 0
	v_addc_co_u32_e32 v9, vcc, 0, v7, vcc
	v_lshlrev_b64 v[40:41], 10, v[10:11]
	v_add_co_u32_e32 v10, vcc, s36, v6
	global_load_dwordx4 v[2:5], v[6:7], off
	s_nop 0
	v_addc_co_u32_e32 v11, vcc, 0, v7, vcc
	v_add_co_u32_e32 v14, vcc, s37, v6
	s_ashr_i32 s5, s4, 31
	s_nop 0
	v_addc_co_u32_e32 v15, vcc, 0, v7, vcc
	v_add_co_u32_e32 v18, vcc, s39, v6
	s_lshl_b64 s[4:5], s[4:5], 1
	s_nop 0
	v_addc_co_u32_e32 v19, vcc, 0, v7, vcc
	v_add_co_u32_e32 v22, vcc, s40, v6
	s_add_u32 s4, s26, s4
	s_nop 0
	v_addc_co_u32_e32 v23, vcc, 0, v7, vcc
	v_add_co_u32_e32 v26, vcc, s41, v6
	v_lshlrev_b32_e32 v0, 1, v42
	s_nop 0
	v_addc_co_u32_e32 v27, vcc, 0, v7, vcc
	v_add_co_u32_e32 v30, vcc, s42, v6
	s_addc_u32 s5, s27, s5
	s_nop 0
	v_addc_co_u32_e32 v31, vcc, 0, v7, vcc
	global_load_dwordx4 v[6:9], v[8:9], off
	s_nop 0
	global_load_dwordx4 v[10:13], v[10:11], off
	s_nop 0
	global_load_dwordx4 v[14:17], v[14:15], off
	s_nop 0
	global_load_dwordx4 v[18:21], v[18:19], off
	s_nop 0
	global_load_dwordx4 v[22:25], v[22:23], off
	s_nop 0
	global_load_dwordx4 v[26:29], v[26:27], off
	s_nop 0
	global_load_dwordx4 v[30:33], v[30:31], off
	v_add_u32_e32 v49, 0x2020, v44
	v_add_u32_e32 v50, 0x2028, v44
	v_add_u32_e32 v51, 0x4040, v44
	v_add_u32_e32 v52, 0x4048, v44
	v_add_u32_e32 v53, 0x6060, v44
	v_add_u32_e32 v54, 0x6068, v44
	v_add_u32_e32 v55, 0x8080, v44
	v_add_u32_e32 v56, 0x8088, v44
	v_add_u32_e32 v57, 0xa0a0, v44
	v_add_u32_e32 v58, 0xa0a8, v44
	v_add_u32_e32 v59, 0xc0c0, v44
	v_add_u32_e32 v60, 0xc0c8, v44
	v_add_u32_e32 v61, 0xe0e0, v44
	v_add_u32_e32 v62, 0xe0e8, v44
	s_waitcnt vmcnt(0)
; DI unsigned pack2(float a, float b) { f2_t v = {a, b}; bf2_t r = __builtin_convertvector(v, bf2_t); return __builtin_bit_cast(unsigned, r); }
; DI int get_tid(int wv) { int l; asm volatile("v_mbcnt_lo_u32_b32 %0, -1, 0\n\tv_mbcnt_hi_u32_b32 %0, -1, %0" : "=v"(l)); return wv * 64 + l; }
; DI void transpose_tile(WVP float* sm, const float* __restrict__ src, int lds_, u16* __restrict__ dst, int ldd, int k0, int n0) {
;   const int tid = get_tid(WV);
;   constexpr int P = 257;
;   f32x4 v[8];
;   const int rb = tid >> 6, c4 = (tid & 63) * 4;
; #pragma unroll
;   for (int i = 0; i < 8; ++i) v[i] = *(const f32x4*)(src + (long)(k0 + rb + 8 * i) * lds_ + n0 + c4);
;   __syncthreads();
; #pragma unroll
;   for (int i = 0; i < 8; ++i) for (int j = 0; j < 4; ++j) sm[(rb + 8 * i) * P + c4 + j] = v[i][j];
;   __syncthreads();
; #pragma unroll
;   for (int i = 0; i < 4; ++i) {
;     const int c = tid + NTHR * i, n = c >> 3, k8 = (c & 7) * 8;
;     u32x4 o;
;     o[0] = pack2(sm[(k8 + 0) * P + n], sm[(k8 + 1) * P + n]); o[1] = pack2(sm[(k8 + 2) * P + n], sm[(k8 + 3) * P + n]);
;     o[2] = pack2(sm[(k8 + 4) * P + n], sm[(k8 + 5) * P + n]); o[3] = pack2(sm[(k8 + 6) * P + n], sm[(k8 + 7) * P + n]);
;     *(u32x4*)(dst + (long)(n0 + n) * ldd + k0 + k8) = o;
;   }
.LBB0_394:
	s_barrier
	v_lshl_add_u64 v[100:101], s[4:5], 0, v[0:1]
	v_lshl_add_u64 v[102:103], v[100:101], 0, v[34:35]
	v_lshl_add_u64 v[104:105], v[100:101], 0, v[36:37]
	v_lshl_add_u64 v[106:107], v[100:101], 0, v[38:39]
	v_lshl_add_u64 v[108:109], v[100:101], 0, v[40:41]
	s_waitcnt vmcnt(11)
	ds_write2_b32 v44, v2, v3 offset1:1
	ds_write2_b32 v44, v4, v5 offset0:2 offset1:3
	s_waitcnt vmcnt(10)
	ds_write2_b32 v49, v6, v7 offset1:1
	ds_write2_b32 v50, v8, v9 offset1:1
	s_waitcnt vmcnt(9)
	ds_write2_b32 v51, v10, v11 offset1:1
	ds_write2_b32 v52, v12, v13 offset1:1
	s_waitcnt vmcnt(8)
	ds_write2_b32 v53, v14, v15 offset1:1
	ds_write2_b32 v54, v16, v17 offset1:1
	s_waitcnt vmcnt(7)
	ds_write2_b32 v55, v18, v19 offset1:1
	ds_write2_b32 v56, v20, v21 offset1:1
	s_waitcnt vmcnt(6)
	ds_write2_b32 v57, v22, v23 offset1:1
	ds_write2_b32 v58, v24, v25 offset1:1
	s_waitcnt vmcnt(5)
	ds_write2_b32 v59, v26, v27 offset1:1
	ds_write2_b32 v60, v28, v29 offset1:1
	s_waitcnt vmcnt(4)
	ds_write2_b32 v61, v30, v31 offset1:1
	ds_write2_b32 v62, v32, v33 offset1:1
	s_waitcnt lgkmcnt(0)
	s_barrier
	s_add_i32 s25, s25, s20
	s_add_i32 s28, s28, s29
	s_movk_i32 s34, 0x404
	s_cmp_lt_i32 s25, 32
	s_cbranch_scc0 .Lwp_skip_394
	s_ashr_i32 s4, s25, 31
	s_lshr_b32 s4, s4, 30
	s_add_i32 s4, s25, s4
	s_ashr_i32 s5, s4, 2
	s_lshl_b32 s4, s5, 6
	s_lshl_b32 s5, s5, 10
	v_mbcnt_lo_u32_b32 v0, -1, 0
	v_mbcnt_hi_u32_b32 v0, -1, v0
	s_sub_i32 s30, s28, s5
	v_add_u32_e32 v2, s3, v0
	v_lshlrev_b32_e32 v3, 4, v0
	v_lshlrev_b32_e32 v4, 3, v0
	v_ashrrev_i32_e32 v5, 6, v2
	v_and_b32_e32 v0, 0x3f0, v3
	v_and_b32_e32 v42, 56, v4
	v_ashrrev_i32_e32 v3, 3, v2
	v_add_u32_e32 v4, 0x200, v2
	v_add_u32_e32 v6, 0x400, v2
	v_add_u32_e32 v2, 0x600, v2
	s_ashr_i32 s31, s30, 31
	v_mul_lo_u32 v7, v5, s34
	v_mad_u32_u24 v8, v42, s34, 0
	v_ashrrev_i32_e32 v4, 3, v4
	v_ashrrev_i32_e32 v9, 3, v2
	v_add_u32_e32 v2, s4, v5
	v_subrev_u32_e32 v5, s5, v3
	s_lshl_b64 s[30:31], s[30:31], 2
	v_ashrrev_i32_e32 v6, 3, v6
	v_add3_u32 v44, 0, v0, v7
	v_lshl_add_u32 v46, v4, 2, v8
	v_subrev_u32_e32 v7, s5, v4
	v_add_u32_e32 v4, s28, v5
	s_add_u32 s30, s0, s30
	v_lshl_add_u32 v45, v3, 2, v8
	v_lshl_add_u32 v47, v6, 2, v8
	v_lshl_add_u32 v48, v9, 2, v8
	v_subrev_u32_e32 v8, s5, v6
	v_ashrrev_i32_e32 v3, 31, v2
	v_add_u32_e32 v6, s28, v7
	v_ashrrev_i32_e32 v5, 31, v4
	s_addc_u32 s31, s1, s31
	v_subrev_u32_e32 v9, s5, v9
	v_add_u32_e32 v8, s28, v8
	v_lshlrev_b64 v[2:3], 12, v[2:3]
	v_ashrrev_i32_e32 v7, 31, v6
	v_lshlrev_b64 v[34:35], 10, v[4:5]
	v_lshl_add_u64 v[4:5], s[30:31], 0, v[0:1]
	v_add_u32_e32 v10, s28, v9
	v_ashrrev_i32_e32 v9, 31, v8
	v_lshlrev_b64 v[36:37], 10, v[6:7]
	v_lshl_add_u64 v[6:7], v[4:5], 0, v[2:3]
	v_lshlrev_b64 v[38:39], 10, v[8:9]
	v_add_co_u32_e32 v8, vcc, s38, v6
	v_ashrrev_i32_e32 v11, 31, v10
	s_nop 0
	v_addc_co_u32_e32 v9, vcc, 0, v7, vcc
	v_lshlrev_b64 v[40:41], 10, v[10:11]
	v_add_co_u32_e32 v10, vcc, s36, v6
	global_load_dwordx4 v[2:5], v[6:7], off
	s_nop 0
	v_addc_co_u32_e32 v11, vcc, 0, v7, vcc
	v_add_co_u32_e32 v14, vcc, s37, v6
	s_ashr_i32 s5, s4, 31
	s_nop 0
	v_addc_co_u32_e32 v15, vcc, 0, v7, vcc
	v_add_co_u32_e32 v18, vcc, s39, v6
	s_lshl_b64 s[4:5], s[4:5], 1
	s_nop 0
	v_addc_co_u32_e32 v19, vcc, 0, v7, vcc
	v_add_co_u32_e32 v22, vcc, s40, v6
	s_add_u32 s4, s26, s4
	s_nop 0
	v_addc_co_u32_e32 v23, vcc, 0, v7, vcc
	v_add_co_u32_e32 v26, vcc, s41, v6
	v_lshlrev_b32_e32 v0, 1, v42
	s_nop 0
	v_addc_co_u32_e32 v27, vcc, 0, v7, vcc
	v_add_co_u32_e32 v30, vcc, s42, v6
	s_addc_u32 s5, s27, s5
	s_nop 0
	v_addc_co_u32_e32 v31, vcc, 0, v7, vcc
	global_load_dwordx4 v[6:9], v[8:9], off
	s_nop 0
	global_load_dwordx4 v[10:13], v[10:11], off
	s_nop 0
	global_load_dwordx4 v[14:17], v[14:15], off
	s_nop 0
	global_load_dwordx4 v[18:21], v[18:19], off
	s_nop 0
	global_load_dwordx4 v[22:25], v[22:23], off
	s_nop 0
	global_load_dwordx4 v[26:29], v[26:27], off
	s_nop 0
	global_load_dwordx4 v[30:33], v[30:31], off
	v_add_u32_e32 v49, 0x2020, v44
	v_add_u32_e32 v50, 0x2028, v44
	v_add_u32_e32 v51, 0x4040, v44
	v_add_u32_e32 v52, 0x4048, v44
	v_add_u32_e32 v53, 0x6060, v44
	v_add_u32_e32 v54, 0x6068, v44
	v_add_u32_e32 v55, 0x8080, v44
	v_add_u32_e32 v56, 0x8088, v44
	v_add_u32_e32 v57, 0xa0a0, v44
	v_add_u32_e32 v58, 0xa0a8, v44
	v_add_u32_e32 v59, 0xc0c0, v44
	v_add_u32_e32 v60, 0xc0c8, v44
	v_add_u32_e32 v61, 0xe0e0, v44
	v_add_u32_e32 v62, 0xe0e8, v44

; DI int get_tid(int wv) { int l; asm volatile("v_mbcnt_lo_u32_b32 %0, -1, 0\n\tv_mbcnt_hi_u32_b32 %0, -1, %0" : "=v"(l)); return wv * 64 + l; }
; DI void transpose_tile(WVP float* sm, const float* __restrict__ src, int lds_, u16* __restrict__ dst, int ldd, int k0, int n0) {
;   const int tid = get_tid(WV);
;   constexpr int P = 257;
;   f32x4 v[8];
;   const int rb = tid >> 6, c4 = (tid & 63) * 4;
; #pragma unroll
;   for (int i = 0; i < 8; ++i) v[i] = *(const f32x4*)(src + (long)(k0 + rb + 8 * i) * lds_ + n0 + c4);
;   __syncthreads();
; #pragma unroll
;   for (int i = 0; i < 8; ++i) for (int j = 0; j < 4; ++j) sm[(rb + 8 * i) * P + c4 + j] = v[i][j];
;     ...
;     int first = (BID - base % GRD + GRD) % GRD;
;     for (int i = first; i < cnt; i += GRD) transpose_tile(WV, sm, src[j], lds_[j], dst[j], Kd[j], (i / nn) * 64, (i % nn) * 256);
.LBB0_395:
	s_mul_hi_u32 s0, s22, 0x150
	s_mul_i32 s0, s0, s12
	s_sub_i32 s0, 0x150, s0
	s_sub_i32 s1, s0, s12
	s_cmp_ge_u32 s0, s12
	s_cselect_b32 s0, s1, s0
	s_sub_i32 s1, s0, s12
	s_cmp_ge_u32 s0, s12
	s_cselect_b32 s0, s1, s0
	s_sub_i32 s0, s13, s0
	s_ashr_i32 s1, s0, 31
	s_abs_i32 s0, s0
	s_mul_hi_u32 s4, s0, s22
	s_mul_i32 s4, s4, s12
	s_sub_i32 s0, s0, s4
	s_sub_i32 s4, s0, s12
	s_cmp_ge_u32 s0, s12
	s_cselect_b32 s0, s4, s0
	s_sub_i32 s4, s0, s12
	s_cmp_ge_u32 s0, s12
	s_cselect_b32 s0, s4, s0
	s_xor_b32 s0, s0, s1
	s_sub_i32 s0, s0, s1
	s_cmp_gt_i32 s0, 63
	s_cbranch_scc1 .LBB0_398
	s_lshl_b64 s[4:5], s[46:47], 22
	s_add_u32 s1, s14, s4
	s_addc_u32 s14, s15, s5
	s_lshl_b32 s15, s0, 8
	s_lshl_b32 s25, s20, 8
	s_ashr_i32 s4, s0, 31
	s_lshr_b32 s4, s4, 30
	s_add_i32 s4, s0, s4
	s_ashr_i32 s5, s4, 2
	s_lshl_b32 s4, s5, 6
	s_lshl_b32 s5, s5, 10
	v_mbcnt_lo_u32_b32 v0, -1, 0
	v_mbcnt_hi_u32_b32 v0, -1, v0
	s_sub_i32 s26, s15, s5
	v_add_u32_e32 v2, s3, v0
	v_lshlrev_b32_e32 v3, 4, v0
	v_lshlrev_b32_e32 v4, 3, v0
	v_ashrrev_i32_e32 v5, 6, v2
	v_and_b32_e32 v0, 0x3f0, v3
	v_and_b32_e32 v42, 56, v4
	v_ashrrev_i32_e32 v3, 3, v2
	v_add_u32_e32 v4, 0x200, v2
	v_add_u32_e32 v6, 0x400, v2
	v_add_u32_e32 v2, 0x600, v2
	s_ashr_i32 s27, s26, 31
	v_mul_lo_u32 v7, v5, s34
	v_mad_u32_u24 v8, v42, s34, 0
	v_ashrrev_i32_e32 v4, 3, v4
	v_ashrrev_i32_e32 v9, 3, v2
	v_add_u32_e32 v2, s4, v5
	v_subrev_u32_e32 v5, s5, v3
	s_lshl_b64 s[26:27], s[26:27], 2
	v_ashrrev_i32_e32 v6, 3, v6
	v_add3_u32 v44, 0, v0, v7
	v_lshl_add_u32 v46, v4, 2, v8
	v_subrev_u32_e32 v7, s5, v4
	v_add_u32_e32 v4, s15, v5
	s_add_u32 s26, s1, s26
	v_lshl_add_u32 v45, v3, 2, v8
	v_lshl_add_u32 v47, v6, 2, v8
	v_lshl_add_u32 v48, v9, 2, v8
	v_subrev_u32_e32 v8, s5, v6
	v_ashrrev_i32_e32 v3, 31, v2
	v_add_u32_e32 v6, s15, v7
	v_ashrrev_i32_e32 v5, 31, v4
	s_addc_u32 s27, s14, s27
	v_subrev_u32_e32 v9, s5, v9
	v_add_u32_e32 v8, s15, v8
	v_lshlrev_b64 v[2:3], 12, v[2:3]
	v_ashrrev_i32_e32 v7, 31, v6
	v_lshlrev_b64 v[34:35], 11, v[4:5]
	v_lshl_add_u64 v[4:5], s[26:27], 0, v[0:1]
	v_add_u32_e32 v10, s15, v9
	v_ashrrev_i32_e32 v9, 31, v8
	v_lshlrev_b64 v[36:37], 11, v[6:7]
	v_lshl_add_u64 v[6:7], v[4:5], 0, v[2:3]
	v_lshlrev_b64 v[38:39], 11, v[8:9]
	v_add_co_u32_e32 v8, vcc, s38, v6
	v_ashrrev_i32_e32 v11, 31, v10
	s_nop 0
	v_addc_co_u32_e32 v9, vcc, 0, v7, vcc
	v_lshlrev_b64 v[40:41], 11, v[10:11]
	v_add_co_u32_e32 v10, vcc, s36, v6
	global_load_dwordx4 v[2:5], v[6:7], off
	s_nop 0
	v_addc_co_u32_e32 v11, vcc, 0, v7, vcc
	v_add_co_u32_e32 v14, vcc, s37, v6
	s_ashr_i32 s5, s4, 31
	s_nop 0
	v_addc_co_u32_e32 v15, vcc, 0, v7, vcc
	v_add_co_u32_e32 v18, vcc, s39, v6
	s_lshl_b64 s[4:5], s[4:5], 1
	s_nop 0
	v_addc_co_u32_e32 v19, vcc, 0, v7, vcc
	v_add_co_u32_e32 v22, vcc, s40, v6
	s_add_u32 s4, s75, s4
	s_nop 0
	v_addc_co_u32_e32 v23, vcc, 0, v7, vcc
	v_add_co_u32_e32 v26, vcc, s41, v6
	v_lshlrev_b32_e32 v0, 1, v42
	s_nop 0
	v_addc_co_u32_e32 v27, vcc, 0, v7, vcc
	v_add_co_u32_e32 v30, vcc, s42, v6
	s_addc_u32 s5, s2, s5
	s_nop 0
	v_addc_co_u32_e32 v31, vcc, 0, v7, vcc
	global_load_dwordx4 v[6:9], v[8:9], off
	s_nop 0
	global_load_dwordx4 v[10:13], v[10:11], off
	s_nop 0
	global_load_dwordx4 v[14:17], v[14:15], off
	s_nop 0
	global_load_dwordx4 v[18:21], v[18:19], off
	s_nop 0
	global_load_dwordx4 v[22:25], v[22:23], off
	s_nop 0
	global_load_dwordx4 v[26:29], v[26:27], off
	s_nop 0
	global_load_dwordx4 v[30:33], v[30:31], off
	v_add_u32_e32 v49, 0x2020, v44
	v_add_u32_e32 v50, 0x2028, v44
	v_add_u32_e32 v51, 0x4040, v44
	v_add_u32_e32 v52, 0x4048, v44
	v_add_u32_e32 v53, 0x6060, v44
	v_add_u32_e32 v54, 0x6068, v44
	v_add_u32_e32 v55, 0x8080, v44
	v_add_u32_e32 v56, 0x8088, v44
	v_add_u32_e32 v57, 0xa0a0, v44
	v_add_u32_e32 v58, 0xa0a8, v44
	v_add_u32_e32 v59, 0xc0c0, v44
	v_add_u32_e32 v60, 0xc0c8, v44
	v_add_u32_e32 v61, 0xe0e0, v44
	v_add_u32_e32 v62, 0xe0e8, v44
	s_waitcnt vmcnt(0)
; DI unsigned pack2(float a, float b) { f2_t v = {a, b}; bf2_t r = __builtin_convertvector(v, bf2_t); return __builtin_bit_cast(unsigned, r); }
; DI int get_tid(int wv) { int l; asm volatile("v_mbcnt_lo_u32_b32 %0, -1, 0\n\tv_mbcnt_hi_u32_b32 %0, -1, %0" : "=v"(l)); return wv * 64 + l; }
; DI void transpose_tile(WVP float* sm, const float* __restrict__ src, int lds_, u16* __restrict__ dst, int ldd, int k0, int n0) {
;   const int tid = get_tid(WV);
;   constexpr int P = 257;
;   f32x4 v[8];
;   const int rb = tid >> 6, c4 = (tid & 63) * 4;
; #pragma unroll
;   for (int i = 0; i < 8; ++i) v[i] = *(const f32x4*)(src + (long)(k0 + rb + 8 * i) * lds_ + n0 + c4);
;   __syncthreads();
; #pragma unroll
;   for (int i = 0; i < 8; ++i) for (int j = 0; j < 4; ++j) sm[(rb + 8 * i) * P + c4 + j] = v[i][j];
;   __syncthreads();
; #pragma unroll
;   for (int i = 0; i < 4; ++i) {
;     const int c = tid + NTHR * i, n = c >> 3, k8 = (c & 7) * 8;
;     u32x4 o;
;     o[0] = pack2(sm[(k8 + 0) * P + n], sm[(k8 + 1) * P + n]); o[1] = pack2(sm[(k8 + 2) * P + n], sm[(k8 + 3) * P + n]);
;     o[2] = pack2(sm[(k8 + 4) * P + n], sm[(k8 + 5) * P + n]); o[3] = pack2(sm[(k8 + 6) * P + n], sm[(k8 + 7) * P + n]);
;     *(u32x4*)(dst + (long)(n0 + n) * ldd + k0 + k8) = o;
;   }
.LBB0_397:
	s_barrier
	v_lshl_add_u64 v[100:101], s[4:5], 0, v[0:1]
	v_lshl_add_u64 v[102:103], v[100:101], 0, v[34:35]
	v_lshl_add_u64 v[104:105], v[100:101], 0, v[36:37]
	v_lshl_add_u64 v[106:107], v[100:101], 0, v[38:39]
	v_lshl_add_u64 v[108:109], v[100:101], 0, v[40:41]
	s_waitcnt vmcnt(11)
	ds_write2_b32 v44, v2, v3 offset1:1
	ds_write2_b32 v44, v4, v5 offset0:2 offset1:3
	s_waitcnt vmcnt(10)
	ds_write2_b32 v49, v6, v7 offset1:1
	ds_write2_b32 v50, v8, v9 offset1:1
	s_waitcnt vmcnt(9)
	ds_write2_b32 v51, v10, v11 offset1:1
	ds_write2_b32 v52, v12, v13 offset1:1
	s_waitcnt vmcnt(8)
	ds_write2_b32 v53, v14, v15 offset1:1
	ds_write2_b32 v54, v16, v17 offset1:1
	s_waitcnt vmcnt(7)
	ds_write2_b32 v55, v18, v19 offset1:1
	ds_write2_b32 v56, v20, v21 offset1:1
	s_waitcnt vmcnt(6)
	ds_write2_b32 v57, v22, v23 offset1:1
	ds_write2_b32 v58, v24, v25 offset1:1
	s_waitcnt vmcnt(5)
	ds_write2_b32 v59, v26, v27 offset1:1
	ds_write2_b32 v60, v28, v29 offset1:1
	s_waitcnt vmcnt(4)
	ds_write2_b32 v61, v30, v31 offset1:1
	ds_write2_b32 v62, v32, v33 offset1:1
	s_waitcnt lgkmcnt(0)
	s_barrier
	s_add_i32 s0, s0, s20
	s_add_i32 s15, s15, s25
	s_movk_i32 s34, 0x404
	s_cmp_lt_i32 s0, 64
	s_cbranch_scc0 .Lwp_skip_397
	s_ashr_i32 s4, s0, 31
	s_lshr_b32 s4, s4, 30
	s_add_i32 s4, s0, s4
	s_ashr_i32 s5, s4, 2
	s_lshl_b32 s4, s5, 6
	s_lshl_b32 s5, s5, 10
	v_mbcnt_lo_u32_b32 v0, -1, 0
	v_mbcnt_hi_u32_b32 v0, -1, v0
	s_sub_i32 s26, s15, s5
	v_add_u32_e32 v2, s3, v0
	v_lshlrev_b32_e32 v3, 4, v0
	v_lshlrev_b32_e32 v4, 3, v0
	v_ashrrev_i32_e32 v5, 6, v2
	v_and_b32_e32 v0, 0x3f0, v3
	v_and_b32_e32 v42, 56, v4
	v_ashrrev_i32_e32 v3, 3, v2
	v_add_u32_e32 v4, 0x200, v2
	v_add_u32_e32 v6, 0x400, v2
	v_add_u32_e32 v2, 0x600, v2
	s_ashr_i32 s27, s26, 31
	v_mul_lo_u32 v7, v5, s34
	v_mad_u32_u24 v8, v42, s34, 0
	v_ashrrev_i32_e32 v4, 3, v4
	v_ashrrev_i32_e32 v9, 3, v2
	v_add_u32_e32 v2, s4, v5
	v_subrev_u32_e32 v5, s5, v3
	s_lshl_b64 s[26:27], s[26:27], 2
	v_ashrrev_i32_e32 v6, 3, v6
	v_add3_u32 v44, 0, v0, v7
	v_lshl_add_u32 v46, v4, 2, v8
	v_subrev_u32_e32 v7, s5, v4
	v_add_u32_e32 v4, s15, v5
	s_add_u32 s26, s1, s26
	v_lshl_add_u32 v45, v3, 2, v8
	v_lshl_add_u32 v47, v6, 2, v8
	v_lshl_add_u32 v48, v9, 2, v8
	v_subrev_u32_e32 v8, s5, v6
	v_ashrrev_i32_e32 v3, 31, v2
	v_add_u32_e32 v6, s15, v7
	v_ashrrev_i32_e32 v5, 31, v4
	s_addc_u32 s27, s14, s27
	v_subrev_u32_e32 v9, s5, v9
	v_add_u32_e32 v8, s15, v8
	v_lshlrev_b64 v[2:3], 12, v[2:3]
	v_ashrrev_i32_e32 v7, 31, v6
	v_lshlrev_b64 v[34:35], 11, v[4:5]
	v_lshl_add_u64 v[4:5], s[26:27], 0, v[0:1]
	v_add_u32_e32 v10, s15, v9
	v_ashrrev_i32_e32 v9, 31, v8
	v_lshlrev_b64 v[36:37], 11, v[6:7]
	v_lshl_add_u64 v[6:7], v[4:5], 0, v[2:3]
	v_lshlrev_b64 v[38:39], 11, v[8:9]
	v_add_co_u32_e32 v8, vcc, s38, v6
	v_ashrrev_i32_e32 v11, 31, v10
	s_nop 0
	v_addc_co_u32_e32 v9, vcc, 0, v7, vcc
	v_lshlrev_b64 v[40:41], 11, v[10:11]
	v_add_co_u32_e32 v10, vcc, s36, v6
	global_load_dwordx4 v[2:5], v[6:7], off
	s_nop 0
	v_addc_co_u32_e32 v11, vcc, 0, v7, vcc
	v_add_co_u32_e32 v14, vcc, s37, v6
	s_ashr_i32 s5, s4, 31
	s_nop 0
	v_addc_co_u32_e32 v15, vcc, 0, v7, vcc
	v_add_co_u32_e32 v18, vcc, s39, v6
	s_lshl_b64 s[4:5], s[4:5], 1
	s_nop 0
	v_addc_co_u32_e32 v19, vcc, 0, v7, vcc
	v_add_co_u32_e32 v22, vcc, s40, v6
	s_add_u32 s4, s75, s4
	s_nop 0
	v_addc_co_u32_e32 v23, vcc, 0, v7, vcc
	v_add_co_u32_e32 v26, vcc, s41, v6
	v_lshlrev_b32_e32 v0, 1, v42
	s_nop 0
	v_addc_co_u32_e32 v27, vcc, 0, v7, vcc
	v_add_co_u32_e32 v30, vcc, s42, v6
	s_addc_u32 s5, s2, s5
	s_nop 0
	v_addc_co_u32_e32 v31, vcc, 0, v7, vcc
	global_load_dwordx4 v[6:9], v[8:9], off
	s_nop 0
	global_load_dwordx4 v[10:13], v[10:11], off
	s_nop 0
	global_load_dwordx4 v[14:17], v[14:15], off
	s_nop 0
	global_load_dwordx4 v[18:21], v[18:19], off
	s_nop 0
	global_load_dwordx4 v[22:25], v[22:23], off
	s_nop 0
	global_load_dwordx4 v[26:29], v[26:27], off
	s_nop 0
	global_load_dwordx4 v[30:33], v[30:31], off
	v_add_u32_e32 v49, 0x2020, v44
	v_add_u32_e32 v50, 0x2028, v44
	v_add_u32_e32 v51, 0x4040, v44
	v_add_u32_e32 v52, 0x4048, v44
	v_add_u32_e32 v53, 0x6060, v44
	v_add_u32_e32 v54, 0x6068, v44
	v_add_u32_e32 v55, 0x8080, v44
	v_add_u32_e32 v56, 0x8088, v44
	v_add_u32_e32 v57, 0xa0a0, v44
	v_add_u32_e32 v58, 0xa0a8, v44
	v_add_u32_e32 v59, 0xc0c0, v44
	v_add_u32_e32 v60, 0xc0c8, v44
	v_add_u32_e32 v61, 0xe0e0, v44
	v_add_u32_e32 v62, 0xe0e8, v44

; DI int get_tid(int wv) { int l; asm volatile("v_mbcnt_lo_u32_b32 %0, -1, 0\n\tv_mbcnt_hi_u32_b32 %0, -1, %0" : "=v"(l)); return wv * 64 + l; }
; DI void transpose_tile(WVP float* sm, const float* __restrict__ src, int lds_, u16* __restrict__ dst, int ldd, int k0, int n0) {
;   const int tid = get_tid(WV);
;   constexpr int P = 257;
;   f32x4 v[8];
;   const int rb = tid >> 6, c4 = (tid & 63) * 4;
; #pragma unroll
;   for (int i = 0; i < 8; ++i) v[i] = *(const f32x4*)(src + (long)(k0 + rb + 8 * i) * lds_ + n0 + c4);
;   __syncthreads();
; #pragma unroll
;   for (int i = 0; i < 8; ++i) for (int j = 0; j < 4; ++j) sm[(rb + 8 * i) * P + c4 + j] = v[i][j];
;   __syncthreads();
;     ...
;     int first = (BID - base % GRD + GRD) % GRD;
;     for (int i = first; i < cnt; i += GRD) transpose_tile(WV, sm, src[j], lds_[j], dst[j], Kd[j], (i / nn) * 64, (i % nn) * 256);
.LBB0_398:
	s_mul_hi_u32 s0, s22, 0x190
	s_mul_i32 s0, s0, s12
	s_sub_i32 s0, 0x190, s0
	s_sub_i32 s1, s0, s12
	s_cmp_ge_u32 s0, s12
	s_cselect_b32 s0, s1, s0
	s_sub_i32 s1, s0, s12
	s_cmp_ge_u32 s0, s12
	s_cselect_b32 s0, s1, s0
	s_sub_i32 s0, s13, s0
	s_ashr_i32 s1, s0, 31
	s_abs_i32 s0, s0
	s_mul_hi_u32 s4, s0, s22
	s_mul_i32 s4, s4, s12
	s_sub_i32 s0, s0, s4
	s_sub_i32 s4, s0, s12
	s_cmp_ge_u32 s0, s12
	s_cselect_b32 s0, s4, s0
	s_sub_i32 s4, s0, s12
	s_cmp_ge_u32 s0, s12
	s_cselect_b32 s0, s4, s0
	s_xor_b32 s0, s0, s1
	s_sub_i32 s0, s0, s1
	s_cmpk_gt_i32 s0, 0x15f
	s_cbranch_scc1 .LBB0_401
	s_mul_i32 s1, s46, 0x1600000
	s_mul_hi_i32 s4, s46, 0x1600000
	s_add_u32 s1, s16, s1
	s_addc_u32 s4, s17, s4
	s_lshl_b32 s5, s0, 8
	s_lshl_b32 s14, s20, 8
	s_movk_i32 s25, 0x5800
	v_readlane_b32 s28, v255, 38
	v_readlane_b32 s29, v255, 39
	s_mul_hi_i32 s15, s0, 0x2e8ba2e9
	s_lshr_b32 s16, s15, 31
	s_ashr_i32 s15, s15, 2
	s_add_i32 s15, s15, s16
	v_mbcnt_lo_u32_b32 v0, -1, 0
	v_mbcnt_hi_u32_b32 v0, -1, v0
	s_mul_i32 s17, s15, 0xffffea00
	v_lshlrev_b32_e32 v4, 3, v0
	v_add_u32_e32 v2, s3, v0
	v_lshlrev_b32_e32 v3, 4, v0
	v_and_b32_e32 v42, 56, v4
	s_add_i32 s26, s5, s17
	v_ashrrev_i32_e32 v5, 6, v2
	v_and_b32_e32 v0, 0x3f0, v3
	v_ashrrev_i32_e32 v3, 3, v2
	v_add_u32_e32 v4, 0x200, v2
	v_add_u32_e32 v6, 0x400, v2
	v_add_u32_e32 v2, 0x600, v2
	s_lshl_b32 s16, s15, 6
	v_mad_u32_u24 v8, v42, s34, 0
	s_mulk_i32 s15, 0x1600
	s_ashr_i32 s27, s26, 31
	v_mul_lo_u32 v7, v5, s34
	v_ashrrev_i32_e32 v4, 3, v4
	v_ashrrev_i32_e32 v6, 3, v6
	v_ashrrev_i32_e32 v2, 3, v2
	v_lshl_add_u32 v45, v3, 2, v8
	v_subrev_u32_e32 v3, s15, v3
	s_lshl_b64 s[26:27], s[26:27], 2
	v_add_u32_e32 v10, s16, v5
	v_add3_u32 v44, 0, v0, v7
	v_lshl_add_u32 v46, v4, 2, v8
	v_subrev_u32_e32 v4, s15, v4
	v_subrev_u32_e32 v5, s15, v6
	v_lshl_add_u32 v48, v2, 2, v8
	v_subrev_u32_e32 v7, s15, v2
	v_add_u32_e32 v2, s5, v3
	s_add_u32 s26, s1, s26
	v_lshl_add_u32 v47, v6, 2, v8
	v_add_u32_e32 v4, s5, v4
	v_add_u32_e32 v6, s5, v5
	v_ashrrev_i32_e32 v3, 31, v2
	s_addc_u32 s27, s4, s27
	v_add_u32_e32 v11, 8, v10
	v_add_u32_e32 v12, 16, v10
	v_add_u32_e32 v13, 24, v10
	v_add_u32_e32 v16, 32, v10
	v_add_u32_e32 v17, 40, v10
	v_add_u32_e32 v20, 48, v10
	v_add_u32_e32 v21, 56, v10
	v_add_u32_e32 v8, s5, v7
	v_ashrrev_i32_e32 v5, 31, v4
	v_ashrrev_i32_e32 v7, 31, v6
	v_lshlrev_b64 v[34:35], 11, v[2:3]
	v_lshl_add_u64 v[2:3], s[26:27], 0, v[0:1]
	v_ashrrev_i32_e32 v9, 31, v8
	v_lshlrev_b64 v[36:37], 11, v[4:5]
	v_lshlrev_b64 v[38:39], 11, v[6:7]
	v_mad_i64_i32 v[4:5], s[26:27], v10, s25, v[2:3]
	v_mad_i64_i32 v[6:7], s[26:27], v11, s25, v[2:3]
	v_mad_i64_i32 v[10:11], s[26:27], v12, s25, v[2:3]
	v_mad_i64_i32 v[14:15], s[26:27], v13, s25, v[2:3]
	v_mad_i64_i32 v[18:19], s[26:27], v16, s25, v[2:3]
	v_mad_i64_i32 v[22:23], s[26:27], v17, s25, v[2:3]
	v_mad_i64_i32 v[26:27], s[26:27], v20, s25, v[2:3]
	v_mad_i64_i32 v[30:31], s[26:27], v21, s25, v[2:3]
	v_lshlrev_b64 v[40:41], 11, v[8:9]
	global_load_dwordx4 v[2:5], v[4:5], off
	s_nop 0
	global_load_dwordx4 v[6:9], v[6:7], off
	s_nop 0
	global_load_dwordx4 v[10:13], v[10:11], off
	s_nop 0
	global_load_dwordx4 v[14:17], v[14:15], off
	s_nop 0
	global_load_dwordx4 v[18:21], v[18:19], off
	s_nop 0
	global_load_dwordx4 v[22:25], v[22:23], off
	s_nop 0
	global_load_dwordx4 v[26:29], v[26:27], off
	s_nop 0
	global_load_dwordx4 v[30:33], v[30:31], off
	s_ashr_i32 s17, s16, 31
	s_lshl_b64 s[16:17], s[16:17], 1
	s_add_u32 s16, s28, s16
	v_lshlrev_b32_e32 v0, 1, v42
	s_addc_u32 s17, s29, s17
	v_add_u32_e32 v49, 0x2020, v44
	v_add_u32_e32 v50, 0x2028, v44
	v_add_u32_e32 v51, 0x4040, v44
	v_add_u32_e32 v52, 0x4048, v44
	v_add_u32_e32 v53, 0x6060, v44
	v_add_u32_e32 v54, 0x6068, v44
	v_add_u32_e32 v55, 0x8080, v44
	v_add_u32_e32 v56, 0x8088, v44
	v_add_u32_e32 v57, 0xa0a0, v44
	v_add_u32_e32 v58, 0xa0a8, v44
	v_add_u32_e32 v59, 0xc0c0, v44
	v_add_u32_e32 v60, 0xc0c8, v44
	v_add_u32_e32 v61, 0xe0e0, v44
	v_add_u32_e32 v62, 0xe0e8, v44
	s_waitcnt vmcnt(0)
.LBB0_400:
	s_barrier
	v_lshl_add_u64 v[100:101], s[16:17], 0, v[0:1]
	v_lshl_add_u64 v[102:103], v[100:101], 0, v[34:35]
	v_lshl_add_u64 v[104:105], v[100:101], 0, v[36:37]
	v_lshl_add_u64 v[106:107], v[100:101], 0, v[38:39]
	v_lshl_add_u64 v[108:109], v[100:101], 0, v[40:41]
	s_waitcnt vmcnt(11)
	ds_write2_b32 v44, v2, v3 offset1:1
	ds_write2_b32 v44, v4, v5 offset0:2 offset1:3
	s_waitcnt vmcnt(10)
	ds_write2_b32 v49, v6, v7 offset1:1
	ds_write2_b32 v50, v8, v9 offset1:1
	s_waitcnt vmcnt(9)
	ds_write2_b32 v51, v10, v11 offset1:1
	ds_write2_b32 v52, v12, v13 offset1:1
	s_waitcnt vmcnt(8)
	ds_write2_b32 v53, v14, v15 offset1:1
	ds_write2_b32 v54, v16, v17 offset1:1
	s_waitcnt vmcnt(7)
	ds_write2_b32 v55, v18, v19 offset1:1
	ds_write2_b32 v56, v20, v21 offset1:1
	s_waitcnt vmcnt(6)
	ds_write2_b32 v57, v22, v23 offset1:1
	ds_write2_b32 v58, v24, v25 offset1:1
	s_waitcnt vmcnt(5)
	ds_write2_b32 v59, v26, v27 offset1:1
	ds_write2_b32 v60, v28, v29 offset1:1
	s_waitcnt vmcnt(4)
	ds_write2_b32 v61, v30, v31 offset1:1
	ds_write2_b32 v62, v32, v33 offset1:1
	s_waitcnt lgkmcnt(0)
	s_barrier
	s_add_i32 s0, s0, s20
	s_add_i32 s5, s5, s14
	s_cmpk_lt_i32 s0, 0x160
	s_cbranch_scc0 .Lwp_skip_400
; DI unsigned pack2(float a, float b) { f2_t v = {a, b}; bf2_t r = __builtin_convertvector(v, bf2_t); return __builtin_bit_cast(unsigned, r); }
; DI int get_tid(int wv) { int l; asm volatile("v_mbcnt_lo_u32_b32 %0, -1, 0\n\tv_mbcnt_hi_u32_b32 %0, -1, %0" : "=v"(l)); return wv * 64 + l; }
; DI void transpose_tile(WVP float* sm, const float* __restrict__ src, int lds_, u16* __restrict__ dst, int ldd, int k0, int n0) {
;   const int tid = get_tid(WV);
;   constexpr int P = 257;
;   f32x4 v[8];
;   const int rb = tid >> 6, c4 = (tid & 63) * 4;
; #pragma unroll
;   for (int i = 0; i < 8; ++i) v[i] = *(const f32x4*)(src + (long)(k0 + rb + 8 * i) * lds_ + n0 + c4);
;   __syncthreads();
; #pragma unroll
;   for (int i = 0; i < 8; ++i) for (int j = 0; j < 4; ++j) sm[(rb + 8 * i) * P + c4 + j] = v[i][j];
;   __syncthreads();
; #pragma unroll
;   for (int i = 0; i < 4; ++i) {
;     const int c = tid + NTHR * i, n = c >> 3, k8 = (c & 7) * 8;
;     u32x4 o;
;     o[0] = pack2(sm[(k8 + 0) * P + n], sm[(k8 + 1) * P + n]); o[1] = pack2(sm[(k8 + 2) * P + n], sm[(k8 + 3) * P + n]);
;     o[2] = pack2(sm[(k8 + 4) * P + n], sm[(k8 + 5) * P + n]); o[3] = pack2(sm[(k8 + 6) * P + n], sm[(k8 + 7) * P + n]);
;     *(u32x4*)(dst + (long)(n0 + n) * ldd + k0 + k8) = o;
;   }
	s_mul_hi_i32 s15, s0, 0x2e8ba2e9
	s_lshr_b32 s16, s15, 31
	s_ashr_i32 s15, s15, 2
	s_add_i32 s15, s15, s16
	v_mbcnt_lo_u32_b32 v0, -1, 0
	v_mbcnt_hi_u32_b32 v0, -1, v0
	s_mul_i32 s17, s15, 0xffffea00
	v_lshlrev_b32_e32 v4, 3, v0
	v_add_u32_e32 v2, s3, v0
	v_lshlrev_b32_e32 v3, 4, v0
	v_and_b32_e32 v42, 56, v4
	s_add_i32 s26, s5, s17
	v_ashrrev_i32_e32 v5, 6, v2
	v_and_b32_e32 v0, 0x3f0, v3
	v_ashrrev_i32_e32 v3, 3, v2
	v_add_u32_e32 v4, 0x200, v2
	v_add_u32_e32 v6, 0x400, v2
	v_add_u32_e32 v2, 0x600, v2
	s_lshl_b32 s16, s15, 6
	v_mad_u32_u24 v8, v42, s34, 0
	s_mulk_i32 s15, 0x1600
	s_ashr_i32 s27, s26, 31
	v_mul_lo_u32 v7, v5, s34
	v_ashrrev_i32_e32 v4, 3, v4
	v_ashrrev_i32_e32 v6, 3, v6
	v_ashrrev_i32_e32 v2, 3, v2
	v_lshl_add_u32 v45, v3, 2, v8
	v_subrev_u32_e32 v3, s15, v3
	s_lshl_b64 s[26:27], s[26:27], 2
	v_add_u32_e32 v10, s16, v5
	v_add3_u32 v44, 0, v0, v7
	v_lshl_add_u32 v46, v4, 2, v8
	v_subrev_u32_e32 v4, s15, v4
	v_subrev_u32_e32 v5, s15, v6
	v_lshl_add_u32 v48, v2, 2, v8
	v_subrev_u32_e32 v7, s15, v2
	v_add_u32_e32 v2, s5, v3
	s_add_u32 s26, s1, s26
	v_lshl_add_u32 v47, v6, 2, v8
	v_add_u32_e32 v4, s5, v4
	v_add_u32_e32 v6, s5, v5
	v_ashrrev_i32_e32 v3, 31, v2
	s_addc_u32 s27, s4, s27
	v_add_u32_e32 v11, 8, v10
	v_add_u32_e32 v12, 16, v10
	v_add_u32_e32 v13, 24, v10
	v_add_u32_e32 v16, 32, v10
	v_add_u32_e32 v17, 40, v10
	v_add_u32_e32 v20, 48, v10
	v_add_u32_e32 v21, 56, v10
	v_add_u32_e32 v8, s5, v7
	v_ashrrev_i32_e32 v5, 31, v4
	v_ashrrev_i32_e32 v7, 31, v6
	v_lshlrev_b64 v[34:35], 11, v[2:3]
	v_lshl_add_u64 v[2:3], s[26:27], 0, v[0:1]
	v_ashrrev_i32_e32 v9, 31, v8
	v_lshlrev_b64 v[36:37], 11, v[4:5]
	v_lshlrev_b64 v[38:39], 11, v[6:7]
	v_mad_i64_i32 v[4:5], s[26:27], v10, s25, v[2:3]
	v_mad_i64_i32 v[6:7], s[26:27], v11, s25, v[2:3]
	v_mad_i64_i32 v[10:11], s[26:27], v12, s25, v[2:3]
	v_mad_i64_i32 v[14:15], s[26:27], v13, s25, v[2:3]
	v_mad_i64_i32 v[18:19], s[26:27], v16, s25, v[2:3]
	v_mad_i64_i32 v[22:23], s[26:27], v17, s25, v[2:3]
	v_mad_i64_i32 v[26:27], s[26:27], v20, s25, v[2:3]
	v_mad_i64_i32 v[30:31], s[26:27], v21, s25, v[2:3]
	v_lshlrev_b64 v[40:41], 11, v[8:9]
	global_load_dwordx4 v[2:5], v[4:5], off
	s_nop 0
	global_load_dwordx4 v[6:9], v[6:7], off
	s_nop 0
	global_load_dwordx4 v[10:13], v[10:11], off
	s_nop 0
	global_load_dwordx4 v[14:17], v[14:15], off
	s_nop 0
	global_load_dwordx4 v[18:21], v[18:19], off
	s_nop 0
	global_load_dwordx4 v[22:25], v[22:23], off
	s_nop 0
	global_load_dwordx4 v[26:29], v[26:27], off
	s_nop 0
	global_load_dwordx4 v[30:33], v[30:31], off
	s_ashr_i32 s17, s16, 31
	s_lshl_b64 s[16:17], s[16:17], 1
	s_add_u32 s16, s28, s16
	v_lshlrev_b32_e32 v0, 1, v42
	s_addc_u32 s17, s29, s17
	v_add_u32_e32 v49, 0x2020, v44
	v_add_u32_e32 v50, 0x2028, v44
	v_add_u32_e32 v51, 0x4040, v44
	v_add_u32_e32 v52, 0x4048, v44
	v_add_u32_e32 v53, 0x6060, v44
	v_add_u32_e32 v54, 0x6068, v44
	v_add_u32_e32 v55, 0x8080, v44
	v_add_u32_e32 v56, 0x8088, v44
	v_add_u32_e32 v57, 0xa0a0, v44
	v_add_u32_e32 v58, 0xa0a8, v44
	v_add_u32_e32 v59, 0xc0c0, v44
	v_add_u32_e32 v60, 0xc0c8, v44
	v_add_u32_e32 v61, 0xe0e0, v44
	v_add_u32_e32 v62, 0xe0e8, v44
.Lwp_skip_400:
	ds_read_b32 v64, v45
	ds_read_b32 v66, v45 offset:1028
	ds_read_b32 v67, v45 offset:2056
	ds_read_b32 v68, v45 offset:3084
	ds_read_b32 v69, v45 offset:4112
	ds_read_b32 v70, v45 offset:5140
	ds_read_b32 v71, v45 offset:6168
	ds_read_b32 v72, v45 offset:7196
	ds_read_b32 v73, v46
	ds_read_b32 v74, v46 offset:1028
	ds_read_b32 v75, v46 offset:2056
	ds_read_b32 v76, v46 offset:3084
	ds_read_b32 v77, v46 offset:4112
	ds_read_b32 v78, v46 offset:5140
	ds_read_b32 v79, v46 offset:6168
	ds_read_b32 v80, v46 offset:7196
	ds_read_b32 v81, v47
	ds_read_b32 v82, v47 offset:1028
	ds_read_b32 v83, v47 offset:2056
	ds_read_b32 v84, v47 offset:3084
	ds_read_b32 v85, v47 offset:4112
	ds_read_b32 v86, v47 offset:5140
	ds_read_b32 v87, v47 offset:6168
	ds_read_b32 v88, v47 offset:7196
	ds_read_b32 v89, v48
	ds_read_b32 v90, v48 offset:1028
	ds_read_b32 v91, v48 offset:2056
	ds_read_b32 v92, v48 offset:3084
	ds_read_b32 v93, v48 offset:4112
	ds_read_b32 v94, v48 offset:5140
	ds_read_b32 v95, v48 offset:6168
	ds_read_b32 v96, v48 offset:7196
	s_waitcnt lgkmcnt(14)
	v_cvt_pk_bf16_f32 v66, v64, v66
	v_cvt_pk_bf16_f32 v67, v67, v68
	v_cvt_pk_bf16_f32 v68, v69, v70
	v_cvt_pk_bf16_f32 v69, v71, v72
	v_cvt_pk_bf16_f32 v70, v73, v74
	v_cvt_pk_bf16_f32 v71, v75, v76
	v_cvt_pk_bf16_f32 v72, v77, v78
	v_cvt_pk_bf16_f32 v73, v79, v80
	v_cvt_pk_bf16_f32 v74, v81, v82
	s_waitcnt lgkmcnt(12)
	v_cvt_pk_bf16_f32 v75, v83, v84
	s_waitcnt lgkmcnt(10)
	v_cvt_pk_bf16_f32 v76, v85, v86
	s_waitcnt lgkmcnt(8)
	v_cvt_pk_bf16_f32 v77, v87, v88
	s_waitcnt lgkmcnt(6)
	v_cvt_pk_bf16_f32 v78, v89, v90
	s_waitcnt lgkmcnt(4)
	v_cvt_pk_bf16_f32 v79, v91, v92
	s_waitcnt lgkmcnt(2)
	v_cvt_pk_bf16_f32 v80, v93, v94
	s_waitcnt lgkmcnt(0)
	v_cvt_pk_bf16_f32 v81, v95, v96
	global_store_dwordx4 v[102:103], v[66:69], off
	global_store_dwordx4 v[104:105], v[70:73], off
	global_store_dwordx4 v[106:107], v[74:77], off
	global_store_dwordx4 v[108:109], v[78:81], off
	s_cmpk_lt_i32 s0, 0x160
	s_cbranch_scc1 .LBB0_400
; DI int get_tid(int wv) { int l; asm volatile("v_mbcnt_lo_u32_b32 %0, -1, 0\n\tv_mbcnt_hi_u32_b32 %0, -1, %0" : "=v"(l)); return wv * 64 + l; }
; DI void transpose_tile(WVP float* sm, const float* __restrict__ src, int lds_, u16* __restrict__ dst, int ldd, int k0, int n0) {
;   const int tid = get_tid(WV);
;   constexpr int P = 257;
;   f32x4 v[8];
;   const int rb = tid >> 6, c4 = (tid & 63) * 4;
; #pragma unroll
;   for (int i = 0; i < 8; ++i) v[i] = *(const f32x4*)(src + (long)(k0 + rb + 8 * i) * lds_ + n0 + c4);
;   __syncthreads();
; #pragma unroll
;   for (int i = 0; i < 8; ++i) for (int j = 0; j < 4; ++j) sm[(rb + 8 * i) * P + c4 + j] = v[i][j];
;   __syncthreads();
;     ...
;     int first = (BID - base % GRD + GRD) % GRD;
;     for (int i = first; i < cnt; i += GRD) transpose_tile(WV, sm, src[j], lds_[j], dst[j], Kd[j], (i / nn) * 64, (i % nn) * 256);
.LBB0_401:
	s_mul_hi_u32 s0, s22, 0x2f0
	s_mul_i32 s0, s0, s12
	s_sub_i32 s0, 0x2f0, s0
	s_sub_i32 s1, s0, s12
	s_cmp_ge_u32 s0, s12
	s_cselect_b32 s0, s1, s0
	s_sub_i32 s1, s0, s12
	s_cmp_ge_u32 s0, s12
	s_cselect_b32 s0, s1, s0
	s_sub_i32 s0, s13, s0
	s_ashr_i32 s1, s0, 31
	s_abs_i32 s0, s0
	s_mul_hi_u32 s4, s0, s22
	s_mul_i32 s4, s4, s12
	s_sub_i32 s0, s0, s4
	s_sub_i32 s4, s0, s12
	s_cmp_ge_u32 s0, s12
	s_cselect_b32 s0, s4, s0
	s_sub_i32 s4, s0, s12
	s_cmp_ge_u32 s0, s12
	s_cselect_b32 s0, s4, s0
	s_xor_b32 s0, s0, s1
	s_sub_i32 s0, s0, s1
	s_cmpk_gt_i32 s0, 0xaf
	s_cbranch_scc1 .LBB0_404
	s_mul_i32 s1, s46, 0xb00000
	s_mul_hi_i32 s4, s46, 0xb00000
	s_add_u32 s1, s18, s1
	s_addc_u32 s4, s19, s4
	s_lshl_b32 s5, s0, 8
	s_lshl_b32 s14, s20, 8
	s_movk_i32 s25, 0x1600
	s_ashr_i32 s15, s0, 31
	s_lshr_b32 s15, s15, 30
	s_add_i32 s15, s0, s15
	s_ashr_i32 s15, s15, 2
	s_lshl_b32 s16, s15, 6
	s_lshl_b32 s15, s15, 10
	s_sub_i32 s18, s5, s15
	v_mbcnt_lo_u32_b32 v0, -1, 0
	v_mbcnt_hi_u32_b32 v0, -1, v0
	s_ashr_i32 s19, s18, 31
	v_add_u32_e32 v2, s3, v0
	v_lshlrev_b32_e32 v3, 4, v0
	v_lshlrev_b32_e32 v4, 3, v0
	v_ashrrev_i32_e32 v5, 6, v2
	v_and_b32_e32 v0, 0x3f0, v3
	v_and_b32_e32 v6, 56, v4
	v_ashrrev_i32_e32 v3, 3, v2
	v_add_u32_e32 v4, 0x200, v2
	v_add_u32_e32 v7, 0x400, v2
	v_add_u32_e32 v2, 0x600, v2
	s_lshl_b64 s[18:19], s[18:19], 2
	v_mad_u32_u24 v9, v6, s34, 0
	v_ashrrev_i32_e32 v4, 3, v4
	v_ashrrev_i32_e32 v10, 3, v2
	v_add_u32_e32 v2, s16, v5
	s_add_u32 s18, s1, s18
	v_mul_lo_u32 v8, v5, s34
	v_ashrrev_i32_e32 v7, 3, v7
	v_lshl_add_u32 v43, v3, 2, v9
	v_lshl_add_u32 v44, v4, 2, v9
	v_subrev_u32_e32 v5, s15, v3
	v_subrev_u32_e32 v4, s15, v4
	v_ashrrev_i32_e32 v3, 31, v2
	s_addc_u32 s19, s4, s19
	v_lshl_add_u32 v45, v7, 2, v9
	v_subrev_u32_e32 v7, s15, v7
	v_add_u32_e32 v36, s5, v5
	v_add_u32_e32 v38, s5, v4
	v_lshlrev_b64 v[2:3], 12, v[2:3]
	v_lshl_add_u64 v[4:5], s[18:19], 0, v[0:1]
	v_add3_u32 v42, 0, v0, v8
	v_subrev_u32_e32 v8, s15, v10
	v_add_u32_e32 v40, s5, v7
	v_lshlrev_b32_e32 v0, 1, v6
	v_lshl_add_u64 v[6:7], v[4:5], 0, v[2:3]
	v_add_u32_e32 v61, s5, v8
	v_add_co_u32_e32 v8, vcc, s38, v6
	v_lshl_add_u32 v46, v10, 2, v9
	s_nop 0
	v_addc_co_u32_e32 v9, vcc, 0, v7, vcc
	v_add_co_u32_e32 v10, vcc, s36, v6
	global_load_dwordx4 v[2:5], v[6:7], off
	s_nop 0
	v_addc_co_u32_e32 v11, vcc, 0, v7, vcc
	v_add_co_u32_e32 v14, vcc, s37, v6
	s_ashr_i32 s17, s16, 31
	s_nop 0
	v_addc_co_u32_e32 v15, vcc, 0, v7, vcc
	v_add_co_u32_e32 v18, vcc, s39, v6
	s_lshl_b64 s[16:17], s[16:17], 1
	s_nop 0
	v_addc_co_u32_e32 v19, vcc, 0, v7, vcc
	v_add_co_u32_e32 v22, vcc, s40, v6
	s_add_u32 s16, s43, s16
	s_nop 0
	v_addc_co_u32_e32 v23, vcc, 0, v7, vcc
	v_add_co_u32_e32 v26, vcc, s41, v6
	s_addc_u32 s17, s52, s17
	s_nop 0
	v_addc_co_u32_e32 v27, vcc, 0, v7, vcc
	v_add_co_u32_e32 v30, vcc, s42, v6
	v_add_u32_e32 v47, 0x2020, v42
	s_nop 0
	v_addc_co_u32_e32 v31, vcc, 0, v7, vcc
	global_load_dwordx4 v[6:9], v[8:9], off
	s_nop 0
	global_load_dwordx4 v[10:13], v[10:11], off
	s_nop 0
	global_load_dwordx4 v[14:17], v[14:15], off
	s_nop 0
	global_load_dwordx4 v[18:21], v[18:19], off
	s_nop 0
	global_load_dwordx4 v[22:25], v[22:23], off
	s_nop 0
	global_load_dwordx4 v[26:29], v[26:27], off
	s_nop 0
	global_load_dwordx4 v[30:33], v[30:31], off
	v_add_u32_e32 v48, 0x2028, v42
	v_add_u32_e32 v49, 0x4040, v42
	v_add_u32_e32 v50, 0x4048, v42
	v_add_u32_e32 v51, 0x6060, v42
	v_add_u32_e32 v52, 0x6068, v42
	v_add_u32_e32 v53, 0x8080, v42
	v_add_u32_e32 v54, 0x8088, v42
	v_add_u32_e32 v55, 0xa0a0, v42
	v_add_u32_e32 v56, 0xa0a8, v42
	v_add_u32_e32 v57, 0xc0c0, v42
	v_add_u32_e32 v58, 0xc0c8, v42
	v_add_u32_e32 v59, 0xe0e0, v42
	v_add_u32_e32 v60, 0xe0e8, v42
	s_waitcnt vmcnt(0)
.LBB0_403:
	s_barrier
	v_lshl_add_u64 v[100:101], s[16:17], 0, v[0:1]
	v_mad_i64_i32 v[102:103], s[16:17], v36, s25, v[100:101]
	v_mad_i64_i32 v[104:105], s[16:17], v38, s25, v[100:101]
	v_mad_i64_i32 v[106:107], s[16:17], v40, s25, v[100:101]
	v_mad_i64_i32 v[108:109], s[16:17], v61, s25, v[100:101]
	s_waitcnt vmcnt(11)
	ds_write2_b32 v42, v2, v3 offset1:1
	ds_write2_b32 v42, v4, v5 offset0:2 offset1:3
	s_waitcnt vmcnt(10)
	ds_write2_b32 v47, v6, v7 offset1:1
	ds_write2_b32 v48, v8, v9 offset1:1
	s_waitcnt vmcnt(9)
	ds_write2_b32 v49, v10, v11 offset1:1
	ds_write2_b32 v50, v12, v13 offset1:1
	s_waitcnt vmcnt(8)
	ds_write2_b32 v51, v14, v15 offset1:1
	ds_write2_b32 v52, v16, v17 offset1:1
	s_waitcnt vmcnt(7)
	ds_write2_b32 v53, v18, v19 offset1:1
	ds_write2_b32 v54, v20, v21 offset1:1
	s_waitcnt vmcnt(6)
	ds_write2_b32 v55, v22, v23 offset1:1
	ds_write2_b32 v56, v24, v25 offset1:1
	s_waitcnt vmcnt(5)
	ds_write2_b32 v57, v26, v27 offset1:1
	ds_write2_b32 v58, v28, v29 offset1:1
	s_waitcnt vmcnt(4)
	ds_write2_b32 v59, v30, v31 offset1:1
	ds_write2_b32 v60, v32, v33 offset1:1
	s_waitcnt lgkmcnt(0)
	s_barrier
	s_add_i32 s0, s0, s20
	s_add_i32 s5, s5, s14
	s_movk_i32 s34, 0x404
	s_cmpk_lt_i32 s0, 0xb0
	s_cbranch_scc0 .Lwp_skip_403
; DI unsigned pack2(float a, float b) { f2_t v = {a, b}; bf2_t r = __builtin_convertvector(v, bf2_t); return __builtin_bit_cast(unsigned, r); }
; DI int get_tid(int wv) { int l; asm volatile("v_mbcnt_lo_u32_b32 %0, -1, 0\n\tv_mbcnt_hi_u32_b32 %0, -1, %0" : "=v"(l)); return wv * 64 + l; }
; DI void transpose_tile(WVP float* sm, const float* __restrict__ src, int lds_, u16* __restrict__ dst, int ldd, int k0, int n0) {
;   const int tid = get_tid(WV);
;   constexpr int P = 257;
;   f32x4 v[8];
;   const int rb = tid >> 6, c4 = (tid & 63) * 4;
; #pragma unroll
;   for (int i = 0; i < 8; ++i) v[i] = *(const f32x4*)(src + (long)(k0 + rb + 8 * i) * lds_ + n0 + c4);
;   __syncthreads();
; #pragma unroll
;   for (int i = 0; i < 8; ++i) for (int j = 0; j < 4; ++j) sm[(rb + 8 * i) * P + c4 + j] = v[i][j];
;   __syncthreads();
; #pragma unroll
;   for (int i = 0; i < 4; ++i) {
;     const int c = tid + NTHR * i, n = c >> 3, k8 = (c & 7) * 8;
;     u32x4 o;
;     o[0] = pack2(sm[(k8 + 0) * P + n], sm[(k8 + 1) * P + n]); o[1] = pack2(sm[(k8 + 2) * P + n], sm[(k8 + 3) * P + n]);
;     o[2] = pack2(sm[(k8 + 4) * P + n], sm[(k8 + 5) * P + n]); o[3] = pack2(sm[(k8 + 6) * P + n], sm[(k8 + 7) * P + n]);
;     *(u32x4*)(dst + (long)(n0 + n) * ldd + k0 + k8) = o;
;   }
	s_ashr_i32 s15, s0, 31
	s_lshr_b32 s15, s15, 30
	s_add_i32 s15, s0, s15
	s_ashr_i32 s15, s15, 2
	s_lshl_b32 s16, s15, 6
	s_lshl_b32 s15, s15, 10
	s_sub_i32 s18, s5, s15
	v_mbcnt_lo_u32_b32 v0, -1, 0
	v_mbcnt_hi_u32_b32 v0, -1, v0
	s_ashr_i32 s19, s18, 31
	v_add_u32_e32 v2, s3, v0
	v_lshlrev_b32_e32 v3, 4, v0
	v_lshlrev_b32_e32 v4, 3, v0
	v_ashrrev_i32_e32 v5, 6, v2
	v_and_b32_e32 v0, 0x3f0, v3
	v_and_b32_e32 v6, 56, v4
	v_ashrrev_i32_e32 v3, 3, v2
	v_add_u32_e32 v4, 0x200, v2
	v_add_u32_e32 v7, 0x400, v2
	v_add_u32_e32 v2, 0x600, v2
	s_lshl_b64 s[18:19], s[18:19], 2
	v_mad_u32_u24 v9, v6, s34, 0
	v_ashrrev_i32_e32 v4, 3, v4
	v_ashrrev_i32_e32 v10, 3, v2
	v_add_u32_e32 v2, s16, v5
	s_add_u32 s18, s1, s18
	v_mul_lo_u32 v8, v5, s34
	v_ashrrev_i32_e32 v7, 3, v7
	v_lshl_add_u32 v43, v3, 2, v9
	v_lshl_add_u32 v44, v4, 2, v9
	v_subrev_u32_e32 v5, s15, v3
	v_subrev_u32_e32 v4, s15, v4
	v_ashrrev_i32_e32 v3, 31, v2
	s_addc_u32 s19, s4, s19
	v_lshl_add_u32 v45, v7, 2, v9
	v_subrev_u32_e32 v7, s15, v7
	v_add_u32_e32 v36, s5, v5
	v_add_u32_e32 v38, s5, v4
	v_lshlrev_b64 v[2:3], 12, v[2:3]
	v_lshl_add_u64 v[4:5], s[18:19], 0, v[0:1]
	v_add3_u32 v42, 0, v0, v8
	v_subrev_u32_e32 v8, s15, v10
	v_add_u32_e32 v40, s5, v7
	v_lshlrev_b32_e32 v0, 1, v6
	v_lshl_add_u64 v[6:7], v[4:5], 0, v[2:3]
	v_add_u32_e32 v61, s5, v8
	v_add_co_u32_e32 v8, vcc, s38, v6
	v_lshl_add_u32 v46, v10, 2, v9
	s_nop 0
	v_addc_co_u32_e32 v9, vcc, 0, v7, vcc
	v_add_co_u32_e32 v10, vcc, s36, v6
	global_load_dwordx4 v[2:5], v[6:7], off
	s_nop 0
	v_addc_co_u32_e32 v11, vcc, 0, v7, vcc
	v_add_co_u32_e32 v14, vcc, s37, v6
	s_ashr_i32 s17, s16, 31
	s_nop 0
	v_addc_co_u32_e32 v15, vcc, 0, v7, vcc
	v_add_co_u32_e32 v18, vcc, s39, v6
	s_lshl_b64 s[16:17], s[16:17], 1
	s_nop 0
	v_addc_co_u32_e32 v19, vcc, 0, v7, vcc
	v_add_co_u32_e32 v22, vcc, s40, v6
	s_add_u32 s16, s43, s16
	s_nop 0
	v_addc_co_u32_e32 v23, vcc, 0, v7, vcc
	v_add_co_u32_e32 v26, vcc, s41, v6
	s_addc_u32 s17, s52, s17
	s_nop 0
	v_addc_co_u32_e32 v27, vcc, 0, v7, vcc
	v_add_co_u32_e32 v30, vcc, s42, v6
	v_add_u32_e32 v47, 0x2020, v42
	s_nop 0
	v_addc_co_u32_e32 v31, vcc, 0, v7, vcc
	global_load_dwordx4 v[6:9], v[8:9], off
	s_nop 0
	global_load_dwordx4 v[10:13], v[10:11], off
	s_nop 0
	global_load_dwordx4 v[14:17], v[14:15], off
	s_nop 0
	global_load_dwordx4 v[18:21], v[18:19], off
	s_nop 0
	global_load_dwordx4 v[22:25], v[22:23], off
	s_nop 0
	global_load_dwordx4 v[26:29], v[26:27], off
	s_nop 0
	global_load_dwordx4 v[30:33], v[30:31], off
	v_add_u32_e32 v48, 0x2028, v42
	v_add_u32_e32 v49, 0x4040, v42
	v_add_u32_e32 v50, 0x4048, v42
	v_add_u32_e32 v51, 0x6060, v42
	v_add_u32_e32 v52, 0x6068, v42
	v_add_u32_e32 v53, 0x8080, v42
	v_add_u32_e32 v54, 0x8088, v42
	v_add_u32_e32 v55, 0xa0a0, v42
	v_add_u32_e32 v56, 0xa0a8, v42
	v_add_u32_e32 v57, 0xc0c0, v42
	v_add_u32_e32 v58, 0xc0c8, v42
	v_add_u32_e32 v59, 0xe0e0, v42
	v_add_u32_e32 v60, 0xe0e8, v42
.Lwp_skip_403:
	ds_read_b32 v64, v43
	ds_read_b32 v66, v43 offset:1028
	ds_read_b32 v67, v43 offset:2056
	ds_read_b32 v68, v43 offset:3084
	ds_read_b32 v69, v43 offset:4112
	ds_read_b32 v70, v43 offset:5140
	ds_read_b32 v71, v43 offset:6168
	ds_read_b32 v72, v43 offset:7196
	ds_read_b32 v73, v44
	ds_read_b32 v74, v44 offset:1028
	ds_read_b32 v75, v44 offset:2056
	ds_read_b32 v76, v44 offset:3084
	ds_read_b32 v77, v44 offset:4112
	ds_read_b32 v78, v44 offset:5140
	ds_read_b32 v79, v44 offset:6168
	ds_read_b32 v80, v44 offset:7196
	ds_read_b32 v81, v45
	ds_read_b32 v82, v45 offset:1028
	ds_read_b32 v83, v45 offset:2056
	ds_read_b32 v84, v45 offset:3084
	ds_read_b32 v85, v45 offset:4112
	ds_read_b32 v86, v45 offset:5140
	ds_read_b32 v87, v45 offset:6168
	ds_read_b32 v88, v45 offset:7196
	ds_read_b32 v89, v46
	ds_read_b32 v90, v46 offset:1028
	ds_read_b32 v91, v46 offset:2056
	ds_read_b32 v92, v46 offset:3084
	ds_read_b32 v93, v46 offset:4112
	ds_read_b32 v94, v46 offset:5140
	ds_read_b32 v95, v46 offset:6168
	ds_read_b32 v96, v46 offset:7196
	s_waitcnt lgkmcnt(14)
	v_cvt_pk_bf16_f32 v66, v64, v66
	v_cvt_pk_bf16_f32 v67, v67, v68
	v_cvt_pk_bf16_f32 v68, v69, v70
	v_cvt_pk_bf16_f32 v69, v71, v72
	v_cvt_pk_bf16_f32 v70, v73, v74
	v_cvt_pk_bf16_f32 v71, v75, v76
	v_cvt_pk_bf16_f32 v72, v77, v78
	v_cvt_pk_bf16_f32 v73, v79, v80
	v_cvt_pk_bf16_f32 v74, v81, v82
	s_waitcnt lgkmcnt(12)
	v_cvt_pk_bf16_f32 v75, v83, v84
	s_waitcnt lgkmcnt(10)
	v_cvt_pk_bf16_f32 v76, v85, v86
	s_waitcnt lgkmcnt(8)
	v_cvt_pk_bf16_f32 v77, v87, v88
	s_waitcnt lgkmcnt(6)
	v_cvt_pk_bf16_f32 v78, v89, v90
	s_waitcnt lgkmcnt(4)
	v_cvt_pk_bf16_f32 v79, v91, v92
	s_waitcnt lgkmcnt(2)
	v_cvt_pk_bf16_f32 v80, v93, v94
	s_waitcnt lgkmcnt(0)
	v_cvt_pk_bf16_f32 v81, v95, v96
	global_store_dwordx4 v[102:103], v[66:69], off
	global_store_dwordx4 v[104:105], v[70:73], off
	global_store_dwordx4 v[106:107], v[74:77], off
	global_store_dwordx4 v[108:109], v[78:81], off
	s_cmpk_lt_i32 s0, 0xb0
	s_cbranch_scc1 .LBB0_403
; DI int get_tid(int wv) { int l; asm volatile("v_mbcnt_lo_u32_b32 %0, -1, 0\n\tv_mbcnt_hi_u32_b32 %0, -1, %0" : "=v"(l)); return wv * 64 + l; }
; DI void transpose_tile(WVP float* sm, const float* __restrict__ src, int lds_, u16* __restrict__ dst, int ldd, int k0, int n0) {
;   const int tid = get_tid(WV);
;   constexpr int P = 257;
;   f32x4 v[8];
;   const int rb = tid >> 6, c4 = (tid & 63) * 4;
; #pragma unroll
;   for (int i = 0; i < 8; ++i) v[i] = *(const f32x4*)(src + (long)(k0 + rb + 8 * i) * lds_ + n0 + c4);
;   __syncthreads();
; #pragma unroll
;   for (int i = 0; i < 8; ++i) for (int j = 0; j < 4; ++j) sm[(rb + 8 * i) * P + c4 + j] = v[i][j];
;     ...
;     int first = (BID - base % GRD + GRD) % GRD;
;     for (int i = first; i < cnt; i += GRD) transpose_tile(WV, sm, src[j], lds_[j], dst[j], Kd[j], (i / nn) * 64, (i % nn) * 256);
.LBB0_404:
	s_mul_hi_u32 s0, s22, 0x3a0
	s_mul_i32 s0, s0, s12
	s_sub_i32 s0, 0x3a0, s0
	s_sub_i32 s1, s0, s12
	s_cmp_ge_u32 s0, s12
	s_cselect_b32 s0, s1, s0
	s_sub_i32 s1, s0, s12
	s_cmp_ge_u32 s0, s12
	s_cselect_b32 s0, s1, s0
	s_sub_i32 s0, s13, s0
	s_ashr_i32 s1, s0, 31
	s_abs_i32 s0, s0
	s_mul_hi_u32 s4, s0, s22
	s_mul_i32 s4, s4, s12
	s_sub_i32 s0, s0, s4
	s_sub_i32 s4, s0, s12
	s_cmp_ge_u32 s0, s12
	s_cselect_b32 s0, s4, s0
	s_sub_i32 s4, s0, s12
	s_cmp_ge_u32 s0, s12
	s_cselect_b32 s0, s4, s0
	s_xor_b32 s0, s0, s1
	s_sub_i32 s0, s0, s1
	s_cmp_gt_i32 s0, 31
	s_cbranch_scc1 .LBB0_407
	s_lshl_b64 s[4:5], s[46:47], 21
	s_add_u32 s1, s8, s4
	s_addc_u32 s8, s9, s5
	s_lshl_b32 s9, s0, 8
	s_lshl_b32 s12, s20, 8
	v_readlane_b32 s2, v255, 43
	v_readlane_b32 s13, v255, 44
	s_ashr_i32 s4, s0, 31
	s_lshr_b32 s4, s4, 30
	s_add_i32 s4, s0, s4
	s_ashr_i32 s5, s4, 2
	s_lshl_b32 s4, s5, 6
	s_lshl_b32 s5, s5, 10
	v_mbcnt_lo_u32_b32 v0, -1, 0
	v_mbcnt_hi_u32_b32 v0, -1, v0
	s_sub_i32 s14, s9, s5
	v_add_u32_e32 v2, s3, v0
	v_lshlrev_b32_e32 v3, 4, v0
	v_lshlrev_b32_e32 v4, 3, v0
	v_ashrrev_i32_e32 v5, 6, v2
	v_and_b32_e32 v0, 0x3f0, v3
	v_and_b32_e32 v42, 56, v4
	v_ashrrev_i32_e32 v3, 3, v2
	v_add_u32_e32 v4, 0x200, v2
	v_add_u32_e32 v6, 0x400, v2
	v_add_u32_e32 v2, 0x600, v2
	s_ashr_i32 s15, s14, 31
	v_mul_lo_u32 v7, v5, s34
	v_mad_u32_u24 v8, v42, s34, 0
	v_ashrrev_i32_e32 v4, 3, v4
	v_ashrrev_i32_e32 v9, 3, v2
	v_add_u32_e32 v2, s4, v5
	v_subrev_u32_e32 v5, s5, v3
	s_lshl_b64 s[14:15], s[14:15], 2
	v_ashrrev_i32_e32 v6, 3, v6
	v_add3_u32 v44, 0, v0, v7
	v_lshl_add_u32 v46, v4, 2, v8
	v_subrev_u32_e32 v7, s5, v4
	v_add_u32_e32 v4, s9, v5
	s_add_u32 s14, s1, s14
	v_lshl_add_u32 v45, v3, 2, v8
	v_lshl_add_u32 v47, v6, 2, v8
	v_lshl_add_u32 v48, v9, 2, v8
	v_subrev_u32_e32 v8, s5, v6
	v_ashrrev_i32_e32 v3, 31, v2
	v_add_u32_e32 v6, s9, v7
	v_ashrrev_i32_e32 v5, 31, v4
	s_addc_u32 s15, s8, s15
	v_subrev_u32_e32 v9, s5, v9
	v_add_u32_e32 v8, s9, v8
	v_lshlrev_b64 v[2:3], 12, v[2:3]
	v_ashrrev_i32_e32 v7, 31, v6
	v_lshlrev_b64 v[34:35], 10, v[4:5]
	v_lshl_add_u64 v[4:5], s[14:15], 0, v[0:1]
	v_add_u32_e32 v10, s9, v9
	v_ashrrev_i32_e32 v9, 31, v8
	v_lshlrev_b64 v[36:37], 10, v[6:7]
	v_lshl_add_u64 v[6:7], v[4:5], 0, v[2:3]
	v_lshlrev_b64 v[38:39], 10, v[8:9]
	v_add_co_u32_e32 v8, vcc, s38, v6
	v_ashrrev_i32_e32 v11, 31, v10
	s_nop 0
	v_addc_co_u32_e32 v9, vcc, 0, v7, vcc
	v_lshlrev_b64 v[40:41], 10, v[10:11]
	v_add_co_u32_e32 v10, vcc, s36, v6
	global_load_dwordx4 v[2:5], v[6:7], off
	s_nop 0
	v_addc_co_u32_e32 v11, vcc, 0, v7, vcc
	v_add_co_u32_e32 v14, vcc, s37, v6
	s_ashr_i32 s5, s4, 31
	s_nop 0
	v_addc_co_u32_e32 v15, vcc, 0, v7, vcc
	v_add_co_u32_e32 v18, vcc, s39, v6
	s_lshl_b64 s[4:5], s[4:5], 1
	s_nop 0
	v_addc_co_u32_e32 v19, vcc, 0, v7, vcc
	v_add_co_u32_e32 v22, vcc, s40, v6
	s_add_u32 s4, s2, s4
	s_nop 0
	v_addc_co_u32_e32 v23, vcc, 0, v7, vcc
	v_add_co_u32_e32 v26, vcc, s41, v6
	v_lshlrev_b32_e32 v0, 1, v42
	s_nop 0
	v_addc_co_u32_e32 v27, vcc, 0, v7, vcc
	v_add_co_u32_e32 v30, vcc, s42, v6
	s_addc_u32 s5, s13, s5
	s_nop 0
	v_addc_co_u32_e32 v31, vcc, 0, v7, vcc
	global_load_dwordx4 v[6:9], v[8:9], off
	s_nop 0
	global_load_dwordx4 v[10:13], v[10:11], off
	s_nop 0
	global_load_dwordx4 v[14:17], v[14:15], off
	s_nop 0
	global_load_dwordx4 v[18:21], v[18:19], off
	s_nop 0
	global_load_dwordx4 v[22:25], v[22:23], off
	s_nop 0
	global_load_dwordx4 v[26:29], v[26:27], off
	s_nop 0
	global_load_dwordx4 v[30:33], v[30:31], off
	v_add_u32_e32 v49, 0x2020, v44
	v_add_u32_e32 v50, 0x2028, v44
	v_add_u32_e32 v51, 0x4040, v44
	v_add_u32_e32 v52, 0x4048, v44
	v_add_u32_e32 v53, 0x6060, v44
	v_add_u32_e32 v54, 0x6068, v44
	v_add_u32_e32 v55, 0x8080, v44
	v_add_u32_e32 v56, 0x8088, v44
	v_add_u32_e32 v57, 0xa0a0, v44
	v_add_u32_e32 v58, 0xa0a8, v44
	v_add_u32_e32 v59, 0xc0c0, v44
	v_add_u32_e32 v60, 0xc0c8, v44
	v_add_u32_e32 v61, 0xe0e0, v44
	v_add_u32_e32 v62, 0xe0e8, v44
	s_waitcnt vmcnt(0)
; DI unsigned pack2(float a, float b) { f2_t v = {a, b}; bf2_t r = __builtin_convertvector(v, bf2_t); return __builtin_bit_cast(unsigned, r); }
; DI int get_tid(int wv) { int l; asm volatile("v_mbcnt_lo_u32_b32 %0, -1, 0\n\tv_mbcnt_hi_u32_b32 %0, -1, %0" : "=v"(l)); return wv * 64 + l; }
; DI void transpose_tile(WVP float* sm, const float* __restrict__ src, int lds_, u16* __restrict__ dst, int ldd, int k0, int n0) {
;   const int tid = get_tid(WV);
;   constexpr int P = 257;
;   f32x4 v[8];
;   const int rb = tid >> 6, c4 = (tid & 63) * 4;
; #pragma unroll
;   for (int i = 0; i < 8; ++i) v[i] = *(const f32x4*)(src + (long)(k0 + rb + 8 * i) * lds_ + n0 + c4);
;   __syncthreads();
; #pragma unroll
;   for (int i = 0; i < 8; ++i) for (int j = 0; j < 4; ++j) sm[(rb + 8 * i) * P + c4 + j] = v[i][j];
;   __syncthreads();
; #pragma unroll
;   for (int i = 0; i < 4; ++i) {
;     const int c = tid + NTHR * i, n = c >> 3, k8 = (c & 7) * 8;
;     u32x4 o;
;     o[0] = pack2(sm[(k8 + 0) * P + n], sm[(k8 + 1) * P + n]); o[1] = pack2(sm[(k8 + 2) * P + n], sm[(k8 + 3) * P + n]);
;     o[2] = pack2(sm[(k8 + 4) * P + n], sm[(k8 + 5) * P + n]); o[3] = pack2(sm[(k8 + 6) * P + n], sm[(k8 + 7) * P + n]);
;     *(u32x4*)(dst + (long)(n0 + n) * ldd + k0 + k8) = o;
;   }
.LBB0_406:
	s_barrier
	v_lshl_add_u64 v[100:101], s[4:5], 0, v[0:1]
	v_lshl_add_u64 v[102:103], v[100:101], 0, v[34:35]
	v_lshl_add_u64 v[104:105], v[100:101], 0, v[36:37]
	v_lshl_add_u64 v[106:107], v[100:101], 0, v[38:39]
	v_lshl_add_u64 v[108:109], v[100:101], 0, v[40:41]
	s_waitcnt vmcnt(11)
	ds_write2_b32 v44, v2, v3 offset1:1
	ds_write2_b32 v44, v4, v5 offset0:2 offset1:3
	s_waitcnt vmcnt(10)
	ds_write2_b32 v49, v6, v7 offset1:1
	ds_write2_b32 v50, v8, v9 offset1:1
	s_waitcnt vmcnt(9)
	ds_write2_b32 v51, v10, v11 offset1:1
	ds_write2_b32 v52, v12, v13 offset1:1
	s_waitcnt vmcnt(8)
	ds_write2_b32 v53, v14, v15 offset1:1
	ds_write2_b32 v54, v16, v17 offset1:1
	s_waitcnt vmcnt(7)
	ds_write2_b32 v55, v18, v19 offset1:1
	ds_write2_b32 v56, v20, v21 offset1:1
	s_waitcnt vmcnt(6)
	ds_write2_b32 v57, v22, v23 offset1:1
	ds_write2_b32 v58, v24, v25 offset1:1
	s_waitcnt vmcnt(5)
	ds_write2_b32 v59, v26, v27 offset1:1
	ds_write2_b32 v60, v28, v29 offset1:1
	s_waitcnt vmcnt(4)
	ds_write2_b32 v61, v30, v31 offset1:1
	ds_write2_b32 v62, v32, v33 offset1:1
	s_waitcnt lgkmcnt(0)
	s_barrier
	s_add_i32 s0, s0, s20
	s_add_i32 s9, s9, s12
	s_movk_i32 s34, 0x404
	s_cmp_lt_i32 s0, 32
	s_cbranch_scc0 .Lwp_skip_406
	s_ashr_i32 s4, s0, 31
	s_lshr_b32 s4, s4, 30
	s_add_i32 s4, s0, s4
	s_ashr_i32 s5, s4, 2
	s_lshl_b32 s4, s5, 6
	s_lshl_b32 s5, s5, 10
	v_mbcnt_lo_u32_b32 v0, -1, 0
	v_mbcnt_hi_u32_b32 v0, -1, v0
	s_sub_i32 s14, s9, s5
	v_add_u32_e32 v2, s3, v0
	v_lshlrev_b32_e32 v3, 4, v0
	v_lshlrev_b32_e32 v4, 3, v0
	v_ashrrev_i32_e32 v5, 6, v2
	v_and_b32_e32 v0, 0x3f0, v3
	v_and_b32_e32 v42, 56, v4
	v_ashrrev_i32_e32 v3, 3, v2
	v_add_u32_e32 v4, 0x200, v2
	v_add_u32_e32 v6, 0x400, v2
	v_add_u32_e32 v2, 0x600, v2
	s_ashr_i32 s15, s14, 31
	v_mul_lo_u32 v7, v5, s34
	v_mad_u32_u24 v8, v42, s34, 0
	v_ashrrev_i32_e32 v4, 3, v4
	v_ashrrev_i32_e32 v9, 3, v2
	v_add_u32_e32 v2, s4, v5
	v_subrev_u32_e32 v5, s5, v3
	s_lshl_b64 s[14:15], s[14:15], 2
	v_ashrrev_i32_e32 v6, 3, v6
	v_add3_u32 v44, 0, v0, v7
	v_lshl_add_u32 v46, v4, 2, v8
	v_subrev_u32_e32 v7, s5, v4
	v_add_u32_e32 v4, s9, v5
	s_add_u32 s14, s1, s14
	v_lshl_add_u32 v45, v3, 2, v8
	v_lshl_add_u32 v47, v6, 2, v8
	v_lshl_add_u32 v48, v9, 2, v8
	v_subrev_u32_e32 v8, s5, v6
	v_ashrrev_i32_e32 v3, 31, v2
	v_add_u32_e32 v6, s9, v7
	v_ashrrev_i32_e32 v5, 31, v4
	s_addc_u32 s15, s8, s15
	v_subrev_u32_e32 v9, s5, v9
	v_add_u32_e32 v8, s9, v8
	v_lshlrev_b64 v[2:3], 12, v[2:3]
	v_ashrrev_i32_e32 v7, 31, v6
	v_lshlrev_b64 v[34:35], 10, v[4:5]
	v_lshl_add_u64 v[4:5], s[14:15], 0, v[0:1]
	v_add_u32_e32 v10, s9, v9
	v_ashrrev_i32_e32 v9, 31, v8
	v_lshlrev_b64 v[36:37], 10, v[6:7]
	v_lshl_add_u64 v[6:7], v[4:5], 0, v[2:3]
	v_lshlrev_b64 v[38:39], 10, v[8:9]
	v_add_co_u32_e32 v8, vcc, s38, v6
	v_ashrrev_i32_e32 v11, 31, v10
	s_nop 0
	v_addc_co_u32_e32 v9, vcc, 0, v7, vcc
	v_lshlrev_b64 v[40:41], 10, v[10:11]
	v_add_co_u32_e32 v10, vcc, s36, v6
	global_load_dwordx4 v[2:5], v[6:7], off
	s_nop 0
	v_addc_co_u32_e32 v11, vcc, 0, v7, vcc
	v_add_co_u32_e32 v14, vcc, s37, v6
	s_ashr_i32 s5, s4, 31
	s_nop 0
	v_addc_co_u32_e32 v15, vcc, 0, v7, vcc
	v_add_co_u32_e32 v18, vcc, s39, v6
	s_lshl_b64 s[4:5], s[4:5], 1
	s_nop 0
	v_addc_co_u32_e32 v19, vcc, 0, v7, vcc
	v_add_co_u32_e32 v22, vcc, s40, v6
	s_add_u32 s4, s2, s4
	s_nop 0
	v_addc_co_u32_e32 v23, vcc, 0, v7, vcc
	v_add_co_u32_e32 v26, vcc, s41, v6
	v_lshlrev_b32_e32 v0, 1, v42
	s_nop 0
	v_addc_co_u32_e32 v27, vcc, 0, v7, vcc
	v_add_co_u32_e32 v30, vcc, s42, v6
	s_addc_u32 s5, s13, s5
	s_nop 0
	v_addc_co_u32_e32 v31, vcc, 0, v7, vcc
	global_load_dwordx4 v[6:9], v[8:9], off
	s_nop 0
	global_load_dwordx4 v[10:13], v[10:11], off
	s_nop 0
	global_load_dwordx4 v[14:17], v[14:15], off
	s_nop 0
	global_load_dwordx4 v[18:21], v[18:19], off
	s_nop 0
	global_load_dwordx4 v[22:25], v[22:23], off
	s_nop 0
	global_load_dwordx4 v[26:29], v[26:27], off
	s_nop 0
	global_load_dwordx4 v[30:33], v[30:31], off
	v_add_u32_e32 v49, 0x2020, v44
	v_add_u32_e32 v50, 0x2028, v44
	v_add_u32_e32 v51, 0x4040, v44
	v_add_u32_e32 v52, 0x4048, v44
	v_add_u32_e32 v53, 0x6060, v44
	v_add_u32_e32 v54, 0x6068, v44
	v_add_u32_e32 v55, 0x8080, v44
	v_add_u32_e32 v56, 0x8088, v44
	v_add_u32_e32 v57, 0xa0a0, v44
	v_add_u32_e32 v58, 0xa0a8, v44
	v_add_u32_e32 v59, 0xc0c0, v44
	v_add_u32_e32 v60, 0xc0c8, v44
	v_add_u32_e32 v61, 0xe0e0, v44
	v_add_u32_e32 v62, 0xe0e8, v44
.Lwp_skip_406:
	ds_read_b32 v64, v45
	ds_read_b32 v66, v45 offset:1028
	ds_read_b32 v67, v45 offset:2056
	ds_read_b32 v68, v45 offset:3084
	ds_read_b32 v69, v45 offset:4112
	ds_read_b32 v70, v45 offset:5140
	ds_read_b32 v71, v45 offset:6168
	ds_read_b32 v72, v45 offset:7196
	ds_read_b32 v73, v46
	ds_read_b32 v74, v46 offset:1028
	ds_read_b32 v75, v46 offset:2056
	ds_read_b32 v76, v46 offset:3084
	ds_read_b32 v77, v46 offset:4112
	ds_read_b32 v78, v46 offset:5140
	ds_read_b32 v79, v46 offset:6168
	ds_read_b32 v80, v46 offset:7196
	ds_read_b32 v81, v47
	ds_read_b32 v82, v47 offset:1028
	ds_read_b32 v83, v47 offset:2056
	ds_read_b32 v84, v47 offset:3084
	ds_read_b32 v85, v47 offset:4112
	ds_read_b32 v86, v47 offset:5140
	ds_read_b32 v87, v47 offset:6168
	ds_read_b32 v88, v47 offset:7196
	ds_read_b32 v89, v48
	ds_read_b32 v90, v48 offset:1028
	ds_read_b32 v91, v48 offset:2056
	ds_read_b32 v92, v48 offset:3084
	ds_read_b32 v93, v48 offset:4112
	ds_read_b32 v94, v48 offset:5140
	ds_read_b32 v95, v48 offset:6168
	ds_read_b32 v96, v48 offset:7196
	s_waitcnt lgkmcnt(14)
	v_cvt_pk_bf16_f32 v66, v64, v66
	v_cvt_pk_bf16_f32 v67, v67, v68
	v_cvt_pk_bf16_f32 v68, v69, v70
	v_cvt_pk_bf16_f32 v69, v71, v72
	v_cvt_pk_bf16_f32 v70, v73, v74
	v_cvt_pk_bf16_f32 v71, v75, v76
	v_cvt_pk_bf16_f32 v72, v77, v78
	v_cvt_pk_bf16_f32 v73, v79, v80
	v_cvt_pk_bf16_f32 v74, v81, v82
	s_waitcnt lgkmcnt(12)
	v_cvt_pk_bf16_f32 v75, v83, v84
	s_waitcnt lgkmcnt(10)
	v_cvt_pk_bf16_f32 v76, v85, v86
	s_waitcnt lgkmcnt(8)
	v_cvt_pk_bf16_f32 v77, v87, v88
	s_waitcnt lgkmcnt(6)
	v_cvt_pk_bf16_f32 v78, v89, v90
	s_waitcnt lgkmcnt(4)
	v_cvt_pk_bf16_f32 v79, v91, v92
	s_waitcnt lgkmcnt(2)
	v_cvt_pk_bf16_f32 v80, v93, v94
	s_waitcnt lgkmcnt(0)
	v_cvt_pk_bf16_f32 v81, v95, v96
	global_store_dwordx4 v[102:103], v[66:69], off
	global_store_dwordx4 v[104:105], v[70:73], off
	global_store_dwordx4 v[106:107], v[74:77], off
	global_store_dwordx4 v[108:109], v[78:81], off
	s_cmp_lt_i32 s0, 32
	s_cbranch_scc1 .LBB0_406
